# speedup vs baseline: 1.0306x; 1.0083x over previous
; template <class Epi>
; __device__ __forceinline__ void small_gemm(const u16* __restrict__ A, const u16* __restrict__ Bt, int K, int N, const Epi& epi) {
;     ...
;   for (int piece = blockIdx.x; piece < npieces; piece += gridDim.x) {
;     int row0 = (piece & 3) * 32, col0 = (piece >> 2) * 64;
;     f32x4 acc[2][4] = {};
;     int kper = K >> 3, k0 = wid * kper;
;     for (int kk = k0; kk < k0 + kper; kk += 32) {
;       bf16x8 a[2], b[4];
; #pragma unroll
;       for (int m = 0; m < 2; ++m) a[m] = *(const bf16x8*)(A + (size_t)(row0 + m * 16 + fr) * K + kk + fq * 8);
; #pragma unroll
;       for (int n = 0; n < 4; ++n) b[n] = *(const bf16x8*)(Bt + (size_t)(col0 + n * 16 + fr) * K + kk + fq * 8);
; #pragma unroll
;       for (int m = 0; m < 2; ++m)
; #pragma unroll
;         for (int n = 0; n < 4; ++n) acc[m][n] = __builtin_amdgcn_mfma_f32_16x16x32_bf16(a[m], b[n], acc[m][n], 0, 0, 0);
;     }
;     __syncthreads();
; #pragma unroll
;     for (int m = 0; m < 2; ++m)
; #pragma unroll
;       for (int n = 0; n < 4; ++n) red[(wid * 8 + m * 4 + n) * 64 + lane] = acc[m][n];
;     __syncthreads();
;     if (wid == 0) {
; #pragma unroll
;       for (int m = 0; m < 2; ++m)
; #pragma unroll
;         for (int n = 0; n < 4; ++n) {
;           f32x4 s = red[(m * 4 + n) * 64 + lane];
; #pragma unroll
;           for (int w = 1; w < 8; ++w) s += red[(w * 8 + m * 4 + n) * 64 + lane];
;           acc[m][n] = s;
;         }
.LBB0_191:
	v_lshl_add_u64 v[58:59], v[48:49], 0, v[32:33]
	v_add_co_u32_e64 v76, s[4:5], s17, v58
	v_lshl_add_u64 v[70:71], v[44:45], 0, v[32:33]
	s_nop 0
	v_addc_co_u32_e64 v77, s[4:5], 0, v59, s[4:5]
	v_add_co_u32_e64 v80, s[4:5], s18, v58
	v_lshl_add_u64 v[72:73], v[42:43], 0, v[32:33]
	v_lshl_add_u64 v[74:75], v[40:41], 0, v[32:33]
	v_lshl_add_u64 v[78:79], v[46:47], 0, v[32:33]
	v_addc_co_u32_e64 v81, s[4:5], 0, v59, s[4:5]
	global_load_dwordx4 v[58:61], v[70:71], off
	global_load_dwordx4 v[62:65], v[76:77], off
	global_load_dwordx4 v[66:69], v[80:81], off
	v_add_u32_e32 v34, 32, v34
	global_load_dwordx4 v[70:73], v[72:73], off
	v_cmp_ge_i32_e64 s[4:5], v34, v52
	global_load_dwordx4 v[74:77], v[74:75], off
	v_lshl_add_u64 v[46:47], v[46:47], 0, 64
	global_load_dwordx4 v[78:81], v[78:79], off
	v_lshl_add_u64 v[40:41], v[40:41], 0, 64
	v_lshl_add_u64 v[42:43], v[42:43], 0, 64
	v_lshl_add_u64 v[44:45], v[44:45], 0, 64
	s_or_b64 s[0:1], s[4:5], s[0:1]
	v_lshl_add_u64 v[48:49], v[48:49], 0, 64
	s_waitcnt vmcnt(4)
	v_mfma_f32_16x16x32_bf16 v[28:31], v[62:65], v[58:61], v[28:31]
	s_waitcnt vmcnt(2)
	v_mfma_f32_16x16x32_bf16 v[24:27], v[62:65], v[70:73], v[24:27]
	s_waitcnt vmcnt(1)
	v_mfma_f32_16x16x32_bf16 v[20:23], v[62:65], v[74:77], v[20:23]
	s_waitcnt vmcnt(0)
	v_mfma_f32_16x16x32_bf16 v[16:19], v[62:65], v[78:81], v[16:19]
	v_mfma_f32_16x16x32_bf16 v[12:15], v[66:69], v[58:61], v[12:15]
	v_mfma_f32_16x16x32_bf16 v[8:11], v[66:69], v[70:73], v[8:11]
	v_mfma_f32_16x16x32_bf16 v[4:7], v[66:69], v[74:77], v[4:7]
	v_mfma_f32_16x16x32_bf16 v[0:3], v[66:69], v[78:81], v[0:3]
	s_andn2_b64 exec, exec, s[0:1]
	s_cbranch_execnz .LBB0_191
	s_or_b64 exec, exec, s[0:1]
	s_barrier
	ds_write_b128 v57, v[28:31]
	ds_write_b128 v57, v[24:27] offset:1024
	ds_write_b128 v57, v[20:23] offset:2048
	ds_write_b128 v57, v[16:19] offset:3072
	ds_write_b128 v57, v[12:15] offset:4096
	ds_write_b128 v57, v[8:11] offset:5120
	ds_write_b128 v57, v[4:7] offset:6144
	ds_write_b128 v57, v[0:3] offset:7168
	s_waitcnt lgkmcnt(0)
	s_barrier
	s_and_saveexec_b64 s[0:1], vcc
	s_cbranch_execz .LBB0_189
	ds_read_b128 v[0:3], v51
	ds_read_b128 v[4:7], v51 offset:8192
	ds_read_b128 v[8:11], v51 offset:16384
	ds_read_b128 v[12:15], v51 offset:1024
	ds_read_b128 v[16:19], v51 offset:9216
	s_andn2_b32 s2, s2, 63
	s_waitcnt lgkmcnt(3)
	v_pk_add_f32 v[20:21], v[2:3], v[6:7]
	v_pk_add_f32 v[22:23], v[0:1], v[4:5]
	ds_read_b128 v[0:3], v51 offset:24576
	ds_read_b128 v[4:7], v51 offset:17408
	s_waitcnt lgkmcnt(4)
	v_pk_add_f32 v[24:25], v[20:21], v[10:11]
	v_pk_add_f32 v[26:27], v[22:23], v[8:9]
	ds_read_b128 v[8:11], v51 offset:32768
	ds_read_b128 v[20:23], v51 offset:25600
	s_waitcnt lgkmcnt(3)
	v_pk_add_f32 v[28:29], v[24:25], v[2:3]
	v_pk_add_f32 v[30:31], v[26:27], v[0:1]
	ds_read_b128 v[0:3], v51 offset:40960
	ds_read_b128 v[24:27], v51 offset:33792
	s_waitcnt lgkmcnt(3)
	v_pk_add_f32 v[40:41], v[28:29], v[10:11]
	v_pk_add_f32 v[42:43], v[30:31], v[8:9]
	ds_read_b128 v[8:11], v51 offset:49152
	ds_read_b128 v[28:31], v51 offset:41984
	s_waitcnt lgkmcnt(3)
	v_pk_add_f32 v[2:3], v[40:41], v[2:3]
	v_pk_add_f32 v[0:1], v[42:43], v[0:1]
	ds_read_b128 v[40:43], v51 offset:57344
	ds_read_b128 v[44:47], v51 offset:50176
	v_pk_add_f32 v[14:15], v[14:15], v[18:19]
	s_waitcnt lgkmcnt(3)
	v_pk_add_f32 v[2:3], v[2:3], v[10:11]
	v_pk_add_f32 v[48:49], v[0:1], v[8:9]
	ds_read_b128 v[8:11], v51 offset:58368
	v_pk_add_f32 v[12:13], v[12:13], v[16:17]
	v_pk_add_f32 v[6:7], v[14:15], v[6:7]
	v_pk_add_f32 v[4:5], v[12:13], v[4:5]
	v_pk_add_f32 v[6:7], v[6:7], v[22:23]
	v_pk_add_f32 v[4:5], v[4:5], v[20:21]
	v_pk_add_f32 v[6:7], v[6:7], v[26:27]
	v_pk_add_f32 v[4:5], v[4:5], v[24:25]
	s_waitcnt lgkmcnt(3)
	v_pk_add_f32 v[6:7], v[6:7], v[30:31]
	v_pk_add_f32 v[4:5], v[4:5], v[28:29]
	s_waitcnt lgkmcnt(1)
	v_pk_add_f32 v[6:7], v[6:7], v[46:47]
	v_pk_add_f32 v[18:19], v[4:5], v[44:45]
	s_waitcnt lgkmcnt(0)
	v_pk_add_f32 v[4:5], v[6:7], v[10:11]
	ds_read_b128 v[10:13], v51 offset:2048
	ds_read_b128 v[14:17], v51 offset:10240
	v_pk_add_f32 v[6:7], v[18:19], v[8:9]
	ds_read_b128 v[18:21], v51 offset:18432
	ds_read_b128 v[22:25], v51 offset:3072
	ds_read_b128 v[26:29], v51 offset:11264
	v_pk_add_f32 v[0:1], v[2:3], v[42:43]
	v_pk_add_f32 v[2:3], v[48:49], v[40:41]
	s_waitcnt lgkmcnt(3)
	v_pk_add_f32 v[16:17], v[12:13], v[16:17]
	v_pk_add_f32 v[30:31], v[10:11], v[14:15]
	ds_read_b128 v[8:11], v51 offset:26624
	ds_read_b128 v[12:15], v51 offset:19456
	s_waitcnt lgkmcnt(4)
	v_pk_add_f32 v[20:21], v[16:17], v[20:21]
	v_pk_add_f32 v[30:31], v[30:31], v[18:19]
	ds_read_b128 v[16:19], v51 offset:34816
	ds_read_b128 v[40:43], v51 offset:27648
	s_waitcnt lgkmcnt(3)
	v_pk_add_f32 v[20:21], v[20:21], v[10:11]
	v_pk_add_f32 v[30:31], v[30:31], v[8:9]
	ds_read_b128 v[8:11], v51 offset:43008
	ds_read_b128 v[44:47], v51 offset:35840
	s_waitcnt lgkmcnt(3)
	v_pk_add_f32 v[20:21], v[20:21], v[18:19]
	v_pk_add_f32 v[30:31], v[30:31], v[16:17]
	ds_read_b128 v[16:19], v51 offset:51200
	ds_read_b128 v[58:61], v51 offset:44032
	ds_read_b128 v[62:65], v51 offset:59392
	ds_read_b128 v[66:69], v51 offset:52224
	s_waitcnt lgkmcnt(5)
	v_pk_add_f32 v[10:11], v[20:21], v[10:11]
	v_pk_add_f32 v[8:9], v[30:31], v[8:9]
	s_waitcnt lgkmcnt(3)
	v_pk_add_f32 v[10:11], v[10:11], v[18:19]
	v_pk_add_f32 v[20:21], v[8:9], v[16:17]
	s_waitcnt lgkmcnt(1)
	v_pk_add_f32 v[8:9], v[10:11], v[64:65]
	v_pk_add_f32 v[10:11], v[20:21], v[62:63]
	v_pk_add_f32 v[20:21], v[24:25], v[28:29]
	ds_read_b128 v[16:19], v51 offset:60416
	v_pk_add_f32 v[22:23], v[22:23], v[26:27]
	v_pk_add_f32 v[14:15], v[20:21], v[14:15]
	v_pk_add_f32 v[12:13], v[22:23], v[12:13]
	v_pk_add_f32 v[14:15], v[14:15], v[42:43]
	v_pk_add_f32 v[12:13], v[12:13], v[40:41]
	v_pk_add_f32 v[14:15], v[14:15], v[46:47]
	v_pk_add_f32 v[12:13], v[12:13], v[44:45]
	v_pk_add_f32 v[14:15], v[14:15], v[60:61]
	v_pk_add_f32 v[12:13], v[12:13], v[58:59]
	s_waitcnt lgkmcnt(1)
; template <int MF, class Epi>
; __device__ __forceinline__ void staged_epilogue(f32x4 (&acc)[MF][4], int row0, int col0, const Epi& epi) {
;   const int lane = tidx() & 63, wid = tidx() >> 6, fr = lane & 15, fq = lane >> 4;
;   float* reg = (float*)(g_shm + 65536 + wid * 8704);
; #pragma unroll
;   for (int mp = 0; mp < MF / 2; ++mp) {
;     __builtin_amdgcn_sched_barrier(0);
; #pragma unroll
;     for (int mm = 0; mm < 2; ++mm)
; #pragma unroll
;       for (int n = 0; n < 4; ++n)
; #pragma unroll
;         for (int j = 0; j < 4; ++j) reg[(mm * 16 + fq * 4 + j) * 68 + n * 16 + fr] = acc[mp * 2 + mm][n][j];
;     __builtin_amdgcn_fence(__ATOMIC_ACQ_REL, "wavefront");
; template <class Epi>
; __device__ __forceinline__ void small_gemm(const u16* __restrict__ A, const u16* __restrict__ Bt, int K, int N, const Epi& epi) {
;     ...
;       for (int m = 0; m < 2; ++m)
; #pragma unroll
;         for (int n = 0; n < 4; ++n) {
;           f32x4 s = red[(m * 4 + n) * 64 + lane];
; #pragma unroll
;           for (int w = 1; w < 8; ++w) s += red[(w * 8 + m * 4 + n) * 64 + lane];
;           acc[m][n] = s;
;         }
;       staged_epilogue<2>(acc, row0, col0, epi);
	v_pk_add_f32 v[14:15], v[14:15], v[68:69]
	v_pk_add_f32 v[22:23], v[12:13], v[66:67]
	s_waitcnt lgkmcnt(0)
	v_pk_add_f32 v[48:49], v[14:15], v[18:19]
	ds_read_b128 v[12:15], v51 offset:4096
	ds_read_b128 v[18:21], v51 offset:12288
	v_pk_add_f32 v[70:71], v[22:23], v[16:17]
	ds_read_b128 v[22:25], v51 offset:20480
	ds_read_b128 v[26:29], v51 offset:5120
	ds_read_b128 v[40:43], v51 offset:13312
	s_waitcnt lgkmcnt(3)
	v_pk_add_f32 v[20:21], v[14:15], v[20:21]
	v_pk_add_f32 v[30:31], v[12:13], v[18:19]
	ds_read_b128 v[12:15], v51 offset:28672
	ds_read_b128 v[16:19], v51 offset:21504
	s_waitcnt lgkmcnt(4)
	v_pk_add_f32 v[24:25], v[20:21], v[24:25]
	v_pk_add_f32 v[30:31], v[30:31], v[22:23]
	ds_read_b128 v[20:23], v51 offset:36864
	ds_read_b128 v[44:47], v51 offset:29696
	s_waitcnt lgkmcnt(3)
	v_pk_add_f32 v[24:25], v[24:25], v[14:15]
	v_pk_add_f32 v[30:31], v[30:31], v[12:13]
	ds_read_b128 v[12:15], v51 offset:45056
	ds_read_b128 v[58:61], v51 offset:37888
	s_waitcnt lgkmcnt(3)
	v_pk_add_f32 v[24:25], v[24:25], v[22:23]
	v_pk_add_f32 v[30:31], v[30:31], v[20:21]
	ds_read_b128 v[20:23], v51 offset:53248
	ds_read_b128 v[62:65], v51 offset:46080
	s_waitcnt lgkmcnt(3)
	v_pk_add_f32 v[24:25], v[24:25], v[14:15]
	v_pk_add_f32 v[30:31], v[30:31], v[12:13]
	ds_read_b128 v[12:15], v51 offset:61440
	ds_read_b128 v[66:69], v51 offset:54272
	s_waitcnt lgkmcnt(3)
	v_pk_add_f32 v[30:31], v[30:31], v[20:21]
	v_pk_add_f32 v[24:25], v[24:25], v[22:23]
	ds_read_b128 v[20:23], v51 offset:62464
	s_waitcnt lgkmcnt(2)
	v_pk_add_f32 v[74:75], v[30:31], v[12:13]
	v_pk_add_f32 v[12:13], v[28:29], v[42:43]
	v_pk_add_f32 v[72:73], v[24:25], v[14:15]
	v_pk_add_f32 v[14:15], v[26:27], v[40:41]
	v_pk_add_f32 v[12:13], v[12:13], v[18:19]
	v_pk_add_f32 v[14:15], v[14:15], v[16:17]
	v_pk_add_f32 v[12:13], v[12:13], v[46:47]
	v_pk_add_f32 v[14:15], v[14:15], v[44:45]
	v_pk_add_f32 v[12:13], v[12:13], v[60:61]
	v_pk_add_f32 v[14:15], v[14:15], v[58:59]
	v_pk_add_f32 v[12:13], v[12:13], v[64:65]
	v_pk_add_f32 v[14:15], v[14:15], v[62:63]
	s_waitcnt lgkmcnt(1)
	v_pk_add_f32 v[12:13], v[12:13], v[68:69]
	v_pk_add_f32 v[24:25], v[14:15], v[66:67]
	s_waitcnt lgkmcnt(0)
	v_pk_add_f32 v[66:67], v[12:13], v[22:23]
	ds_read_b128 v[12:15], v51 offset:6144
	ds_read_b128 v[16:19], v51 offset:14336
	v_pk_add_f32 v[68:69], v[24:25], v[20:21]
	ds_read_b128 v[20:23], v51 offset:22528
	ds_read_b128 v[24:27], v51 offset:7168
	ds_read_b128 v[28:31], v51 offset:15360
	s_waitcnt lgkmcnt(3)
	v_pk_add_f32 v[40:41], v[14:15], v[18:19]
	v_pk_add_f32 v[42:43], v[12:13], v[16:17]
	ds_read_b128 v[12:15], v51 offset:30720
	ds_read_b128 v[16:19], v51 offset:23552
	s_waitcnt lgkmcnt(4)
	v_pk_add_f32 v[44:45], v[40:41], v[22:23]
	v_pk_add_f32 v[46:47], v[42:43], v[20:21]
	ds_read_b128 v[20:23], v51 offset:38912
	ds_read_b128 v[40:43], v51 offset:31744
	s_waitcnt lgkmcnt(3)
	v_pk_add_f32 v[58:59], v[44:45], v[14:15]
	v_pk_add_f32 v[60:61], v[46:47], v[12:13]
	ds_read_b128 v[12:15], v51 offset:47104
	ds_read_b128 v[44:47], v51 offset:39936
	s_waitcnt lgkmcnt(3)
	v_pk_add_f32 v[62:63], v[58:59], v[22:23]
	v_pk_add_f32 v[64:65], v[60:61], v[20:21]
	ds_read_b128 v[20:23], v51 offset:55296
	ds_read_b128 v[58:61], v51 offset:48128
	s_waitcnt lgkmcnt(3)
	v_pk_add_f32 v[76:77], v[62:63], v[14:15]
	v_pk_add_f32 v[78:79], v[64:65], v[12:13]
	ds_read_b128 v[12:15], v51 offset:63488
	ds_read_b128 v[62:65], v51 offset:56320
	s_waitcnt lgkmcnt(3)
	v_pk_add_f32 v[78:79], v[78:79], v[20:21]
	v_pk_add_f32 v[76:77], v[76:77], v[22:23]
	ds_read_b128 v[20:23], v51 offset:64512
	s_waitcnt lgkmcnt(2)
	v_pk_add_f32 v[78:79], v[78:79], v[12:13]
	v_pk_add_f32 v[12:13], v[26:27], v[30:31]
	v_pk_add_f32 v[76:77], v[76:77], v[14:15]
	v_pk_add_f32 v[12:13], v[12:13], v[18:19]
	v_pk_add_f32 v[14:15], v[24:25], v[28:29]
	v_pk_add_f32 v[12:13], v[12:13], v[42:43]
	v_pk_add_f32 v[14:15], v[14:15], v[16:17]
	v_pk_add_f32 v[12:13], v[12:13], v[46:47]
	v_pk_add_f32 v[14:15], v[14:15], v[40:41]
	v_pk_add_f32 v[12:13], v[12:13], v[60:61]
	v_pk_add_f32 v[14:15], v[14:15], v[44:45]
	s_waitcnt lgkmcnt(1)
	v_pk_add_f32 v[12:13], v[12:13], v[64:65]
	v_pk_add_f32 v[14:15], v[14:15], v[58:59]
	s_waitcnt lgkmcnt(0)
	v_pk_add_f32 v[16:17], v[12:13], v[22:23]
	v_mov_b32_e32 v13, v204
	v_mov_b32_e32 v12, v204
	v_pk_add_f32 v[14:15], v[14:15], v[62:63]
	v_lshrrev_b32_e32 v12, 6, v12
	v_mul_lo_u32 v12, v12, s19
	v_pk_add_f32 v[18:19], v[14:15], v[20:21]
	v_add_u32_e32 v14, 0x10000, v12
	v_lshrrev_b32_e32 v12, 2, v13
	v_and_b32_e32 v21, 15, v13
	v_and_b32_e32 v22, 12, v12
	v_bfe_u32 v12, v13, 4, 2
	v_lshlrev_b32_e32 v13, 2, v13
	v_and_b32_e32 v13, 60, v13
	v_lshl_or_b32 v23, v21, 2, v14
	v_lshl_or_b32 v14, v13, 2, v14
	v_or_b32_e32 v15, s22, v12
	v_or_b32_e32 v13, s2, v13
	v_cmp_eq_u32_e64 s[4:5], 0, v21
	v_mad_u32_u24 v24, v12, s20, v14
	v_lshl_add_u32 v20, v15, 10, v13
	v_mad_u32_u24 v21, v22, s20, v23
	ds_write2_b32 v21, v2, v6 offset1:16
	ds_write2_b32 v21, v3, v7 offset0:68 offset1:84
	ds_write2_b32 v21, v0, v4 offset0:136 offset1:152
	ds_write2_b32 v21, v1, v5 offset0:204 offset1:220
	ds_write2_b32 v21, v10, v70 offset0:32 offset1:48
	ds_write2_b32 v21, v11, v71 offset0:100 offset1:116
	ds_write2_b32 v21, v8, v48 offset0:168 offset1:184
	ds_write2_b32 v21, v9, v49 offset0:236 offset1:252
	v_add_u32_e32 v0, 0x1000, v21
	v_add_u32_e32 v1, 0x1400, v21
	ds_write2_b32 v0, v74, v68 offset0:64 offset1:80
	ds_write2_b32 v0, v75, v69 offset0:132 offset1:148
	ds_write2_b32 v0, v72, v66 offset0:200 offset1:216
	ds_write2_b32 v1, v73, v67 offset0:12 offset1:28
	ds_write2_b32 v0, v78, v18 offset0:96 offset1:112
	ds_write2_b32 v0, v79, v19 offset0:164 offset1:180
; template <class F> __device__ __forceinline__ void rows4(const float* reg, int lane, F f) {
; #pragma unroll
;   for (int it = 0; it < 8; ++it) {
;     if ((it & 3) == 0) __builtin_amdgcn_sched_barrier(0);
;     int rr = it * 4 + (lane >> 4), c4 = (lane & 15) * 4;
;     float4 v = *(const float4*)(reg + rr * 68 + c4);
;     f(it, rr, c4, v);
;   }
;   __device__ __forceinline__ void tile(const float* reg, int row0, int col0, int lane) const {
;     rows4(reg, lane, [&](int it, int rr, int c4, float4 v) {
;       int row = row0 + rr, idx = row * 1024 + col0 + c4;
;       float4 xo = *(const float4*)(xold + idx);
;       v.x = fmaf(coef, v.x, xo.x); v.y = fmaf(coef, v.y, xo.y); v.z = fmaf(coef, v.z, xo.z); v.w = fmaf(coef, v.w, xo.w);
;       *(float4*)(xnew + idx) = v;
;       *(bf16x4*)(xb + idx) = pack4(v.x, v.y, v.z, v.w);
;       float s = row16_sum(v.x * v.x + v.y * v.y + v.z * v.z + v.w * v.w);
;       if ((lane & 15) == 0) atomicAdd(ssqn + row, s);
;     });
	ds_write2_b32 v0, v76, v16 offset0:232 offset1:248
	ds_write2_b32 v1, v77, v17 offset0:44 offset1:60
	v_mov_b32_e32 v180, v20
	v_ashrrev_i32_e32 v181, 31, v180
	v_lshlrev_b64 v[178:179], 2, v[180:181]
	v_lshl_add_u64 v[176:177], s[6:7], 0, v[178:179]
	global_load_dwordx4 v[144:147], v[176:177], off
	v_or3_b32 v184, v12, s22, 4
	v_lshl_add_u32 v178, v184, 10, v13
	v_ashrrev_i32_e32 v179, 31, v178
	v_lshlrev_b64 v[180:181], 2, v[178:179]
	v_lshl_add_u64 v[176:177], s[6:7], 0, v[180:181]
	global_load_dwordx4 v[148:151], v[176:177], off
	v_or3_b32 v184, v12, s22, 8
	v_lshl_add_u32 v178, v184, 10, v13
	v_ashrrev_i32_e32 v179, 31, v178
	v_lshlrev_b64 v[180:181], 2, v[178:179]
	v_lshl_add_u64 v[176:177], s[6:7], 0, v[180:181]
	global_load_dwordx4 v[152:155], v[176:177], off
	v_or3_b32 v184, v12, s22, 12
	v_lshl_add_u32 v178, v184, 10, v13
	v_ashrrev_i32_e32 v179, 31, v178
	v_lshlrev_b64 v[180:181], 2, v[178:179]
	v_lshl_add_u64 v[176:177], s[6:7], 0, v[180:181]
	global_load_dwordx4 v[156:159], v[176:177], off
	v_or3_b32 v184, v12, s22, 16
	v_lshl_add_u32 v178, v184, 10, v13
	v_ashrrev_i32_e32 v179, 31, v178
	v_lshlrev_b64 v[180:181], 2, v[178:179]
	v_lshl_add_u64 v[176:177], s[6:7], 0, v[180:181]
	global_load_dwordx4 v[160:163], v[176:177], off
	v_or3_b32 v184, v12, s22, 20
	v_lshl_add_u32 v178, v184, 10, v13
	v_ashrrev_i32_e32 v179, 31, v178
	v_lshlrev_b64 v[180:181], 2, v[178:179]
	v_lshl_add_u64 v[176:177], s[6:7], 0, v[180:181]
	global_load_dwordx4 v[164:167], v[176:177], off
	v_or3_b32 v184, v12, s22, 24
	v_lshl_add_u32 v178, v184, 10, v13
	v_ashrrev_i32_e32 v179, 31, v178
	v_lshlrev_b64 v[180:181], 2, v[178:179]
	v_lshl_add_u64 v[176:177], s[6:7], 0, v[180:181]
	global_load_dwordx4 v[168:171], v[176:177], off
	v_or3_b32 v184, v12, s22, 28
	v_lshl_add_u32 v178, v184, 10, v13
	v_ashrrev_i32_e32 v179, 31, v178
	v_lshlrev_b64 v[180:181], 2, v[178:179]
	v_lshl_add_u64 v[176:177], s[6:7], 0, v[180:181]
	global_load_dwordx4 v[172:175], v[176:177], off
	v_ashrrev_i32_e32 v21, 31, v20
	v_lshlrev_b64 v[8:9], 2, v[20:21]
	v_lshl_add_u64 v[0:1], s[6:7], 0, v[8:9]
	ds_read_b128 v[4:7], v24
	v_lshl_add_u64 v[8:9], s[8:9], 0, v[8:9]
	v_lshl_add_u64 v[10:11], v[20:21], 1, s[12:13]
	s_waitcnt vmcnt(7) lgkmcnt(0)
	v_mov_b32_e32 v0, v144
	v_mov_b32_e32 v1, v145
	v_mov_b32_e32 v2, v146
	v_mov_b32_e32 v3, v147
	v_pk_fma_f32 v[0:1], v[4:5], 0.5, v[0:1] op_sel_hi:[1,0,1]
	v_pk_fma_f32 v[2:3], v[6:7], 0.5, v[2:3] op_sel_hi:[1,0,1]
	global_store_dwordx4 v[8:9], v[0:3], off
	v_cvt_pk_bf16_f32 v4, v0, v1
	v_cvt_pk_bf16_f32 v5, v2, v3
	v_pk_mul_f32 v[0:1], v[0:1], v[0:1]
	v_pk_mul_f32 v[2:3], v[2:3], v[2:3]
	v_add_f32_e32 v0, v0, v1
	v_add_f32_e32 v0, v2, v0
	v_add_f32_e32 v0, v3, v0
	v_mov_b32_e32 v1, 0
	global_store_dwordx2 v[10:11], v[4:5], off
	v_add_f32_dpp v0, v0, v0 quad_perm:[1,0,3,2] row_mask:0xf bank_mask:0xf bound_ctrl:1
	s_nop 1
	v_add_f32_dpp v0, v0, v0 quad_perm:[2,3,0,1] row_mask:0xf bank_mask:0xf bound_ctrl:1
	s_nop 1
	v_add_f32_dpp v0, v0, v0 row_half_mirror row_mask:0xf bank_mask:0xf bound_ctrl:1
	s_nop 1
	v_mov_b32_dpp v1, v0 row_mirror row_mask:0xf bank_mask:0xf
	s_and_saveexec_b64 s[2:3], s[4:5]
	s_cbranch_execz .LBB0_195
	v_add_f32_e32 v0, v0, v1
	v_lshlrev_b32_e32 v1, 2, v15
	global_atomic_add_f32 v1, v0, s[14:15]
.LBB0_195:
	s_or_b64 exec, exec, s[2:3]
	v_or3_b32 v1, v12, s22, 4
	v_lshl_add_u32 v10, v1, 10, v13
	v_ashrrev_i32_e32 v11, 31, v10
	v_lshlrev_b64 v[16:17], 2, v[10:11]
	v_lshl_add_u64 v[2:3], s[6:7], 0, v[16:17]
	v_mul_u32_u24_e32 v0, 0x110, v12
	v_add_u32_e32 v0, v14, v0
	ds_read_b128 v[6:9], v0 offset:1088
	v_lshl_add_u64 v[14:15], s[8:9], 0, v[16:17]
	v_lshl_add_u64 v[10:11], v[10:11], 1, s[12:13]
	s_waitcnt vmcnt(9) lgkmcnt(0)
	v_mov_b32_e32 v2, v148
	v_mov_b32_e32 v3, v149
	v_mov_b32_e32 v4, v150
	v_mov_b32_e32 v5, v151
	v_pk_fma_f32 v[2:3], v[6:7], 0.5, v[2:3] op_sel_hi:[1,0,1]
	v_pk_fma_f32 v[4:5], v[8:9], 0.5, v[4:5] op_sel_hi:[1,0,1]
	global_store_dwordx4 v[14:15], v[2:5], off
	v_cvt_pk_bf16_f32 v6, v2, v3
	v_cvt_pk_bf16_f32 v7, v4, v5
	v_pk_mul_f32 v[2:3], v[2:3], v[2:3]
	v_pk_mul_f32 v[4:5], v[4:5], v[4:5]
	v_add_f32_e32 v2, v2, v3
	v_add_f32_e32 v2, v4, v2
	v_add_f32_e32 v2, v5, v2
	v_mov_b32_e32 v3, 0
	global_store_dwordx2 v[10:11], v[6:7], off
	v_add_f32_dpp v2, v2, v2 quad_perm:[1,0,3,2] row_mask:0xf bank_mask:0xf bound_ctrl:1
	s_nop 1
	v_add_f32_dpp v2, v2, v2 quad_perm:[2,3,0,1] row_mask:0xf bank_mask:0xf bound_ctrl:1
	s_nop 1
	v_add_f32_dpp v2, v2, v2 row_half_mirror row_mask:0xf bank_mask:0xf bound_ctrl:1
	s_nop 1
	v_mov_b32_dpp v3, v2 row_mirror row_mask:0xf bank_mask:0xf
	s_and_saveexec_b64 s[2:3], s[4:5]
	s_cbranch_execz .LBB0_197
	v_add_f32_e32 v2, v2, v3
	v_lshlrev_b32_e32 v1, 2, v1
	global_atomic_add_f32 v1, v2, s[14:15]
.LBB0_197:
	s_or_b64 exec, exec, s[2:3]
	v_or3_b32 v1, v12, s22, 8
	v_lshl_add_u32 v10, v1, 10, v13
	v_ashrrev_i32_e32 v11, 31, v10
	v_lshlrev_b64 v[14:15], 2, v[10:11]
	v_lshl_add_u64 v[2:3], s[6:7], 0, v[14:15]
	ds_read_b128 v[6:9], v0 offset:2176
	v_lshl_add_u64 v[14:15], s[8:9], 0, v[14:15]
	v_lshl_add_u64 v[10:11], v[10:11], 1, s[12:13]
	s_waitcnt vmcnt(11) lgkmcnt(0)
	v_mov_b32_e32 v2, v152
	v_mov_b32_e32 v3, v153
	v_mov_b32_e32 v4, v154
	v_mov_b32_e32 v5, v155
	v_pk_fma_f32 v[2:3], v[6:7], 0.5, v[2:3] op_sel_hi:[1,0,1]
	v_pk_fma_f32 v[4:5], v[8:9], 0.5, v[4:5] op_sel_hi:[1,0,1]
	global_store_dwordx4 v[14:15], v[2:5], off
	v_cvt_pk_bf16_f32 v6, v2, v3
	v_cvt_pk_bf16_f32 v7, v4, v5
	v_pk_mul_f32 v[2:3], v[2:3], v[2:3]
	v_pk_mul_f32 v[4:5], v[4:5], v[4:5]
	v_add_f32_e32 v2, v2, v3
	v_add_f32_e32 v2, v4, v2
	v_add_f32_e32 v2, v5, v2
	v_mov_b32_e32 v3, 0
	global_store_dwordx2 v[10:11], v[6:7], off
	v_add_f32_dpp v2, v2, v2 quad_perm:[1,0,3,2] row_mask:0xf bank_mask:0xf bound_ctrl:1
	s_nop 1
	v_add_f32_dpp v2, v2, v2 quad_perm:[2,3,0,1] row_mask:0xf bank_mask:0xf bound_ctrl:1
	s_nop 1
	v_add_f32_dpp v2, v2, v2 row_half_mirror row_mask:0xf bank_mask:0xf bound_ctrl:1
	s_nop 1
	v_mov_b32_dpp v3, v2 row_mirror row_mask:0xf bank_mask:0xf
	s_and_saveexec_b64 s[2:3], s[4:5]
	s_cbranch_execz .LBB0_199
	v_add_f32_e32 v2, v2, v3
	v_lshlrev_b32_e32 v1, 2, v1
	global_atomic_add_f32 v1, v2, s[14:15]
; template <class F> __device__ __forceinline__ void rows4(const float* reg, int lane, F f) {
; #pragma unroll
;   for (int it = 0; it < 8; ++it) {
;     if ((it & 3) == 0) __builtin_amdgcn_sched_barrier(0);
;     int rr = it * 4 + (lane >> 4), c4 = (lane & 15) * 4;
;     float4 v = *(const float4*)(reg + rr * 68 + c4);
;     f(it, rr, c4, v);
;   }
;   __device__ __forceinline__ void tile(const float* reg, int row0, int col0, int lane) const {
;     rows4(reg, lane, [&](int it, int rr, int c4, float4 v) {
;       int row = row0 + rr, idx = row * 1024 + col0 + c4;
;       float4 xo = *(const float4*)(xold + idx);
;       v.x = fmaf(coef, v.x, xo.x); v.y = fmaf(coef, v.y, xo.y); v.z = fmaf(coef, v.z, xo.z); v.w = fmaf(coef, v.w, xo.w);
;       *(float4*)(xnew + idx) = v;
;       *(bf16x4*)(xb + idx) = pack4(v.x, v.y, v.z, v.w);
;       float s = row16_sum(v.x * v.x + v.y * v.y + v.z * v.z + v.w * v.w);
;       if ((lane & 15) == 0) atomicAdd(ssqn + row, s);
;     });
.LBB0_199:
	s_or_b64 exec, exec, s[2:3]
	v_or3_b32 v1, v12, s22, 12
	v_lshl_add_u32 v10, v1, 10, v13
	v_ashrrev_i32_e32 v11, 31, v10
	v_lshlrev_b64 v[14:15], 2, v[10:11]
	v_lshl_add_u64 v[2:3], s[6:7], 0, v[14:15]
	ds_read_b128 v[6:9], v0 offset:3264
	v_lshl_add_u64 v[14:15], s[8:9], 0, v[14:15]
	v_lshl_add_u64 v[10:11], v[10:11], 1, s[12:13]
	s_waitcnt vmcnt(13) lgkmcnt(0)
	v_mov_b32_e32 v2, v156
	v_mov_b32_e32 v3, v157
	v_mov_b32_e32 v4, v158
	v_mov_b32_e32 v5, v159
	v_pk_fma_f32 v[2:3], v[6:7], 0.5, v[2:3] op_sel_hi:[1,0,1]
	v_pk_fma_f32 v[4:5], v[8:9], 0.5, v[4:5] op_sel_hi:[1,0,1]
	global_store_dwordx4 v[14:15], v[2:5], off
	v_cvt_pk_bf16_f32 v6, v2, v3
	v_cvt_pk_bf16_f32 v7, v4, v5
	v_pk_mul_f32 v[2:3], v[2:3], v[2:3]
	v_pk_mul_f32 v[4:5], v[4:5], v[4:5]
	v_add_f32_e32 v2, v2, v3
	v_add_f32_e32 v2, v4, v2
	v_add_f32_e32 v2, v5, v2
	v_mov_b32_e32 v3, 0
	global_store_dwordx2 v[10:11], v[6:7], off
	v_add_f32_dpp v2, v2, v2 quad_perm:[1,0,3,2] row_mask:0xf bank_mask:0xf bound_ctrl:1
	s_nop 1
	v_add_f32_dpp v2, v2, v2 quad_perm:[2,3,0,1] row_mask:0xf bank_mask:0xf bound_ctrl:1
	s_nop 1
	v_add_f32_dpp v2, v2, v2 row_half_mirror row_mask:0xf bank_mask:0xf bound_ctrl:1
	s_nop 1
	v_mov_b32_dpp v3, v2 row_mirror row_mask:0xf bank_mask:0xf
	s_and_saveexec_b64 s[2:3], s[4:5]
	s_cbranch_execz .LBB0_201
	v_add_f32_e32 v2, v2, v3
	v_lshlrev_b32_e32 v1, 2, v1
	global_atomic_add_f32 v1, v2, s[14:15]
.LBB0_201:
	s_or_b64 exec, exec, s[2:3]
	v_or3_b32 v1, v12, s22, 16
	v_lshl_add_u32 v10, v1, 10, v13
	v_ashrrev_i32_e32 v11, 31, v10
	v_lshlrev_b64 v[14:15], 2, v[10:11]
	v_lshl_add_u64 v[2:3], s[6:7], 0, v[14:15]
	ds_read_b128 v[6:9], v0 offset:4352
	v_lshl_add_u64 v[14:15], s[8:9], 0, v[14:15]
	v_lshl_add_u64 v[10:11], v[10:11], 1, s[12:13]
	s_waitcnt vmcnt(15) lgkmcnt(0)
	v_mov_b32_e32 v2, v160
	v_mov_b32_e32 v3, v161
	v_mov_b32_e32 v4, v162
	v_mov_b32_e32 v5, v163
	v_pk_fma_f32 v[2:3], v[6:7], 0.5, v[2:3] op_sel_hi:[1,0,1]
	v_pk_fma_f32 v[4:5], v[8:9], 0.5, v[4:5] op_sel_hi:[1,0,1]
	global_store_dwordx4 v[14:15], v[2:5], off
	v_cvt_pk_bf16_f32 v6, v2, v3
	v_cvt_pk_bf16_f32 v7, v4, v5
	v_pk_mul_f32 v[2:3], v[2:3], v[2:3]
	v_pk_mul_f32 v[4:5], v[4:5], v[4:5]
	v_add_f32_e32 v2, v2, v3
	v_add_f32_e32 v2, v4, v2
	v_add_f32_e32 v2, v5, v2
	v_mov_b32_e32 v3, 0
	global_store_dwordx2 v[10:11], v[6:7], off
	v_add_f32_dpp v2, v2, v2 quad_perm:[1,0,3,2] row_mask:0xf bank_mask:0xf bound_ctrl:1
	s_nop 1
	v_add_f32_dpp v2, v2, v2 quad_perm:[2,3,0,1] row_mask:0xf bank_mask:0xf bound_ctrl:1
	s_nop 1
	v_add_f32_dpp v2, v2, v2 row_half_mirror row_mask:0xf bank_mask:0xf bound_ctrl:1
	s_nop 1
	v_mov_b32_dpp v3, v2 row_mirror row_mask:0xf bank_mask:0xf
	s_and_saveexec_b64 s[2:3], s[4:5]
	s_cbranch_execz .LBB0_203
	v_add_f32_e32 v2, v2, v3
	v_lshlrev_b32_e32 v1, 2, v1
	global_atomic_add_f32 v1, v2, s[14:15]
.LBB0_203:
	s_or_b64 exec, exec, s[2:3]
	v_or3_b32 v1, v12, s22, 20
	v_lshl_add_u32 v10, v1, 10, v13
	v_ashrrev_i32_e32 v11, 31, v10
	v_lshlrev_b64 v[14:15], 2, v[10:11]
	v_lshl_add_u64 v[2:3], s[6:7], 0, v[14:15]
	ds_read_b128 v[6:9], v0 offset:5440
	v_lshl_add_u64 v[14:15], s[8:9], 0, v[14:15]
	v_lshl_add_u64 v[10:11], v[10:11], 1, s[12:13]
	s_waitcnt vmcnt(17) lgkmcnt(0)
	v_mov_b32_e32 v2, v164
	v_mov_b32_e32 v3, v165
	v_mov_b32_e32 v4, v166
	v_mov_b32_e32 v5, v167
	v_pk_fma_f32 v[2:3], v[6:7], 0.5, v[2:3] op_sel_hi:[1,0,1]
	v_pk_fma_f32 v[4:5], v[8:9], 0.5, v[4:5] op_sel_hi:[1,0,1]
	global_store_dwordx4 v[14:15], v[2:5], off
	v_cvt_pk_bf16_f32 v6, v2, v3
	v_cvt_pk_bf16_f32 v7, v4, v5
	v_pk_mul_f32 v[2:3], v[2:3], v[2:3]
	v_pk_mul_f32 v[4:5], v[4:5], v[4:5]
	v_add_f32_e32 v2, v2, v3
	v_add_f32_e32 v2, v4, v2
	v_add_f32_e32 v2, v5, v2
	v_mov_b32_e32 v3, 0
	global_store_dwordx2 v[10:11], v[6:7], off
	v_add_f32_dpp v2, v2, v2 quad_perm:[1,0,3,2] row_mask:0xf bank_mask:0xf bound_ctrl:1
	s_nop 1
	v_add_f32_dpp v2, v2, v2 quad_perm:[2,3,0,1] row_mask:0xf bank_mask:0xf bound_ctrl:1
	s_nop 1
	v_add_f32_dpp v2, v2, v2 row_half_mirror row_mask:0xf bank_mask:0xf bound_ctrl:1
	s_nop 1
	v_mov_b32_dpp v3, v2 row_mirror row_mask:0xf bank_mask:0xf
	s_and_saveexec_b64 s[2:3], s[4:5]
	s_cbranch_execz .LBB0_205
	v_add_f32_e32 v2, v2, v3
	v_lshlrev_b32_e32 v1, 2, v1
	global_atomic_add_f32 v1, v2, s[14:15]
; template <class F> __device__ __forceinline__ void rows4(const float* reg, int lane, F f) {
; #pragma unroll
;   for (int it = 0; it < 8; ++it) {
;     if ((it & 3) == 0) __builtin_amdgcn_sched_barrier(0);
;     int rr = it * 4 + (lane >> 4), c4 = (lane & 15) * 4;
;     float4 v = *(const float4*)(reg + rr * 68 + c4);
;     f(it, rr, c4, v);
;   }
;   __device__ __forceinline__ void tile(const float* reg, int row0, int col0, int lane) const {
;     rows4(reg, lane, [&](int it, int rr, int c4, float4 v) {
;       int row = row0 + rr, idx = row * 1024 + col0 + c4;
;       float4 xo = *(const float4*)(xold + idx);
;       v.x = fmaf(coef, v.x, xo.x); v.y = fmaf(coef, v.y, xo.y); v.z = fmaf(coef, v.z, xo.z); v.w = fmaf(coef, v.w, xo.w);
;       *(float4*)(xnew + idx) = v;
;       *(bf16x4*)(xb + idx) = pack4(v.x, v.y, v.z, v.w);
;       float s = row16_sum(v.x * v.x + v.y * v.y + v.z * v.z + v.w * v.w);
;       if ((lane & 15) == 0) atomicAdd(ssqn + row, s);
;     });
.LBB0_205:
	s_or_b64 exec, exec, s[2:3]
	v_or3_b32 v1, v12, s22, 24
	v_lshl_add_u32 v10, v1, 10, v13
	v_ashrrev_i32_e32 v11, 31, v10
	v_lshlrev_b64 v[14:15], 2, v[10:11]
	v_lshl_add_u64 v[2:3], s[6:7], 0, v[14:15]
	ds_read_b128 v[6:9], v0 offset:6528
	v_lshl_add_u64 v[14:15], s[8:9], 0, v[14:15]
	v_lshl_add_u64 v[10:11], v[10:11], 1, s[12:13]
	s_waitcnt vmcnt(19) lgkmcnt(0)
	v_mov_b32_e32 v2, v168
	v_mov_b32_e32 v3, v169
	v_mov_b32_e32 v4, v170
	v_mov_b32_e32 v5, v171
	v_pk_fma_f32 v[2:3], v[6:7], 0.5, v[2:3] op_sel_hi:[1,0,1]
	v_pk_fma_f32 v[4:5], v[8:9], 0.5, v[4:5] op_sel_hi:[1,0,1]
	global_store_dwordx4 v[14:15], v[2:5], off
	v_cvt_pk_bf16_f32 v6, v2, v3
	v_cvt_pk_bf16_f32 v7, v4, v5
	v_pk_mul_f32 v[2:3], v[2:3], v[2:3]
	v_pk_mul_f32 v[4:5], v[4:5], v[4:5]
	v_add_f32_e32 v2, v2, v3
	v_add_f32_e32 v2, v4, v2
	v_add_f32_e32 v2, v5, v2
	v_mov_b32_e32 v3, 0
	global_store_dwordx2 v[10:11], v[6:7], off
	v_add_f32_dpp v2, v2, v2 quad_perm:[1,0,3,2] row_mask:0xf bank_mask:0xf bound_ctrl:1
	s_nop 1
	v_add_f32_dpp v2, v2, v2 quad_perm:[2,3,0,1] row_mask:0xf bank_mask:0xf bound_ctrl:1
	s_nop 1
	v_add_f32_dpp v2, v2, v2 row_half_mirror row_mask:0xf bank_mask:0xf bound_ctrl:1
	s_nop 1
	v_mov_b32_dpp v3, v2 row_mirror row_mask:0xf bank_mask:0xf
	s_and_saveexec_b64 s[2:3], s[4:5]
	s_cbranch_execz .LBB0_207
	v_add_f32_e32 v2, v2, v3
	v_lshlrev_b32_e32 v1, 2, v1
	global_atomic_add_f32 v1, v2, s[14:15]
.LBB0_207:
	s_or_b64 exec, exec, s[2:3]
	v_or3_b32 v1, v12, s22, 28
	v_lshl_add_u32 v10, v1, 10, v13
	v_ashrrev_i32_e32 v11, 31, v10
	v_lshlrev_b64 v[12:13], 2, v[10:11]
	v_lshl_add_u64 v[2:3], s[6:7], 0, v[12:13]
	ds_read_b128 v[6:9], v0 offset:7616
	v_lshl_add_u64 v[12:13], s[8:9], 0, v[12:13]
	v_lshl_add_u64 v[10:11], v[10:11], 1, s[12:13]
	s_waitcnt vmcnt(21) lgkmcnt(0)
	v_mov_b32_e32 v2, v172
	v_mov_b32_e32 v3, v173
	v_mov_b32_e32 v4, v174
	v_mov_b32_e32 v5, v175
	v_pk_fma_f32 v[2:3], v[6:7], 0.5, v[2:3] op_sel_hi:[1,0,1]
	v_pk_fma_f32 v[4:5], v[8:9], 0.5, v[4:5] op_sel_hi:[1,0,1]
	global_store_dwordx4 v[12:13], v[2:5], off
	v_cvt_pk_bf16_f32 v6, v2, v3
	v_cvt_pk_bf16_f32 v7, v4, v5
	v_pk_mul_f32 v[2:3], v[2:3], v[2:3]
	v_pk_mul_f32 v[4:5], v[4:5], v[4:5]
	v_add_f32_e32 v0, v2, v3
	v_add_f32_e32 v0, v4, v0
	v_add_f32_e32 v0, v5, v0
	v_mov_b32_e32 v2, 0
	global_store_dwordx2 v[10:11], v[6:7], off
	v_add_f32_dpp v0, v0, v0 quad_perm:[1,0,3,2] row_mask:0xf bank_mask:0xf bound_ctrl:1
	s_nop 1
	v_add_f32_dpp v0, v0, v0 quad_perm:[2,3,0,1] row_mask:0xf bank_mask:0xf bound_ctrl:1
	s_nop 1
	v_add_f32_dpp v0, v0, v0 row_half_mirror row_mask:0xf bank_mask:0xf bound_ctrl:1
	s_nop 1
	v_mov_b32_dpp v2, v0 row_mirror row_mask:0xf bank_mask:0xf
	s_and_b64 exec, exec, s[4:5]
	s_cbranch_execz .LBB0_188
	v_add_f32_e32 v0, v0, v2
	v_lshlrev_b32_e32 v1, 2, v1
	global_atomic_add_f32 v1, v0, s[14:15]
	s_branch .LBB0_188

; template <class Epi>
; __device__ __forceinline__ void small_gemm(const u16* __restrict__ A, const u16* __restrict__ Bt, int K, int N, const Epi& epi) {
;     ...
;     f32x4 acc[2][4] = {};
;     int kper = K >> 3, k0 = wid * kper;
;     for (int kk = k0; kk < k0 + kper; kk += 32) {
;       bf16x8 a[2], b[4];
; #pragma unroll
;       for (int m = 0; m < 2; ++m) a[m] = *(const bf16x8*)(A + (size_t)(row0 + m * 16 + fr) * K + kk + fq * 8);
; #pragma unroll
;       for (int n = 0; n < 4; ++n) b[n] = *(const bf16x8*)(Bt + (size_t)(col0 + n * 16 + fr) * K + kk + fq * 8);
; #pragma unroll
;       for (int m = 0; m < 2; ++m)
; #pragma unroll
;         for (int n = 0; n < 4; ++n) acc[m][n] = __builtin_amdgcn_mfma_f32_16x16x32_bf16(a[m], b[n], acc[m][n], 0, 0, 0);
;     }
;     __syncthreads();
; #pragma unroll
;     for (int m = 0; m < 2; ++m)
; #pragma unroll
;       for (int n = 0; n < 4; ++n) red[(wid * 8 + m * 4 + n) * 64 + lane] = acc[m][n];
;     __syncthreads();
.LBB0_1477:
	s_and_b32 s24, s18, 0x60
	v_or_b32_e32 v0, s24, v18
	s_and_b32 s2, s14, 0xffffffc0
	v_or_b32_e32 v22, s2, v18
	v_lshlrev_b32_e32 v0, 11, v0
	v_lshl_add_u64 v[70:71], v[2:3], 0, v[0:1]
	v_ashrrev_i32_e32 v23, 31, v22
	global_load_dwordx4 v[6:9], v[70:71], off
	v_lshlrev_b64 v[10:11], 11, v[22:23]
	v_or_b32_e32 v14, 16, v22
	v_or_b32_e32 v22, 32, v22
	v_ashrrev_i32_e32 v15, 31, v14
	v_ashrrev_i32_e32 v23, 31, v22
	v_or_b32_e32 v26, s14, v20
	v_lshlrev_b64 v[14:15], 11, v[14:15]
	v_lshlrev_b64 v[22:23], 11, v[22:23]
	v_ashrrev_i32_e32 v27, 31, v26
	v_lshl_add_u64 v[72:73], v[4:5], 0, v[10:11]
	v_lshl_add_u64 v[74:75], v[4:5], 0, v[14:15]
	v_lshl_add_u64 v[78:79], v[4:5], 0, v[22:23]
	v_lshlrev_b64 v[26:27], 11, v[26:27]
	global_load_dwordx4 v[10:13], v[72:73], off
	global_load_dwordx4 v[14:17], v[74:75], off
	global_load_dwordx4 v[22:25], v[78:79], off
	v_lshl_add_u64 v[86:87], v[4:5], 0, v[26:27]
	global_load_dwordx4 v[26:29], v[70:71], off offset:64
	global_load_dwordx4 v[30:33], v[72:73], off offset:64
	global_load_dwordx4 v[38:41], v[86:87], off
	global_load_dwordx4 v[42:45], v[74:75], off offset:64
	v_add_co_u32_e64 v88, s[6:7], s20, v70
	global_load_dwordx4 v[50:53], v[78:79], off offset:64
	s_nop 0
	v_addc_co_u32_e64 v89, s[6:7], 0, v71, s[6:7]
	global_load_dwordx4 v[58:61], v[88:89], off
	global_load_dwordx4 v[62:65], v[86:87], off offset:64
	global_load_dwordx4 v[66:69], v[88:89], off offset:64
	s_waitcnt vmcnt(10)
	v_mfma_f32_16x16x32_bf16 v[34:37], v[6:9], v[10:13], 0
	s_waitcnt vmcnt(9)
	v_mfma_f32_16x16x32_bf16 v[46:49], v[6:9], v[14:17], 0
	s_waitcnt vmcnt(8)
	v_mfma_f32_16x16x32_bf16 v[54:57], v[6:9], v[22:25], 0
	s_waitcnt vmcnt(5)
	v_mfma_f32_16x16x32_bf16 v[6:9], v[6:9], v[38:41], 0
	s_waitcnt vmcnt(2)
	v_mfma_f32_16x16x32_bf16 v[10:13], v[58:61], v[10:13], 0
	v_mfma_f32_16x16x32_bf16 v[34:37], v[26:29], v[30:33], v[34:37]
	v_mfma_f32_16x16x32_bf16 v[46:49], v[26:29], v[42:45], v[46:49]
	v_mfma_f32_16x16x32_bf16 v[54:57], v[26:29], v[50:53], v[54:57]
	s_waitcnt vmcnt(1)
	v_mfma_f32_16x16x32_bf16 v[6:9], v[26:29], v[62:65], v[6:9]
	global_load_dwordx4 v[26:29], v[70:71], off offset:128
	v_mfma_f32_16x16x32_bf16 v[14:17], v[58:61], v[14:17], 0
	v_mfma_f32_16x16x32_bf16 v[22:25], v[58:61], v[22:25], 0
	v_mfma_f32_16x16x32_bf16 v[38:41], v[58:61], v[38:41], 0
	s_waitcnt vmcnt(1)
	v_mfma_f32_16x16x32_bf16 v[10:13], v[66:69], v[30:33], v[10:13]
	global_load_dwordx4 v[30:33], v[72:73], off offset:128
	v_mfma_f32_16x16x32_bf16 v[14:17], v[66:69], v[42:45], v[14:17]
	v_mfma_f32_16x16x32_bf16 v[22:25], v[66:69], v[50:53], v[22:25]
	global_load_dwordx4 v[42:45], v[74:75], off offset:128
	global_load_dwordx4 v[50:53], v[70:71], off offset:192
	global_load_dwordx4 v[58:61], v[72:73], off offset:192
	v_mfma_f32_16x16x32_bf16 v[38:41], v[66:69], v[62:65], v[38:41]
	global_load_dwordx4 v[62:65], v[78:79], off offset:128
	global_load_dwordx4 v[66:69], v[74:75], off offset:192
	global_load_dwordx4 v[70:73], v[86:87], off offset:128
	s_nop 0
	global_load_dwordx4 v[74:77], v[78:79], off offset:192
	s_nop 0
	global_load_dwordx4 v[78:81], v[88:89], off offset:128
	global_load_dwordx4 v[82:85], v[86:87], off offset:192
	s_waitcnt vmcnt(1)
	v_mfma_f32_16x16x32_bf16 v[14:17], v[78:81], v[42:45], v[14:17]
	v_mfma_f32_16x16x32_bf16 v[34:37], v[26:29], v[30:33], v[34:37]
	v_mfma_f32_16x16x32_bf16 v[46:49], v[26:29], v[42:45], v[46:49]
	v_mfma_f32_16x16x32_bf16 v[54:57], v[26:29], v[62:65], v[54:57]
	v_mfma_f32_16x16x32_bf16 v[6:9], v[26:29], v[70:73], v[6:9]
	global_load_dwordx4 v[26:29], v[88:89], off offset:192
	s_barrier
	v_mfma_f32_16x16x32_bf16 v[10:13], v[78:81], v[30:33], v[10:13]
	v_mfma_f32_16x16x32_bf16 v[22:25], v[78:81], v[62:65], v[22:25]
	v_mfma_f32_16x16x32_bf16 v[30:33], v[78:81], v[70:73], v[38:41]
	v_mfma_f32_16x16x32_bf16 v[34:37], v[50:53], v[58:61], v[34:37]
	v_mfma_f32_16x16x32_bf16 v[38:41], v[50:53], v[66:69], v[46:49]
	v_mfma_f32_16x16x32_bf16 v[42:45], v[50:53], v[74:77], v[54:57]
	s_nop 5
	ds_write_b128 v21, v[34:37]
	s_waitcnt vmcnt(1)
	v_mfma_f32_16x16x32_bf16 v[6:9], v[50:53], v[82:85], v[6:9]
	ds_write_b128 v21, v[38:41] offset:1024
	ds_write_b128 v21, v[42:45] offset:2048
	s_nop 5
	ds_write_b128 v21, v[6:9] offset:3072
	s_waitcnt vmcnt(0)
	v_mfma_f32_16x16x32_bf16 v[10:13], v[26:29], v[58:61], v[10:13]
	v_mfma_f32_16x16x32_bf16 v[14:17], v[26:29], v[66:69], v[14:17]
	v_mfma_f32_16x16x32_bf16 v[6:9], v[26:29], v[74:77], v[22:25]
	s_nop 5
	ds_write_b128 v21, v[10:13] offset:4096
	ds_write_b128 v21, v[14:17] offset:5120
	ds_write_b128 v21, v[6:9] offset:6144
	v_mfma_f32_16x16x32_bf16 v[6:9], v[26:29], v[82:85], v[30:33]
	s_nop 7
	ds_write_b128 v21, v[6:9] offset:7168
	s_waitcnt lgkmcnt(0)
	s_barrier
	s_and_saveexec_b64 s[0:1], vcc
	s_cbranch_execz .LBB0_1476
; template <class Epi>
; __device__ __forceinline__ void small_gemm(const u16* __restrict__ A, const u16* __restrict__ Bt, int K, int N, const Epi& epi) {
;     ...
;     if (wid == 0) {
; #pragma unroll
;       for (int m = 0; m < 2; ++m)
; #pragma unroll
;         for (int n = 0; n < 4; ++n) {
;           f32x4 s = red[(m * 4 + n) * 64 + lane];
; #pragma unroll
;           for (int w = 1; w < 8; ++w) s += red[(w * 8 + m * 4 + n) * 64 + lane];
;           acc[m][n] = s;
;         }
	ds_read_b128 v[6:9], v19
	ds_read_b128 v[10:13], v19 offset:8192
	ds_read_b128 v[14:17], v19 offset:16384
	ds_read_b128 v[22:25], v19 offset:1024
	ds_read_b128 v[26:29], v19 offset:9216
	v_mov_b32_e32 v0, v204
	s_waitcnt lgkmcnt(3)
	v_pk_add_f32 v[30:31], v[8:9], v[12:13]
	v_pk_add_f32 v[32:33], v[6:7], v[10:11]
	ds_read_b128 v[6:9], v19 offset:24576
	ds_read_b128 v[10:13], v19 offset:17408
	s_waitcnt lgkmcnt(4)
	v_pk_add_f32 v[34:35], v[30:31], v[16:17]
	v_pk_add_f32 v[36:37], v[32:33], v[14:15]
	ds_read_b128 v[14:17], v19 offset:32768
	ds_read_b128 v[30:33], v19 offset:25600
	s_waitcnt lgkmcnt(3)
	v_pk_add_f32 v[38:39], v[34:35], v[8:9]
	v_pk_add_f32 v[40:41], v[36:37], v[6:7]
	ds_read_b128 v[6:9], v19 offset:40960
	ds_read_b128 v[34:37], v19 offset:33792
	s_waitcnt lgkmcnt(3)
	v_pk_add_f32 v[42:43], v[38:39], v[16:17]
	v_pk_add_f32 v[44:45], v[40:41], v[14:15]
	ds_read_b128 v[14:17], v19 offset:49152
	ds_read_b128 v[38:41], v19 offset:41984
	s_waitcnt lgkmcnt(3)
	v_pk_add_f32 v[8:9], v[42:43], v[8:9]
	v_pk_add_f32 v[6:7], v[44:45], v[6:7]
	ds_read_b128 v[42:45], v19 offset:57344
	ds_read_b128 v[46:49], v19 offset:50176
	v_pk_add_f32 v[24:25], v[24:25], v[28:29]
	v_pk_add_f32 v[22:23], v[22:23], v[26:27]
	s_waitcnt lgkmcnt(3)
	v_pk_add_f32 v[8:9], v[8:9], v[16:17]
	v_pk_add_f32 v[50:51], v[6:7], v[14:15]
	ds_read_b128 v[14:17], v19 offset:58368
	v_pk_add_f32 v[12:13], v[24:25], v[12:13]
	v_pk_add_f32 v[10:11], v[22:23], v[10:11]
	ds_read_b128 v[22:25], v19 offset:2048
	ds_read_b128 v[26:29], v19 offset:10240
	v_pk_add_f32 v[12:13], v[12:13], v[32:33]
	v_pk_add_f32 v[10:11], v[10:11], v[30:31]
	v_pk_add_f32 v[12:13], v[12:13], v[36:37]
	v_pk_add_f32 v[10:11], v[10:11], v[34:35]
	s_waitcnt lgkmcnt(5)
	v_pk_add_f32 v[12:13], v[12:13], v[40:41]
	v_pk_add_f32 v[10:11], v[10:11], v[38:39]
	s_waitcnt lgkmcnt(3)
	v_pk_add_f32 v[12:13], v[12:13], v[48:49]
	v_pk_add_f32 v[30:31], v[10:11], v[46:47]
	s_waitcnt lgkmcnt(2)
	v_pk_add_f32 v[10:11], v[12:13], v[16:17]
	v_pk_add_f32 v[12:13], v[30:31], v[14:15]
	ds_read_b128 v[14:17], v19 offset:18432
	ds_read_b128 v[30:33], v19 offset:3072
	ds_read_b128 v[34:37], v19 offset:11264
	s_waitcnt lgkmcnt(3)
	v_pk_add_f32 v[38:39], v[24:25], v[28:29]
	v_pk_add_f32 v[40:41], v[22:23], v[26:27]
	ds_read_b128 v[22:25], v19 offset:26624
	ds_read_b128 v[26:29], v19 offset:19456
	v_pk_add_f32 v[6:7], v[8:9], v[44:45]
	v_pk_add_f32 v[8:9], v[50:51], v[42:43]
	s_waitcnt lgkmcnt(4)
	v_pk_add_f32 v[42:43], v[38:39], v[16:17]
	v_pk_add_f32 v[44:45], v[40:41], v[14:15]
	ds_read_b128 v[14:17], v19 offset:34816
	ds_read_b128 v[38:41], v19 offset:27648
	s_waitcnt lgkmcnt(3)
	v_pk_add_f32 v[46:47], v[42:43], v[24:25]
	v_pk_add_f32 v[48:49], v[44:45], v[22:23]
	ds_read_b128 v[22:25], v19 offset:43008
	ds_read_b128 v[42:45], v19 offset:35840
	s_waitcnt lgkmcnt(3)
	v_pk_add_f32 v[50:51], v[46:47], v[16:17]
	v_pk_add_f32 v[52:53], v[48:49], v[14:15]
	ds_read_b128 v[14:17], v19 offset:51200
	ds_read_b128 v[46:49], v19 offset:44032
	s_waitcnt lgkmcnt(3)
	v_pk_add_f32 v[54:55], v[50:51], v[24:25]
	v_pk_add_f32 v[56:57], v[52:53], v[22:23]
	ds_read_b128 v[22:25], v19 offset:59392
	ds_read_b128 v[50:53], v19 offset:52224
	s_waitcnt lgkmcnt(3)
	v_pk_add_f32 v[16:17], v[54:55], v[16:17]
	v_pk_add_f32 v[58:59], v[56:57], v[14:15]
	ds_read_b128 v[54:57], v19 offset:60416
	s_waitcnt lgkmcnt(2)
	v_pk_add_f32 v[14:15], v[16:17], v[24:25]
	v_pk_add_f32 v[16:17], v[58:59], v[22:23]
	v_pk_add_f32 v[22:23], v[32:33], v[36:37]
	v_pk_add_f32 v[24:25], v[30:31], v[34:35]
	v_pk_add_f32 v[22:23], v[22:23], v[28:29]
	v_pk_add_f32 v[24:25], v[24:25], v[26:27]
	v_pk_add_f32 v[22:23], v[22:23], v[40:41]
	v_pk_add_f32 v[24:25], v[24:25], v[38:39]
	v_pk_add_f32 v[22:23], v[22:23], v[44:45]
	v_pk_add_f32 v[24:25], v[24:25], v[42:43]
	v_pk_add_f32 v[22:23], v[22:23], v[48:49]
	v_pk_add_f32 v[24:25], v[24:25], v[46:47]
	s_waitcnt lgkmcnt(1)
	v_pk_add_f32 v[22:23], v[22:23], v[52:53]
	v_pk_add_f32 v[30:31], v[24:25], v[50:51]
	s_waitcnt lgkmcnt(0)
	v_pk_add_f32 v[58:59], v[22:23], v[56:57]
	ds_read_b128 v[22:25], v19 offset:4096
	ds_read_b128 v[26:29], v19 offset:12288
	v_pk_add_f32 v[60:61], v[30:31], v[54:55]
	ds_read_b128 v[30:33], v19 offset:20480
	ds_read_b128 v[34:37], v19 offset:5120
	ds_read_b128 v[38:41], v19 offset:13312
	s_waitcnt lgkmcnt(3)
	v_pk_add_f32 v[42:43], v[24:25], v[28:29]
	v_pk_add_f32 v[44:45], v[22:23], v[26:27]
	ds_read_b128 v[22:25], v19 offset:28672
	ds_read_b128 v[26:29], v19 offset:21504
	s_waitcnt lgkmcnt(4)
	v_pk_add_f32 v[46:47], v[42:43], v[32:33]
	v_pk_add_f32 v[48:49], v[44:45], v[30:31]
	ds_read_b128 v[30:33], v19 offset:36864
	ds_read_b128 v[42:45], v19 offset:29696
	s_waitcnt lgkmcnt(3)
	v_pk_add_f32 v[50:51], v[46:47], v[24:25]
	v_pk_add_f32 v[52:53], v[48:49], v[22:23]
	ds_read_b128 v[22:25], v19 offset:45056
	ds_read_b128 v[46:49], v19 offset:37888
	s_waitcnt lgkmcnt(3)
	v_pk_add_f32 v[54:55], v[50:51], v[32:33]
	v_pk_add_f32 v[56:57], v[52:53], v[30:31]
	ds_read_b128 v[30:33], v19 offset:53248
	ds_read_b128 v[50:53], v19 offset:46080
	s_waitcnt lgkmcnt(3)
	v_pk_add_f32 v[62:63], v[54:55], v[24:25]
	v_pk_add_f32 v[64:65], v[56:57], v[22:23]
	ds_read_b128 v[22:25], v19 offset:61440
	ds_read_b128 v[54:57], v19 offset:54272
	s_waitcnt lgkmcnt(3)
	v_pk_add_f32 v[64:65], v[64:65], v[30:31]
	v_pk_add_f32 v[62:63], v[62:63], v[32:33]
	ds_read_b128 v[30:33], v19 offset:62464
	s_waitcnt lgkmcnt(2)
; template <int MF, class Epi>
; __device__ __forceinline__ void staged_epilogue(f32x4 (&acc)[MF][4], int row0, int col0, const Epi& epi) {
;   const int lane = tidx() & 63, wid = tidx() >> 6, fr = lane & 15, fq = lane >> 4;
;   float* reg = (float*)(g_shm + 65536 + wid * 8704);
; #pragma unroll
;   for (int mp = 0; mp < MF / 2; ++mp) {
;     __builtin_amdgcn_sched_barrier(0);
; #pragma unroll
;     for (int mm = 0; mm < 2; ++mm)
; #pragma unroll
;       for (int n = 0; n < 4; ++n)
; #pragma unroll
;         for (int j = 0; j < 4; ++j) reg[(mm * 16 + fq * 4 + j) * 68 + n * 16 + fr] = acc[mp * 2 + mm][n][j];
;     __builtin_amdgcn_fence(__ATOMIC_ACQ_REL, "wavefront");
;     epi.tile(reg, row0 + mp * 32, col0, lane);
; template <class Epi>
; __device__ __forceinline__ void small_gemm(const u16* __restrict__ A, const u16* __restrict__ Bt, int K, int N, const Epi& epi) {
;     ...
;     if (wid == 0) {
; #pragma unroll
;       for (int m = 0; m < 2; ++m)
; #pragma unroll
;         for (int n = 0; n < 4; ++n) {
;           f32x4 s = red[(m * 4 + n) * 64 + lane];
; #pragma unroll
;           for (int w = 1; w < 8; ++w) s += red[(w * 8 + m * 4 + n) * 64 + lane];
;           acc[m][n] = s;
;         }
;       staged_epilogue<2>(acc, row0, col0, epi);
	v_pk_add_f32 v[64:65], v[64:65], v[22:23]
	v_pk_add_f32 v[22:23], v[36:37], v[40:41]
	v_pk_add_f32 v[62:63], v[62:63], v[24:25]
	v_pk_add_f32 v[24:25], v[34:35], v[38:39]
	v_pk_add_f32 v[22:23], v[22:23], v[28:29]
	v_pk_add_f32 v[24:25], v[24:25], v[26:27]
	v_pk_add_f32 v[22:23], v[22:23], v[44:45]
	v_pk_add_f32 v[24:25], v[24:25], v[42:43]
	v_pk_add_f32 v[22:23], v[22:23], v[48:49]
	v_pk_add_f32 v[24:25], v[24:25], v[46:47]
	v_pk_add_f32 v[22:23], v[22:23], v[52:53]
	v_pk_add_f32 v[24:25], v[24:25], v[50:51]
	s_waitcnt lgkmcnt(1)
	v_pk_add_f32 v[22:23], v[22:23], v[56:57]
	v_pk_add_f32 v[34:35], v[24:25], v[54:55]
	s_waitcnt lgkmcnt(0)
	v_pk_add_f32 v[66:67], v[22:23], v[32:33]
	ds_read_b128 v[22:25], v19 offset:6144
	ds_read_b128 v[26:29], v19 offset:14336
	v_pk_add_f32 v[68:69], v[34:35], v[30:31]
	ds_read_b128 v[30:33], v19 offset:22528
	ds_read_b128 v[34:37], v19 offset:7168
	ds_read_b128 v[38:41], v19 offset:15360
	s_waitcnt lgkmcnt(3)
	v_pk_add_f32 v[42:43], v[24:25], v[28:29]
	v_pk_add_f32 v[44:45], v[22:23], v[26:27]
	ds_read_b128 v[22:25], v19 offset:30720
	ds_read_b128 v[26:29], v19 offset:23552
	s_waitcnt lgkmcnt(4)
	v_pk_add_f32 v[46:47], v[42:43], v[32:33]
	v_pk_add_f32 v[48:49], v[44:45], v[30:31]
	ds_read_b128 v[30:33], v19 offset:38912
	ds_read_b128 v[42:45], v19 offset:31744
	s_waitcnt lgkmcnt(3)
	v_pk_add_f32 v[50:51], v[46:47], v[24:25]
	v_pk_add_f32 v[52:53], v[48:49], v[22:23]
	ds_read_b128 v[22:25], v19 offset:47104
	ds_read_b128 v[46:49], v19 offset:39936
	s_waitcnt lgkmcnt(3)
	v_pk_add_f32 v[54:55], v[50:51], v[32:33]
	v_pk_add_f32 v[56:57], v[52:53], v[30:31]
	ds_read_b128 v[30:33], v19 offset:55296
	ds_read_b128 v[50:53], v19 offset:48128
	s_waitcnt lgkmcnt(3)
	v_pk_add_f32 v[70:71], v[54:55], v[24:25]
	v_pk_add_f32 v[72:73], v[56:57], v[22:23]
	ds_read_b128 v[22:25], v19 offset:63488
	ds_read_b128 v[54:57], v19 offset:56320
	s_waitcnt lgkmcnt(3)
	v_pk_add_f32 v[72:73], v[72:73], v[30:31]
	v_pk_add_f32 v[70:71], v[70:71], v[32:33]
	ds_read_b128 v[30:33], v19 offset:64512
	s_waitcnt lgkmcnt(2)
	v_pk_add_f32 v[72:73], v[72:73], v[22:23]
	v_pk_add_f32 v[22:23], v[36:37], v[40:41]
	v_pk_add_f32 v[70:71], v[70:71], v[24:25]
	v_pk_add_f32 v[22:23], v[22:23], v[28:29]
	v_pk_add_f32 v[24:25], v[34:35], v[38:39]
	v_pk_add_f32 v[22:23], v[22:23], v[44:45]
	v_pk_add_f32 v[24:25], v[24:25], v[26:27]
	v_pk_add_f32 v[22:23], v[22:23], v[48:49]
	v_pk_add_f32 v[24:25], v[24:25], v[42:43]
	v_pk_add_f32 v[22:23], v[22:23], v[52:53]
	v_pk_add_f32 v[24:25], v[24:25], v[46:47]
	s_waitcnt lgkmcnt(1)
	v_pk_add_f32 v[22:23], v[22:23], v[56:57]
	v_pk_add_f32 v[24:25], v[24:25], v[50:51]
	s_waitcnt lgkmcnt(0)
	v_pk_add_f32 v[26:27], v[22:23], v[32:33]
	v_mov_b32_e32 v22, v204
	v_pk_add_f32 v[24:25], v[24:25], v[54:55]
	v_lshrrev_b32_e32 v0, 6, v0
	v_mul_lo_u32 v0, v0, s21
	v_add_u32_e32 v23, 0x10000, v0
	v_lshrrev_b32_e32 v0, 2, v22
	v_pk_add_f32 v[28:29], v[24:25], v[30:31]
	v_and_b32_e32 v25, 15, v22
	v_and_b32_e32 v31, 12, v0
	v_bfe_u32 v0, v22, 4, 2
	v_lshlrev_b32_e32 v22, 2, v22
	v_and_b32_e32 v22, 60, v22
	v_lshl_or_b32 v32, v25, 2, v23
	v_lshl_or_b32 v23, v22, 2, v23
	v_or_b32_e32 v24, s24, v0
	v_or_b32_e32 v22, s2, v22
	v_cmp_eq_u32_e64 s[6:7], 0, v25
	v_mad_u32_u24 v33, v0, s22, v23
	v_lshl_add_u32 v30, v24, 10, v22
	v_mad_u32_u24 v25, v31, s22, v32
	ds_write2_b32 v25, v8, v12 offset1:16
	ds_write2_b32 v25, v9, v13 offset0:68 offset1:84
	ds_write2_b32 v25, v6, v10 offset0:136 offset1:152
	ds_write2_b32 v25, v7, v11 offset0:204 offset1:220
	ds_write2_b32 v25, v16, v60 offset0:32 offset1:48
	ds_write2_b32 v25, v17, v61 offset0:100 offset1:116
	ds_write2_b32 v25, v14, v58 offset0:168 offset1:184
	ds_write2_b32 v25, v15, v59 offset0:236 offset1:252
	v_add_u32_e32 v6, 0x1000, v25
	v_add_u32_e32 v7, 0x1400, v25
	ds_write2_b32 v6, v64, v68 offset0:64 offset1:80
	ds_write2_b32 v6, v65, v69 offset0:132 offset1:148
	ds_write2_b32 v6, v62, v66 offset0:200 offset1:216
	ds_write2_b32 v7, v63, v67 offset0:12 offset1:28
	ds_write2_b32 v6, v72, v28 offset0:96 offset1:112
	ds_write2_b32 v6, v73, v29 offset0:164 offset1:180
	ds_write2_b32 v6, v70, v26 offset0:232 offset1:248
	ds_write2_b32 v7, v71, v27 offset0:44 offset1:60
	v_mov_b32_e32 v178, v30
	v_ashrrev_i32_e32 v179, 31, v178
	v_lshl_add_u64 v[176:177], v[178:179], 2, s[10:11]
	global_load_dwordx4 v[144:147], v[176:177], off
	v_or3_b32 v184, v0, s24, 4
	v_lshl_add_u32 v176, v184, 10, v22
	v_ashrrev_i32_e32 v177, 31, v176
	v_lshl_add_u64 v[178:179], v[176:177], 2, s[10:11]
	global_load_dwordx4 v[148:151], v[178:179], off
	v_or3_b32 v184, v0, s24, 8
	v_lshl_add_u32 v176, v184, 10, v22
	v_ashrrev_i32_e32 v177, 31, v176
	v_lshl_add_u64 v[178:179], v[176:177], 2, s[10:11]
	global_load_dwordx4 v[152:155], v[178:179], off
	v_or3_b32 v184, v0, s24, 12
	v_lshl_add_u32 v176, v184, 10, v22
	v_ashrrev_i32_e32 v177, 31, v176
	v_lshl_add_u64 v[178:179], v[176:177], 2, s[10:11]
	global_load_dwordx4 v[156:159], v[178:179], off
	v_or3_b32 v184, v0, s24, 16
	v_lshl_add_u32 v176, v184, 10, v22
	v_ashrrev_i32_e32 v177, 31, v176
	v_lshl_add_u64 v[178:179], v[176:177], 2, s[10:11]
	global_load_dwordx4 v[160:163], v[178:179], off
	v_or3_b32 v184, v0, s24, 20
	v_lshl_add_u32 v176, v184, 10, v22
	v_ashrrev_i32_e32 v177, 31, v176
	v_lshl_add_u64 v[178:179], v[176:177], 2, s[10:11]
	global_load_dwordx4 v[164:167], v[178:179], off
	v_or3_b32 v184, v0, s24, 24
	v_lshl_add_u32 v176, v184, 10, v22
	v_ashrrev_i32_e32 v177, 31, v176
	v_lshl_add_u64 v[178:179], v[176:177], 2, s[10:11]
	global_load_dwordx4 v[168:171], v[178:179], off
	v_or3_b32 v184, v0, s24, 28
	v_lshl_add_u32 v176, v184, 10, v22
	v_ashrrev_i32_e32 v177, 31, v176
	v_lshl_add_u64 v[178:179], v[176:177], 2, s[10:11]
	global_load_dwordx4 v[172:175], v[178:179], off
	v_ashrrev_i32_e32 v31, 31, v30
	v_lshl_add_u64 v[14:15], v[30:31], 2, s[10:11]
	ds_read_b128 v[10:13], v33
	v_lshl_add_u64 v[16:17], v[30:31], 1, s[12:13]
	s_waitcnt vmcnt(7) lgkmcnt(0)
	v_mov_b32_e32 v6, v144
	v_mov_b32_e32 v7, v145
	v_mov_b32_e32 v8, v146
	v_mov_b32_e32 v9, v147
	v_pk_add_f32 v[6:7], v[10:11], v[6:7]
	v_pk_add_f32 v[8:9], v[12:13], v[8:9]
	global_store_dwordx4 v[14:15], v[6:9], off
	v_cvt_pk_bf16_f32 v10, v6, v7
	v_cvt_pk_bf16_f32 v11, v8, v9
	v_pk_mul_f32 v[6:7], v[6:7], v[6:7]
	v_pk_mul_f32 v[8:9], v[8:9], v[8:9]
	v_add_f32_e32 v6, v6, v7
	v_add_f32_e32 v6, v8, v6
	v_add_f32_e32 v6, v9, v6
	v_mov_b32_e32 v7, 0
	global_store_dwordx2 v[16:17], v[10:11], off
	v_add_f32_dpp v6, v6, v6 quad_perm:[1,0,3,2] row_mask:0xf bank_mask:0xf bound_ctrl:1
	s_nop 1
	v_add_f32_dpp v6, v6, v6 quad_perm:[2,3,0,1] row_mask:0xf bank_mask:0xf bound_ctrl:1
	s_nop 1
	v_add_f32_dpp v6, v6, v6 row_half_mirror row_mask:0xf bank_mask:0xf bound_ctrl:1
	s_nop 1
	v_mov_b32_dpp v7, v6 row_mirror row_mask:0xf bank_mask:0xf
	s_and_saveexec_b64 s[2:3], s[6:7]
	s_cbranch_execz .LBB0_1480
	v_add_f32_e32 v6, v6, v7
	v_lshlrev_b32_e32 v7, 2, v24
	global_atomic_add_f32 v7, v6, s[16:17]
; template <class F> __device__ __forceinline__ void rows4(const float* reg, int lane, F f) {
; #pragma unroll
;   for (int it = 0; it < 8; ++it) {
;     if ((it & 3) == 0) __builtin_amdgcn_sched_barrier(0);
;     int rr = it * 4 + (lane >> 4), c4 = (lane & 15) * 4;
;     float4 v = *(const float4*)(reg + rr * 68 + c4);
;     f(it, rr, c4, v);
;   }
;   __device__ __forceinline__ void tile(const float* reg, int row0, int col0, int lane) const {
;     rows4(reg, lane, [&](int it, int rr, int c4, float4 v) {
;       int row = row0 + rr, idx = row * 1024 + col0 + c4;
;       float4 xo = *(const float4*)(xold + idx);
;       v.x = fmaf(coef, v.x, xo.x); v.y = fmaf(coef, v.y, xo.y); v.z = fmaf(coef, v.z, xo.z); v.w = fmaf(coef, v.w, xo.w);
;       *(float4*)(xnew + idx) = v;
;       *(bf16x4*)(xb + idx) = pack4(v.x, v.y, v.z, v.w);
;       float s = row16_sum(v.x * v.x + v.y * v.y + v.z * v.z + v.w * v.w);
;       if ((lane & 15) == 0) atomicAdd(ssqn + row, s);
;     });
.LBB0_1480:
	s_or_b64 exec, exec, s[2:3]
	v_or3_b32 v7, v0, s24, 4
	v_lshl_add_u32 v16, v7, 10, v22
	v_ashrrev_i32_e32 v17, 31, v16
	v_lshl_add_u64 v[24:25], v[16:17], 2, s[10:11]
	v_mul_u32_u24_e32 v6, 0x110, v0
	v_add_u32_e32 v6, v23, v6
	ds_read_b128 v[12:15], v6 offset:1088
	v_lshl_add_u64 v[16:17], v[16:17], 1, s[12:13]
	s_waitcnt vmcnt(9) lgkmcnt(0)
	v_mov_b32_e32 v8, v148
	v_mov_b32_e32 v9, v149
	v_mov_b32_e32 v10, v150
	v_mov_b32_e32 v11, v151
	v_pk_add_f32 v[8:9], v[12:13], v[8:9]
	v_pk_add_f32 v[10:11], v[14:15], v[10:11]
	global_store_dwordx4 v[24:25], v[8:11], off
	v_cvt_pk_bf16_f32 v12, v8, v9
	v_cvt_pk_bf16_f32 v13, v10, v11
	v_pk_mul_f32 v[8:9], v[8:9], v[8:9]
	v_pk_mul_f32 v[10:11], v[10:11], v[10:11]
	v_add_f32_e32 v8, v8, v9
	v_add_f32_e32 v8, v10, v8
	v_add_f32_e32 v8, v11, v8
	v_mov_b32_e32 v9, 0
	global_store_dwordx2 v[16:17], v[12:13], off
	v_add_f32_dpp v8, v8, v8 quad_perm:[1,0,3,2] row_mask:0xf bank_mask:0xf bound_ctrl:1
	s_nop 1
	v_add_f32_dpp v8, v8, v8 quad_perm:[2,3,0,1] row_mask:0xf bank_mask:0xf bound_ctrl:1
	s_nop 1
	v_add_f32_dpp v8, v8, v8 row_half_mirror row_mask:0xf bank_mask:0xf bound_ctrl:1
	s_nop 1
	v_mov_b32_dpp v9, v8 row_mirror row_mask:0xf bank_mask:0xf
	s_and_saveexec_b64 s[2:3], s[6:7]
	s_cbranch_execz .LBB0_1482
	v_add_f32_e32 v8, v8, v9
	v_lshlrev_b32_e32 v7, 2, v7
	global_atomic_add_f32 v7, v8, s[16:17]
.LBB0_1482:
	s_or_b64 exec, exec, s[2:3]
	v_or3_b32 v7, v0, s24, 8
	v_lshl_add_u32 v16, v7, 10, v22
	v_ashrrev_i32_e32 v17, 31, v16
	v_lshl_add_u64 v[24:25], v[16:17], 2, s[10:11]
	ds_read_b128 v[12:15], v6 offset:2176
	v_lshl_add_u64 v[16:17], v[16:17], 1, s[12:13]
	s_waitcnt vmcnt(11) lgkmcnt(0)
	v_mov_b32_e32 v8, v152
	v_mov_b32_e32 v9, v153
	v_mov_b32_e32 v10, v154
	v_mov_b32_e32 v11, v155
	v_pk_add_f32 v[8:9], v[12:13], v[8:9]
	v_pk_add_f32 v[10:11], v[14:15], v[10:11]
	global_store_dwordx4 v[24:25], v[8:11], off
	v_cvt_pk_bf16_f32 v12, v8, v9
	v_cvt_pk_bf16_f32 v13, v10, v11
	v_pk_mul_f32 v[8:9], v[8:9], v[8:9]
	v_pk_mul_f32 v[10:11], v[10:11], v[10:11]
	v_add_f32_e32 v8, v8, v9
	v_add_f32_e32 v8, v10, v8
	v_add_f32_e32 v8, v11, v8
	v_mov_b32_e32 v9, 0
	global_store_dwordx2 v[16:17], v[12:13], off
	v_add_f32_dpp v8, v8, v8 quad_perm:[1,0,3,2] row_mask:0xf bank_mask:0xf bound_ctrl:1
	s_nop 1
	v_add_f32_dpp v8, v8, v8 quad_perm:[2,3,0,1] row_mask:0xf bank_mask:0xf bound_ctrl:1
	s_nop 1
	v_add_f32_dpp v8, v8, v8 row_half_mirror row_mask:0xf bank_mask:0xf bound_ctrl:1
	s_nop 1
	v_mov_b32_dpp v9, v8 row_mirror row_mask:0xf bank_mask:0xf
	s_and_saveexec_b64 s[2:3], s[6:7]
	s_cbranch_execz .LBB0_1484
	v_add_f32_e32 v8, v8, v9
	v_lshlrev_b32_e32 v7, 2, v7
	global_atomic_add_f32 v7, v8, s[16:17]
.LBB0_1484:
	s_or_b64 exec, exec, s[2:3]
	v_or3_b32 v7, v0, s24, 12
	v_lshl_add_u32 v16, v7, 10, v22
	v_ashrrev_i32_e32 v17, 31, v16
	v_lshl_add_u64 v[24:25], v[16:17], 2, s[10:11]
	ds_read_b128 v[12:15], v6 offset:3264
	v_lshl_add_u64 v[16:17], v[16:17], 1, s[12:13]
	s_waitcnt vmcnt(13) lgkmcnt(0)
	v_mov_b32_e32 v8, v156
	v_mov_b32_e32 v9, v157
	v_mov_b32_e32 v10, v158
	v_mov_b32_e32 v11, v159
	v_pk_add_f32 v[8:9], v[12:13], v[8:9]
	v_pk_add_f32 v[10:11], v[14:15], v[10:11]
	global_store_dwordx4 v[24:25], v[8:11], off
	v_cvt_pk_bf16_f32 v12, v8, v9
	v_cvt_pk_bf16_f32 v13, v10, v11
	v_pk_mul_f32 v[8:9], v[8:9], v[8:9]
	v_pk_mul_f32 v[10:11], v[10:11], v[10:11]
	v_add_f32_e32 v8, v8, v9
	v_add_f32_e32 v8, v10, v8
	v_add_f32_e32 v8, v11, v8
	v_mov_b32_e32 v9, 0
	global_store_dwordx2 v[16:17], v[12:13], off
	v_add_f32_dpp v8, v8, v8 quad_perm:[1,0,3,2] row_mask:0xf bank_mask:0xf bound_ctrl:1
	s_nop 1
	v_add_f32_dpp v8, v8, v8 quad_perm:[2,3,0,1] row_mask:0xf bank_mask:0xf bound_ctrl:1
	s_nop 1
	v_add_f32_dpp v8, v8, v8 row_half_mirror row_mask:0xf bank_mask:0xf bound_ctrl:1
	s_nop 1
	v_mov_b32_dpp v9, v8 row_mirror row_mask:0xf bank_mask:0xf
	s_and_saveexec_b64 s[2:3], s[6:7]
	s_cbranch_execz .LBB0_1486
	v_add_f32_e32 v8, v8, v9
	v_lshlrev_b32_e32 v7, 2, v7
	global_atomic_add_f32 v7, v8, s[16:17]
; template <class F> __device__ __forceinline__ void rows4(const float* reg, int lane, F f) {
; #pragma unroll
;   for (int it = 0; it < 8; ++it) {
;     if ((it & 3) == 0) __builtin_amdgcn_sched_barrier(0);
;     int rr = it * 4 + (lane >> 4), c4 = (lane & 15) * 4;
;     float4 v = *(const float4*)(reg + rr * 68 + c4);
;     f(it, rr, c4, v);
;   }
;   __device__ __forceinline__ void tile(const float* reg, int row0, int col0, int lane) const {
;     rows4(reg, lane, [&](int it, int rr, int c4, float4 v) {
;       int row = row0 + rr, idx = row * 1024 + col0 + c4;
;       float4 xo = *(const float4*)(xold + idx);
;       v.x = fmaf(coef, v.x, xo.x); v.y = fmaf(coef, v.y, xo.y); v.z = fmaf(coef, v.z, xo.z); v.w = fmaf(coef, v.w, xo.w);
;       *(float4*)(xnew + idx) = v;
;       *(bf16x4*)(xb + idx) = pack4(v.x, v.y, v.z, v.w);
;       float s = row16_sum(v.x * v.x + v.y * v.y + v.z * v.z + v.w * v.w);
;       if ((lane & 15) == 0) atomicAdd(ssqn + row, s);
;     });
.LBB0_1486:
	s_or_b64 exec, exec, s[2:3]
	v_or3_b32 v7, v0, s24, 16
	v_lshl_add_u32 v16, v7, 10, v22
	v_ashrrev_i32_e32 v17, 31, v16
	v_lshl_add_u64 v[24:25], v[16:17], 2, s[10:11]
	ds_read_b128 v[12:15], v6 offset:4352
	v_lshl_add_u64 v[16:17], v[16:17], 1, s[12:13]
	s_waitcnt vmcnt(15) lgkmcnt(0)
	v_mov_b32_e32 v8, v160
	v_mov_b32_e32 v9, v161
	v_mov_b32_e32 v10, v162
	v_mov_b32_e32 v11, v163
	v_pk_add_f32 v[8:9], v[12:13], v[8:9]
	v_pk_add_f32 v[10:11], v[14:15], v[10:11]
	global_store_dwordx4 v[24:25], v[8:11], off
	v_cvt_pk_bf16_f32 v12, v8, v9
	v_cvt_pk_bf16_f32 v13, v10, v11
	v_pk_mul_f32 v[8:9], v[8:9], v[8:9]
	v_pk_mul_f32 v[10:11], v[10:11], v[10:11]
	v_add_f32_e32 v8, v8, v9
	v_add_f32_e32 v8, v10, v8
	v_add_f32_e32 v8, v11, v8
	v_mov_b32_e32 v9, 0
	global_store_dwordx2 v[16:17], v[12:13], off
	v_add_f32_dpp v8, v8, v8 quad_perm:[1,0,3,2] row_mask:0xf bank_mask:0xf bound_ctrl:1
	s_nop 1
	v_add_f32_dpp v8, v8, v8 quad_perm:[2,3,0,1] row_mask:0xf bank_mask:0xf bound_ctrl:1
	s_nop 1
	v_add_f32_dpp v8, v8, v8 row_half_mirror row_mask:0xf bank_mask:0xf bound_ctrl:1
	s_nop 1
	v_mov_b32_dpp v9, v8 row_mirror row_mask:0xf bank_mask:0xf
	s_and_saveexec_b64 s[2:3], s[6:7]
	s_cbranch_execz .LBB0_1488
	v_add_f32_e32 v8, v8, v9
	v_lshlrev_b32_e32 v7, 2, v7
	global_atomic_add_f32 v7, v8, s[16:17]
.LBB0_1488:
	s_or_b64 exec, exec, s[2:3]
	v_or3_b32 v7, v0, s24, 20
	v_lshl_add_u32 v16, v7, 10, v22
	v_ashrrev_i32_e32 v17, 31, v16
	v_lshl_add_u64 v[24:25], v[16:17], 2, s[10:11]
	ds_read_b128 v[12:15], v6 offset:5440
	v_lshl_add_u64 v[16:17], v[16:17], 1, s[12:13]
	s_waitcnt vmcnt(17) lgkmcnt(0)
	v_mov_b32_e32 v8, v164
	v_mov_b32_e32 v9, v165
	v_mov_b32_e32 v10, v166
	v_mov_b32_e32 v11, v167
	v_pk_add_f32 v[8:9], v[12:13], v[8:9]
	v_pk_add_f32 v[10:11], v[14:15], v[10:11]
	global_store_dwordx4 v[24:25], v[8:11], off
	v_cvt_pk_bf16_f32 v12, v8, v9
	v_cvt_pk_bf16_f32 v13, v10, v11
	v_pk_mul_f32 v[8:9], v[8:9], v[8:9]
	v_pk_mul_f32 v[10:11], v[10:11], v[10:11]
	v_add_f32_e32 v8, v8, v9
	v_add_f32_e32 v8, v10, v8
	v_add_f32_e32 v8, v11, v8
	v_mov_b32_e32 v9, 0
	global_store_dwordx2 v[16:17], v[12:13], off
	v_add_f32_dpp v8, v8, v8 quad_perm:[1,0,3,2] row_mask:0xf bank_mask:0xf bound_ctrl:1
	s_nop 1
	v_add_f32_dpp v8, v8, v8 quad_perm:[2,3,0,1] row_mask:0xf bank_mask:0xf bound_ctrl:1
	s_nop 1
	v_add_f32_dpp v8, v8, v8 row_half_mirror row_mask:0xf bank_mask:0xf bound_ctrl:1
	s_nop 1
	v_mov_b32_dpp v9, v8 row_mirror row_mask:0xf bank_mask:0xf
	s_and_saveexec_b64 s[2:3], s[6:7]
	s_cbranch_execz .LBB0_1490
	v_add_f32_e32 v8, v8, v9
	v_lshlrev_b32_e32 v7, 2, v7
	global_atomic_add_f32 v7, v8, s[16:17]
.LBB0_1490:
	s_or_b64 exec, exec, s[2:3]
	v_or3_b32 v7, v0, s24, 24
	v_lshl_add_u32 v16, v7, 10, v22
	v_ashrrev_i32_e32 v17, 31, v16
	v_lshl_add_u64 v[24:25], v[16:17], 2, s[10:11]
	ds_read_b128 v[12:15], v6 offset:6528
	v_lshl_add_u64 v[16:17], v[16:17], 1, s[12:13]
	s_waitcnt vmcnt(19) lgkmcnt(0)
	v_mov_b32_e32 v8, v168
	v_mov_b32_e32 v9, v169
	v_mov_b32_e32 v10, v170
	v_mov_b32_e32 v11, v171
	v_pk_add_f32 v[8:9], v[12:13], v[8:9]
	v_pk_add_f32 v[10:11], v[14:15], v[10:11]
	global_store_dwordx4 v[24:25], v[8:11], off
	v_cvt_pk_bf16_f32 v12, v8, v9
	v_cvt_pk_bf16_f32 v13, v10, v11
	v_pk_mul_f32 v[8:9], v[8:9], v[8:9]
	v_pk_mul_f32 v[10:11], v[10:11], v[10:11]
	v_add_f32_e32 v8, v8, v9
	v_add_f32_e32 v8, v10, v8
	v_add_f32_e32 v8, v11, v8
	v_mov_b32_e32 v9, 0
	global_store_dwordx2 v[16:17], v[12:13], off
	v_add_f32_dpp v8, v8, v8 quad_perm:[1,0,3,2] row_mask:0xf bank_mask:0xf bound_ctrl:1
	s_nop 1
	v_add_f32_dpp v8, v8, v8 quad_perm:[2,3,0,1] row_mask:0xf bank_mask:0xf bound_ctrl:1
	s_nop 1
	v_add_f32_dpp v8, v8, v8 row_half_mirror row_mask:0xf bank_mask:0xf bound_ctrl:1
	s_nop 1
	v_mov_b32_dpp v9, v8 row_mirror row_mask:0xf bank_mask:0xf
	s_and_saveexec_b64 s[2:3], s[6:7]
	s_cbranch_execz .LBB0_1492
	v_add_f32_e32 v8, v8, v9
	v_lshlrev_b32_e32 v7, 2, v7
	global_atomic_add_f32 v7, v8, s[16:17]
.LBB0_1492:
	s_or_b64 exec, exec, s[2:3]
	v_or3_b32 v0, v0, s24, 28
	v_lshl_add_u32 v16, v0, 10, v22
	v_ashrrev_i32_e32 v17, 31, v16
	v_lshl_add_u64 v[22:23], v[16:17], 2, s[10:11]
	ds_read_b128 v[12:15], v6 offset:7616
	v_lshl_add_u64 v[16:17], v[16:17], 1, s[12:13]
	s_waitcnt vmcnt(21) lgkmcnt(0)
	v_mov_b32_e32 v8, v172
	v_mov_b32_e32 v9, v173
	v_mov_b32_e32 v10, v174
	v_mov_b32_e32 v11, v175
	v_pk_add_f32 v[6:7], v[12:13], v[8:9]
	v_pk_add_f32 v[8:9], v[14:15], v[10:11]
	global_store_dwordx4 v[22:23], v[6:9], off
	v_cvt_pk_bf16_f32 v10, v6, v7
	v_cvt_pk_bf16_f32 v11, v8, v9
	v_pk_mul_f32 v[6:7], v[6:7], v[6:7]
	v_pk_mul_f32 v[8:9], v[8:9], v[8:9]
	v_add_f32_e32 v6, v6, v7
	v_add_f32_e32 v6, v8, v6
	v_add_f32_e32 v6, v9, v6
	v_mov_b32_e32 v7, 0
	global_store_dwordx2 v[16:17], v[10:11], off
	v_add_f32_dpp v6, v6, v6 quad_perm:[1,0,3,2] row_mask:0xf bank_mask:0xf bound_ctrl:1
	s_nop 1
	v_add_f32_dpp v6, v6, v6 quad_perm:[2,3,0,1] row_mask:0xf bank_mask:0xf bound_ctrl:1
	s_nop 1
	v_add_f32_dpp v6, v6, v6 row_half_mirror row_mask:0xf bank_mask:0xf bound_ctrl:1
	s_nop 1
	v_mov_b32_dpp v7, v6 row_mirror row_mask:0xf bank_mask:0xf
	s_and_b64 exec, exec, s[6:7]
	s_cbranch_execz .LBB0_1475
	v_add_f32_e32 v6, v6, v7
	v_lshlrev_b32_e32 v0, 2, v0
	global_atomic_add_f32 v0, v6, s[16:17]
	s_branch .LBB0_1475

; template <class Epi>
; __device__ __forceinline__ void small_gemm(const u16* __restrict__ A, const u16* __restrict__ Bt, int K, int N, const Epi& epi) {
;     ...
;   for (int piece = blockIdx.x; piece < npieces; piece += gridDim.x) {
;     int row0 = (piece & 3) * 32, col0 = (piece >> 2) * 64;
;     f32x4 acc[2][4] = {};
;     int kper = K >> 3, k0 = wid * kper;
;     for (int kk = k0; kk < k0 + kper; kk += 32) {
;       bf16x8 a[2], b[4];
; #pragma unroll
;       for (int m = 0; m < 2; ++m) a[m] = *(const bf16x8*)(A + (size_t)(row0 + m * 16 + fr) * K + kk + fq * 8);
; #pragma unroll
;       for (int n = 0; n < 4; ++n) b[n] = *(const bf16x8*)(Bt + (size_t)(col0 + n * 16 + fr) * K + kk + fq * 8);
; #pragma unroll
;       for (int m = 0; m < 2; ++m)
; #pragma unroll
;         for (int n = 0; n < 4; ++n) acc[m][n] = __builtin_amdgcn_mfma_f32_16x16x32_bf16(a[m], b[n], acc[m][n], 0, 0, 0);
;     }
;     __syncthreads();
; #pragma unroll
;     for (int m = 0; m < 2; ++m)
; #pragma unroll
;       for (int n = 0; n < 4; ++n) red[(wid * 8 + m * 4 + n) * 64 + lane] = acc[m][n];
;     __syncthreads();
;     if (wid == 0) {
; #pragma unroll
;       for (int m = 0; m < 2; ++m)
; #pragma unroll
;         for (int n = 0; n < 4; ++n) {
;           f32x4 s = red[(m * 4 + n) * 64 + lane];
; #pragma unroll
;           for (int w = 1; w < 8; ++w) s += red[(w * 8 + m * 4 + n) * 64 + lane];
;           acc[m][n] = s;
;         }
.LBB0_1598:
	v_lshl_add_u64 v[58:59], v[46:47], 0, v[36:37]
	v_add_co_u32_e64 v82, s[10:11], s21, v58
	v_lshl_add_u64 v[74:75], v[46:47], 0, v[38:39]
	s_nop 0
	v_addc_co_u32_e64 v83, s[10:11], 0, v59, s[10:11]
	v_lshl_add_u64 v[76:77], v[46:47], 0, v[40:41]
	v_lshl_add_u64 v[78:79], v[46:47], 0, v[42:43]
	v_lshl_add_u64 v[80:81], v[46:47], 0, v[44:45]
	v_add_co_u32_e64 v84, s[10:11], s22, v58
	v_add_u32_e32 v56, 32, v56
	s_nop 0
	v_addc_co_u32_e64 v85, s[10:11], 0, v59, s[10:11]
	global_load_dwordx4 v[58:61], v[74:75], off
	global_load_dwordx4 v[62:65], v[76:77], off
	global_load_dwordx4 v[66:69], v[82:83], off
	global_load_dwordx4 v[70:73], v[84:85], off
	v_cmp_ge_i32_e64 s[10:11], v56, v50
	global_load_dwordx4 v[74:77], v[78:79], off
	s_or_b64 s[0:1], s[10:11], s[0:1]
	global_load_dwordx4 v[78:81], v[80:81], off
	v_lshl_add_u64 v[46:47], v[46:47], 0, 64
	s_waitcnt vmcnt(3)
	v_mfma_f32_16x16x32_bf16 v[28:31], v[66:69], v[58:61], v[28:31]
	v_mfma_f32_16x16x32_bf16 v[24:27], v[66:69], v[62:65], v[24:27]
	s_waitcnt vmcnt(1)
	v_mfma_f32_16x16x32_bf16 v[20:23], v[66:69], v[74:77], v[20:23]
	s_waitcnt vmcnt(0)
	v_mfma_f32_16x16x32_bf16 v[16:19], v[66:69], v[78:81], v[16:19]
	v_mfma_f32_16x16x32_bf16 v[12:15], v[70:73], v[58:61], v[12:15]
	v_mfma_f32_16x16x32_bf16 v[8:11], v[70:73], v[62:65], v[8:11]
	v_mfma_f32_16x16x32_bf16 v[4:7], v[70:73], v[74:77], v[4:7]
	v_mfma_f32_16x16x32_bf16 v[0:3], v[70:73], v[78:81], v[0:3]
	s_andn2_b64 exec, exec, s[0:1]
	s_cbranch_execnz .LBB0_1598
	s_or_b64 exec, exec, s[0:1]
	s_barrier
	ds_write_b128 v55, v[28:31]
	ds_write_b128 v55, v[24:27] offset:1024
	ds_write_b128 v55, v[20:23] offset:2048
	ds_write_b128 v55, v[16:19] offset:3072
	ds_write_b128 v55, v[12:15] offset:4096
	ds_write_b128 v55, v[8:11] offset:5120
	ds_write_b128 v55, v[4:7] offset:6144
	ds_write_b128 v55, v[0:3] offset:7168
	s_waitcnt lgkmcnt(0)
	s_barrier
	s_and_saveexec_b64 s[0:1], vcc
	s_cbranch_execz .LBB0_1596
	ds_read_b128 v[0:3], v49
	ds_read_b128 v[4:7], v49 offset:8192
	ds_read_b128 v[8:11], v49 offset:16384
	ds_read_b128 v[12:15], v49 offset:1024
	ds_read_b128 v[16:19], v49 offset:9216
	s_andn2_b32 s2, s2, 63
	s_waitcnt lgkmcnt(3)
	v_pk_add_f32 v[20:21], v[2:3], v[6:7]
	v_pk_add_f32 v[22:23], v[0:1], v[4:5]
	ds_read_b128 v[0:3], v49 offset:24576
	ds_read_b128 v[4:7], v49 offset:17408
	s_waitcnt lgkmcnt(4)
	v_pk_add_f32 v[24:25], v[20:21], v[10:11]
	v_pk_add_f32 v[26:27], v[22:23], v[8:9]
	ds_read_b128 v[8:11], v49 offset:32768
	ds_read_b128 v[20:23], v49 offset:25600
	s_waitcnt lgkmcnt(3)
	v_pk_add_f32 v[28:29], v[24:25], v[2:3]
	v_pk_add_f32 v[30:31], v[26:27], v[0:1]
	ds_read_b128 v[0:3], v49 offset:40960
	ds_read_b128 v[24:27], v49 offset:33792
	s_waitcnt lgkmcnt(3)
	v_pk_add_f32 v[38:39], v[28:29], v[10:11]
	v_pk_add_f32 v[40:41], v[30:31], v[8:9]
	ds_read_b128 v[8:11], v49 offset:49152
	ds_read_b128 v[28:31], v49 offset:41984
	s_waitcnt lgkmcnt(3)
	v_pk_add_f32 v[2:3], v[38:39], v[2:3]
	v_pk_add_f32 v[0:1], v[40:41], v[0:1]
	ds_read_b128 v[38:41], v49 offset:57344
	ds_read_b128 v[42:45], v49 offset:50176
	v_pk_add_f32 v[14:15], v[14:15], v[18:19]
	s_waitcnt lgkmcnt(3)
	v_pk_add_f32 v[2:3], v[2:3], v[10:11]
	v_pk_add_f32 v[46:47], v[0:1], v[8:9]
	ds_read_b128 v[8:11], v49 offset:58368
	v_pk_add_f32 v[12:13], v[12:13], v[16:17]
	v_pk_add_f32 v[6:7], v[14:15], v[6:7]
	v_pk_add_f32 v[4:5], v[12:13], v[4:5]
	v_pk_add_f32 v[6:7], v[6:7], v[22:23]
	v_pk_add_f32 v[4:5], v[4:5], v[20:21]
	v_pk_add_f32 v[6:7], v[6:7], v[26:27]
	v_pk_add_f32 v[4:5], v[4:5], v[24:25]
	s_waitcnt lgkmcnt(3)
	v_pk_add_f32 v[6:7], v[6:7], v[30:31]
	v_pk_add_f32 v[4:5], v[4:5], v[28:29]
	s_waitcnt lgkmcnt(1)
	v_pk_add_f32 v[6:7], v[6:7], v[44:45]
	v_pk_add_f32 v[18:19], v[4:5], v[42:43]
	s_waitcnt lgkmcnt(0)
	v_pk_add_f32 v[4:5], v[6:7], v[10:11]
	ds_read_b128 v[10:13], v49 offset:2048
	ds_read_b128 v[14:17], v49 offset:10240
	v_pk_add_f32 v[6:7], v[18:19], v[8:9]
	ds_read_b128 v[18:21], v49 offset:18432
	ds_read_b128 v[22:25], v49 offset:3072
	ds_read_b128 v[26:29], v49 offset:11264
	v_pk_add_f32 v[0:1], v[2:3], v[40:41]
	v_pk_add_f32 v[2:3], v[46:47], v[38:39]
	s_waitcnt lgkmcnt(3)
	v_pk_add_f32 v[16:17], v[12:13], v[16:17]
	v_pk_add_f32 v[30:31], v[10:11], v[14:15]
	ds_read_b128 v[8:11], v49 offset:26624
	ds_read_b128 v[12:15], v49 offset:19456
	s_waitcnt lgkmcnt(4)
	v_pk_add_f32 v[20:21], v[16:17], v[20:21]
	v_pk_add_f32 v[30:31], v[30:31], v[18:19]
	ds_read_b128 v[16:19], v49 offset:34816
	ds_read_b128 v[38:41], v49 offset:27648
	s_waitcnt lgkmcnt(3)
	v_pk_add_f32 v[20:21], v[20:21], v[10:11]
	v_pk_add_f32 v[30:31], v[30:31], v[8:9]
	ds_read_b128 v[8:11], v49 offset:43008
	ds_read_b128 v[42:45], v49 offset:35840
	s_waitcnt lgkmcnt(3)
	v_pk_add_f32 v[20:21], v[20:21], v[18:19]
	v_pk_add_f32 v[30:31], v[30:31], v[16:17]
	ds_read_b128 v[16:19], v49 offset:51200
	ds_read_b128 v[56:59], v49 offset:44032
	ds_read_b128 v[60:63], v49 offset:59392
	ds_read_b128 v[64:67], v49 offset:52224
	s_waitcnt lgkmcnt(5)
	v_pk_add_f32 v[10:11], v[20:21], v[10:11]
	v_pk_add_f32 v[8:9], v[30:31], v[8:9]
	s_waitcnt lgkmcnt(3)
	v_pk_add_f32 v[10:11], v[10:11], v[18:19]
	v_pk_add_f32 v[20:21], v[8:9], v[16:17]
	s_waitcnt lgkmcnt(1)
	v_pk_add_f32 v[8:9], v[10:11], v[62:63]
	v_pk_add_f32 v[10:11], v[20:21], v[60:61]
	v_pk_add_f32 v[20:21], v[24:25], v[28:29]
	ds_read_b128 v[16:19], v49 offset:60416
	v_pk_add_f32 v[22:23], v[22:23], v[26:27]
	v_pk_add_f32 v[14:15], v[20:21], v[14:15]
	v_pk_add_f32 v[12:13], v[22:23], v[12:13]
	v_pk_add_f32 v[14:15], v[14:15], v[40:41]
	v_pk_add_f32 v[12:13], v[12:13], v[38:39]
	v_pk_add_f32 v[14:15], v[14:15], v[44:45]
	v_pk_add_f32 v[12:13], v[12:13], v[42:43]
	v_pk_add_f32 v[14:15], v[14:15], v[58:59]
	v_pk_add_f32 v[12:13], v[12:13], v[56:57]
	s_waitcnt lgkmcnt(1)
; template <int MF, class Epi>
; __device__ __forceinline__ void staged_epilogue(f32x4 (&acc)[MF][4], int row0, int col0, const Epi& epi) {
;   const int lane = tidx() & 63, wid = tidx() >> 6, fr = lane & 15, fq = lane >> 4;
;   float* reg = (float*)(g_shm + 65536 + wid * 8704);
; #pragma unroll
;   for (int mp = 0; mp < MF / 2; ++mp) {
;     __builtin_amdgcn_sched_barrier(0);
; #pragma unroll
;     for (int mm = 0; mm < 2; ++mm)
; #pragma unroll
;       for (int n = 0; n < 4; ++n)
; #pragma unroll
;         for (int j = 0; j < 4; ++j) reg[(mm * 16 + fq * 4 + j) * 68 + n * 16 + fr] = acc[mp * 2 + mm][n][j];
;     __builtin_amdgcn_fence(__ATOMIC_ACQ_REL, "wavefront");
; template <class Epi>
; __device__ __forceinline__ void small_gemm(const u16* __restrict__ A, const u16* __restrict__ Bt, int K, int N, const Epi& epi) {
;     ...
;       for (int m = 0; m < 2; ++m)
; #pragma unroll
;         for (int n = 0; n < 4; ++n) {
;           f32x4 s = red[(m * 4 + n) * 64 + lane];
; #pragma unroll
;           for (int w = 1; w < 8; ++w) s += red[(w * 8 + m * 4 + n) * 64 + lane];
;           acc[m][n] = s;
;         }
;       staged_epilogue<2>(acc, row0, col0, epi);
	v_pk_add_f32 v[14:15], v[14:15], v[66:67]
	v_pk_add_f32 v[22:23], v[12:13], v[64:65]
	s_waitcnt lgkmcnt(0)
	v_pk_add_f32 v[46:47], v[14:15], v[18:19]
	ds_read_b128 v[12:15], v49 offset:4096
	ds_read_b128 v[18:21], v49 offset:12288
	v_pk_add_f32 v[68:69], v[22:23], v[16:17]
	ds_read_b128 v[22:25], v49 offset:20480
	ds_read_b128 v[26:29], v49 offset:5120
	ds_read_b128 v[38:41], v49 offset:13312
	s_waitcnt lgkmcnt(3)
	v_pk_add_f32 v[20:21], v[14:15], v[20:21]
	v_pk_add_f32 v[30:31], v[12:13], v[18:19]
	ds_read_b128 v[12:15], v49 offset:28672
	ds_read_b128 v[16:19], v49 offset:21504
	s_waitcnt lgkmcnt(4)
	v_pk_add_f32 v[24:25], v[20:21], v[24:25]
	v_pk_add_f32 v[30:31], v[30:31], v[22:23]
	ds_read_b128 v[20:23], v49 offset:36864
	ds_read_b128 v[42:45], v49 offset:29696
	s_waitcnt lgkmcnt(3)
	v_pk_add_f32 v[24:25], v[24:25], v[14:15]
	v_pk_add_f32 v[30:31], v[30:31], v[12:13]
	ds_read_b128 v[12:15], v49 offset:45056
	ds_read_b128 v[56:59], v49 offset:37888
	s_waitcnt lgkmcnt(3)
	v_pk_add_f32 v[24:25], v[24:25], v[22:23]
	v_pk_add_f32 v[30:31], v[30:31], v[20:21]
	ds_read_b128 v[20:23], v49 offset:53248
	ds_read_b128 v[60:63], v49 offset:46080
	s_waitcnt lgkmcnt(3)
	v_pk_add_f32 v[24:25], v[24:25], v[14:15]
	v_pk_add_f32 v[30:31], v[30:31], v[12:13]
	ds_read_b128 v[12:15], v49 offset:61440
	ds_read_b128 v[64:67], v49 offset:54272
	s_waitcnt lgkmcnt(3)
	v_pk_add_f32 v[30:31], v[30:31], v[20:21]
	v_pk_add_f32 v[24:25], v[24:25], v[22:23]
	ds_read_b128 v[20:23], v49 offset:62464
	s_waitcnt lgkmcnt(2)
	v_pk_add_f32 v[72:73], v[30:31], v[12:13]
	v_pk_add_f32 v[12:13], v[28:29], v[40:41]
	v_pk_add_f32 v[70:71], v[24:25], v[14:15]
	v_pk_add_f32 v[14:15], v[26:27], v[38:39]
	v_pk_add_f32 v[12:13], v[12:13], v[18:19]
	v_pk_add_f32 v[14:15], v[14:15], v[16:17]
	v_pk_add_f32 v[12:13], v[12:13], v[44:45]
	v_pk_add_f32 v[14:15], v[14:15], v[42:43]
	v_pk_add_f32 v[12:13], v[12:13], v[58:59]
	v_pk_add_f32 v[14:15], v[14:15], v[56:57]
	v_pk_add_f32 v[12:13], v[12:13], v[62:63]
	v_pk_add_f32 v[14:15], v[14:15], v[60:61]
	s_waitcnt lgkmcnt(1)
	v_pk_add_f32 v[12:13], v[12:13], v[66:67]
	v_pk_add_f32 v[24:25], v[14:15], v[64:65]
	s_waitcnt lgkmcnt(0)
	v_pk_add_f32 v[64:65], v[12:13], v[22:23]
	ds_read_b128 v[12:15], v49 offset:6144
	ds_read_b128 v[16:19], v49 offset:14336
	v_pk_add_f32 v[66:67], v[24:25], v[20:21]
	ds_read_b128 v[20:23], v49 offset:22528
	ds_read_b128 v[24:27], v49 offset:7168
	ds_read_b128 v[28:31], v49 offset:15360
	s_waitcnt lgkmcnt(3)
	v_pk_add_f32 v[38:39], v[14:15], v[18:19]
	v_pk_add_f32 v[40:41], v[12:13], v[16:17]
	ds_read_b128 v[12:15], v49 offset:30720
	ds_read_b128 v[16:19], v49 offset:23552
	s_waitcnt lgkmcnt(4)
	v_pk_add_f32 v[42:43], v[38:39], v[22:23]
	v_pk_add_f32 v[44:45], v[40:41], v[20:21]
	ds_read_b128 v[20:23], v49 offset:38912
	ds_read_b128 v[38:41], v49 offset:31744
	s_waitcnt lgkmcnt(3)
	v_pk_add_f32 v[56:57], v[42:43], v[14:15]
	v_pk_add_f32 v[58:59], v[44:45], v[12:13]
	ds_read_b128 v[12:15], v49 offset:47104
	ds_read_b128 v[42:45], v49 offset:39936
	s_waitcnt lgkmcnt(3)
	v_pk_add_f32 v[60:61], v[56:57], v[22:23]
	v_pk_add_f32 v[62:63], v[58:59], v[20:21]
	ds_read_b128 v[20:23], v49 offset:55296
	ds_read_b128 v[56:59], v49 offset:48128
	s_waitcnt lgkmcnt(3)
	v_pk_add_f32 v[74:75], v[60:61], v[14:15]
	v_pk_add_f32 v[76:77], v[62:63], v[12:13]
	ds_read_b128 v[12:15], v49 offset:63488
	ds_read_b128 v[60:63], v49 offset:56320
	s_waitcnt lgkmcnt(3)
	v_pk_add_f32 v[76:77], v[76:77], v[20:21]
	v_pk_add_f32 v[74:75], v[74:75], v[22:23]
	ds_read_b128 v[20:23], v49 offset:64512
	s_waitcnt lgkmcnt(2)
	v_pk_add_f32 v[76:77], v[76:77], v[12:13]
	v_pk_add_f32 v[12:13], v[26:27], v[30:31]
	v_pk_add_f32 v[74:75], v[74:75], v[14:15]
	v_pk_add_f32 v[12:13], v[12:13], v[18:19]
	v_pk_add_f32 v[14:15], v[24:25], v[28:29]
	v_pk_add_f32 v[12:13], v[12:13], v[40:41]
	v_pk_add_f32 v[14:15], v[14:15], v[16:17]
	v_pk_add_f32 v[12:13], v[12:13], v[44:45]
	v_pk_add_f32 v[14:15], v[14:15], v[38:39]
	v_pk_add_f32 v[12:13], v[12:13], v[58:59]
	v_pk_add_f32 v[14:15], v[14:15], v[42:43]
	s_waitcnt lgkmcnt(1)
	v_pk_add_f32 v[12:13], v[12:13], v[62:63]
	v_pk_add_f32 v[14:15], v[14:15], v[56:57]
	s_waitcnt lgkmcnt(0)
	v_pk_add_f32 v[16:17], v[12:13], v[22:23]
	v_mov_b32_e32 v13, v204
	v_mov_b32_e32 v12, v204
	v_pk_add_f32 v[14:15], v[14:15], v[60:61]
	v_lshrrev_b32_e32 v12, 6, v12
	v_mul_lo_u32 v12, v12, s23
	v_pk_add_f32 v[18:19], v[14:15], v[20:21]
	v_add_u32_e32 v14, 0x10000, v12
	v_lshrrev_b32_e32 v12, 2, v13
	v_and_b32_e32 v21, 15, v13
	v_and_b32_e32 v22, 12, v12
	v_bfe_u32 v12, v13, 4, 2
	v_lshlrev_b32_e32 v13, 2, v13
	v_and_b32_e32 v13, 60, v13
	v_lshl_or_b32 v23, v21, 2, v14
	v_lshl_or_b32 v14, v13, 2, v14
	v_or_b32_e32 v15, s26, v12
	v_or_b32_e32 v13, s2, v13
	v_cmp_eq_u32_e64 s[10:11], 0, v21
	v_mad_u32_u24 v24, v12, s24, v14
	v_lshl_add_u32 v20, v15, 10, v13
	v_mad_u32_u24 v21, v22, s24, v23
	ds_write2_b32 v21, v2, v6 offset1:16
	ds_write2_b32 v21, v3, v7 offset0:68 offset1:84
	ds_write2_b32 v21, v0, v4 offset0:136 offset1:152
	ds_write2_b32 v21, v1, v5 offset0:204 offset1:220
	ds_write2_b32 v21, v10, v68 offset0:32 offset1:48
	ds_write2_b32 v21, v11, v69 offset0:100 offset1:116
	ds_write2_b32 v21, v8, v46 offset0:168 offset1:184
	ds_write2_b32 v21, v9, v47 offset0:236 offset1:252
	v_add_u32_e32 v0, 0x1000, v21
	v_add_u32_e32 v1, 0x1400, v21
	ds_write2_b32 v0, v72, v66 offset0:64 offset1:80
	ds_write2_b32 v0, v73, v67 offset0:132 offset1:148
	ds_write2_b32 v0, v70, v64 offset0:200 offset1:216
	ds_write2_b32 v1, v71, v65 offset0:12 offset1:28
	ds_write2_b32 v0, v76, v18 offset0:96 offset1:112
	ds_write2_b32 v0, v77, v19 offset0:164 offset1:180
; template <class F> __device__ __forceinline__ void rows4(const float* reg, int lane, F f) {
; #pragma unroll
;   for (int it = 0; it < 8; ++it) {
;     if ((it & 3) == 0) __builtin_amdgcn_sched_barrier(0);
;     int rr = it * 4 + (lane >> 4), c4 = (lane & 15) * 4;
;     float4 v = *(const float4*)(reg + rr * 68 + c4);
;     f(it, rr, c4, v);
;   }
;   __device__ __forceinline__ void tile(const float* reg, int row0, int col0, int lane) const {
;     rows4(reg, lane, [&](int it, int rr, int c4, float4 v) {
;       int row = row0 + rr, idx = row * 1024 + col0 + c4;
;       float4 xo = *(const float4*)(xold + idx);
;       v.x = fmaf(coef, v.x, xo.x); v.y = fmaf(coef, v.y, xo.y); v.z = fmaf(coef, v.z, xo.z); v.w = fmaf(coef, v.w, xo.w);
;       *(float4*)(xnew + idx) = v;
;       *(bf16x4*)(xb + idx) = pack4(v.x, v.y, v.z, v.w);
;       float s = row16_sum(v.x * v.x + v.y * v.y + v.z * v.z + v.w * v.w);
;       if ((lane & 15) == 0) atomicAdd(ssqn + row, s);
;     });
	ds_write2_b32 v0, v74, v16 offset0:232 offset1:248
	ds_write2_b32 v1, v75, v17 offset0:44 offset1:60
	v_mov_b32_e32 v178, v20
	v_ashrrev_i32_e32 v179, 31, v178
	v_lshl_add_u64 v[176:177], v[178:179], 2, s[12:13]
	global_load_dwordx4 v[144:147], v[176:177], off
	v_or3_b32 v184, v12, s26, 4
	v_lshl_add_u32 v176, v184, 10, v13
	v_ashrrev_i32_e32 v177, 31, v176
	v_lshl_add_u64 v[178:179], v[176:177], 2, s[12:13]
	global_load_dwordx4 v[148:151], v[178:179], off
	v_or3_b32 v184, v12, s26, 8
	v_lshl_add_u32 v176, v184, 10, v13
	v_ashrrev_i32_e32 v177, 31, v176
	v_lshl_add_u64 v[178:179], v[176:177], 2, s[12:13]
	global_load_dwordx4 v[152:155], v[178:179], off
	v_or3_b32 v184, v12, s26, 12
	v_lshl_add_u32 v176, v184, 10, v13
	v_ashrrev_i32_e32 v177, 31, v176
	v_lshl_add_u64 v[178:179], v[176:177], 2, s[12:13]
	global_load_dwordx4 v[156:159], v[178:179], off
	v_or3_b32 v184, v12, s26, 16
	v_lshl_add_u32 v176, v184, 10, v13
	v_ashrrev_i32_e32 v177, 31, v176
	v_lshl_add_u64 v[178:179], v[176:177], 2, s[12:13]
	global_load_dwordx4 v[160:163], v[178:179], off
	v_or3_b32 v184, v12, s26, 20
	v_lshl_add_u32 v176, v184, 10, v13
	v_ashrrev_i32_e32 v177, 31, v176
	v_lshl_add_u64 v[178:179], v[176:177], 2, s[12:13]
	global_load_dwordx4 v[164:167], v[178:179], off
	v_or3_b32 v184, v12, s26, 24
	v_lshl_add_u32 v176, v184, 10, v13
	v_ashrrev_i32_e32 v177, 31, v176
	v_lshl_add_u64 v[178:179], v[176:177], 2, s[12:13]
	global_load_dwordx4 v[168:171], v[178:179], off
	v_or3_b32 v184, v12, s26, 28
	v_lshl_add_u32 v176, v184, 10, v13
	v_ashrrev_i32_e32 v177, 31, v176
	v_lshl_add_u64 v[178:179], v[176:177], 2, s[12:13]
	global_load_dwordx4 v[172:175], v[178:179], off
	v_ashrrev_i32_e32 v21, 31, v20
	v_lshl_add_u64 v[8:9], v[20:21], 2, s[12:13]
	ds_read_b128 v[4:7], v24
	v_lshl_add_u64 v[10:11], v[20:21], 1, s[16:17]
	s_waitcnt vmcnt(7) lgkmcnt(0)
	v_mov_b32_e32 v0, v144
	v_mov_b32_e32 v1, v145
	v_mov_b32_e32 v2, v146
	v_mov_b32_e32 v3, v147
	v_pk_fma_f32 v[0:1], v[4:5], 0.5, v[0:1] op_sel_hi:[1,0,1]
	v_pk_fma_f32 v[2:3], v[6:7], 0.5, v[2:3] op_sel_hi:[1,0,1]
	global_store_dwordx4 v[8:9], v[0:3], off
	v_cvt_pk_bf16_f32 v4, v0, v1
	v_cvt_pk_bf16_f32 v5, v2, v3
	v_pk_mul_f32 v[0:1], v[0:1], v[0:1]
	v_pk_mul_f32 v[2:3], v[2:3], v[2:3]
	v_add_f32_e32 v0, v0, v1
	v_add_f32_e32 v0, v2, v0
	v_add_f32_e32 v0, v3, v0
	v_mov_b32_e32 v1, v37
	global_store_dwordx2 v[10:11], v[4:5], off
	v_add_f32_dpp v0, v0, v0 quad_perm:[1,0,3,2] row_mask:0xf bank_mask:0xf bound_ctrl:1
	s_nop 1
	v_add_f32_dpp v0, v0, v0 quad_perm:[2,3,0,1] row_mask:0xf bank_mask:0xf bound_ctrl:1
	s_nop 1
	v_add_f32_dpp v0, v0, v0 row_half_mirror row_mask:0xf bank_mask:0xf bound_ctrl:1
	s_nop 1
	v_mov_b32_dpp v1, v0 row_mirror row_mask:0xf bank_mask:0xf
	s_and_saveexec_b64 s[2:3], s[10:11]
	s_cbranch_execz .LBB0_1602
	v_add_f32_e32 v0, v0, v1
	v_lshlrev_b32_e32 v1, 2, v15
	global_atomic_add_f32 v1, v0, s[18:19]
.LBB0_1602:
	s_or_b64 exec, exec, s[2:3]
	v_or3_b32 v1, v12, s26, 4
	v_lshl_add_u32 v10, v1, 10, v13
	v_ashrrev_i32_e32 v11, 31, v10
	v_lshl_add_u64 v[16:17], v[10:11], 2, s[12:13]
	v_mul_u32_u24_e32 v0, 0x110, v12
	v_add_u32_e32 v0, v14, v0
	ds_read_b128 v[6:9], v0 offset:1088
	v_lshl_add_u64 v[10:11], v[10:11], 1, s[16:17]
	s_waitcnt vmcnt(9) lgkmcnt(0)
	v_mov_b32_e32 v2, v148
	v_mov_b32_e32 v3, v149
	v_mov_b32_e32 v4, v150
	v_mov_b32_e32 v5, v151
	v_pk_fma_f32 v[2:3], v[6:7], 0.5, v[2:3] op_sel_hi:[1,0,1]
	v_pk_fma_f32 v[4:5], v[8:9], 0.5, v[4:5] op_sel_hi:[1,0,1]
	global_store_dwordx4 v[16:17], v[2:5], off
	v_cvt_pk_bf16_f32 v6, v2, v3
	v_cvt_pk_bf16_f32 v7, v4, v5
	v_pk_mul_f32 v[2:3], v[2:3], v[2:3]
	v_pk_mul_f32 v[4:5], v[4:5], v[4:5]
	v_add_f32_e32 v2, v2, v3
	v_add_f32_e32 v2, v4, v2
	v_add_f32_e32 v2, v5, v2
	v_mov_b32_e32 v3, 0
	global_store_dwordx2 v[10:11], v[6:7], off
	v_add_f32_dpp v2, v2, v2 quad_perm:[1,0,3,2] row_mask:0xf bank_mask:0xf bound_ctrl:1
	s_nop 1
	v_add_f32_dpp v2, v2, v2 quad_perm:[2,3,0,1] row_mask:0xf bank_mask:0xf bound_ctrl:1
	s_nop 1
	v_add_f32_dpp v2, v2, v2 row_half_mirror row_mask:0xf bank_mask:0xf bound_ctrl:1
	s_nop 1
	v_mov_b32_dpp v3, v2 row_mirror row_mask:0xf bank_mask:0xf
	s_and_saveexec_b64 s[2:3], s[10:11]
	s_cbranch_execz .LBB0_1604
	v_add_f32_e32 v2, v2, v3
	v_lshlrev_b32_e32 v1, 2, v1
	global_atomic_add_f32 v1, v2, s[18:19]
.LBB0_1604:
	s_or_b64 exec, exec, s[2:3]
	v_or3_b32 v1, v12, s26, 8
	v_lshl_add_u32 v10, v1, 10, v13
	v_ashrrev_i32_e32 v11, 31, v10
	v_lshl_add_u64 v[14:15], v[10:11], 2, s[12:13]
	ds_read_b128 v[6:9], v0 offset:2176
	v_lshl_add_u64 v[10:11], v[10:11], 1, s[16:17]
	s_waitcnt vmcnt(11) lgkmcnt(0)
	v_mov_b32_e32 v2, v152
	v_mov_b32_e32 v3, v153
	v_mov_b32_e32 v4, v154
	v_mov_b32_e32 v5, v155
	v_pk_fma_f32 v[2:3], v[6:7], 0.5, v[2:3] op_sel_hi:[1,0,1]
	v_pk_fma_f32 v[4:5], v[8:9], 0.5, v[4:5] op_sel_hi:[1,0,1]
	global_store_dwordx4 v[14:15], v[2:5], off
	v_cvt_pk_bf16_f32 v6, v2, v3
	v_cvt_pk_bf16_f32 v7, v4, v5
	v_pk_mul_f32 v[2:3], v[2:3], v[2:3]
	v_pk_mul_f32 v[4:5], v[4:5], v[4:5]
	v_add_f32_e32 v2, v2, v3
	v_add_f32_e32 v2, v4, v2
	v_add_f32_e32 v2, v5, v2
	v_mov_b32_e32 v3, 0
	global_store_dwordx2 v[10:11], v[6:7], off
	v_add_f32_dpp v2, v2, v2 quad_perm:[1,0,3,2] row_mask:0xf bank_mask:0xf bound_ctrl:1
	s_nop 1
	v_add_f32_dpp v2, v2, v2 quad_perm:[2,3,0,1] row_mask:0xf bank_mask:0xf bound_ctrl:1
	s_nop 1
	v_add_f32_dpp v2, v2, v2 row_half_mirror row_mask:0xf bank_mask:0xf bound_ctrl:1
	s_nop 1
	v_mov_b32_dpp v3, v2 row_mirror row_mask:0xf bank_mask:0xf
	s_and_saveexec_b64 s[2:3], s[10:11]
	s_cbranch_execz .LBB0_1606
	v_add_f32_e32 v2, v2, v3
	v_lshlrev_b32_e32 v1, 2, v1
	global_atomic_add_f32 v1, v2, s[18:19]
; template <class F> __device__ __forceinline__ void rows4(const float* reg, int lane, F f) {
; #pragma unroll
;   for (int it = 0; it < 8; ++it) {
;     if ((it & 3) == 0) __builtin_amdgcn_sched_barrier(0);
;     int rr = it * 4 + (lane >> 4), c4 = (lane & 15) * 4;
;     float4 v = *(const float4*)(reg + rr * 68 + c4);
;     f(it, rr, c4, v);
;   }
;   __device__ __forceinline__ void tile(const float* reg, int row0, int col0, int lane) const {
;     rows4(reg, lane, [&](int it, int rr, int c4, float4 v) {
;       int row = row0 + rr, idx = row * 1024 + col0 + c4;
;       float4 xo = *(const float4*)(xold + idx);
;       v.x = fmaf(coef, v.x, xo.x); v.y = fmaf(coef, v.y, xo.y); v.z = fmaf(coef, v.z, xo.z); v.w = fmaf(coef, v.w, xo.w);
;       *(float4*)(xnew + idx) = v;
;       *(bf16x4*)(xb + idx) = pack4(v.x, v.y, v.z, v.w);
;       float s = row16_sum(v.x * v.x + v.y * v.y + v.z * v.z + v.w * v.w);
;       if ((lane & 15) == 0) atomicAdd(ssqn + row, s);
;     });
.LBB0_1606:
	s_or_b64 exec, exec, s[2:3]
	v_or3_b32 v1, v12, s26, 12
	v_lshl_add_u32 v10, v1, 10, v13
	v_ashrrev_i32_e32 v11, 31, v10
	v_lshl_add_u64 v[14:15], v[10:11], 2, s[12:13]
	ds_read_b128 v[6:9], v0 offset:3264
	v_lshl_add_u64 v[10:11], v[10:11], 1, s[16:17]
	s_waitcnt vmcnt(13) lgkmcnt(0)
	v_mov_b32_e32 v2, v156
	v_mov_b32_e32 v3, v157
	v_mov_b32_e32 v4, v158
	v_mov_b32_e32 v5, v159
	v_pk_fma_f32 v[2:3], v[6:7], 0.5, v[2:3] op_sel_hi:[1,0,1]
	v_pk_fma_f32 v[4:5], v[8:9], 0.5, v[4:5] op_sel_hi:[1,0,1]
	global_store_dwordx4 v[14:15], v[2:5], off
	v_cvt_pk_bf16_f32 v6, v2, v3
	v_cvt_pk_bf16_f32 v7, v4, v5
	v_pk_mul_f32 v[2:3], v[2:3], v[2:3]
	v_pk_mul_f32 v[4:5], v[4:5], v[4:5]
	v_add_f32_e32 v2, v2, v3
	v_add_f32_e32 v2, v4, v2
	v_add_f32_e32 v2, v5, v2
	v_mov_b32_e32 v3, 0
	global_store_dwordx2 v[10:11], v[6:7], off
	v_add_f32_dpp v2, v2, v2 quad_perm:[1,0,3,2] row_mask:0xf bank_mask:0xf bound_ctrl:1
	s_nop 1
	v_add_f32_dpp v2, v2, v2 quad_perm:[2,3,0,1] row_mask:0xf bank_mask:0xf bound_ctrl:1
	s_nop 1
	v_add_f32_dpp v2, v2, v2 row_half_mirror row_mask:0xf bank_mask:0xf bound_ctrl:1
	s_nop 1
	v_mov_b32_dpp v3, v2 row_mirror row_mask:0xf bank_mask:0xf
	s_and_saveexec_b64 s[2:3], s[10:11]
	s_cbranch_execz .LBB0_1608
	v_add_f32_e32 v2, v2, v3
	v_lshlrev_b32_e32 v1, 2, v1
	global_atomic_add_f32 v1, v2, s[18:19]
.LBB0_1608:
	s_or_b64 exec, exec, s[2:3]
	v_or3_b32 v1, v12, s26, 16
	v_lshl_add_u32 v10, v1, 10, v13
	v_ashrrev_i32_e32 v11, 31, v10
	v_lshl_add_u64 v[14:15], v[10:11], 2, s[12:13]
	ds_read_b128 v[6:9], v0 offset:4352
	v_lshl_add_u64 v[10:11], v[10:11], 1, s[16:17]
	s_waitcnt vmcnt(15) lgkmcnt(0)
	v_mov_b32_e32 v2, v160
	v_mov_b32_e32 v3, v161
	v_mov_b32_e32 v4, v162
	v_mov_b32_e32 v5, v163
	v_pk_fma_f32 v[2:3], v[6:7], 0.5, v[2:3] op_sel_hi:[1,0,1]
	v_pk_fma_f32 v[4:5], v[8:9], 0.5, v[4:5] op_sel_hi:[1,0,1]
	global_store_dwordx4 v[14:15], v[2:5], off
	v_cvt_pk_bf16_f32 v6, v2, v3
	v_cvt_pk_bf16_f32 v7, v4, v5
	v_pk_mul_f32 v[2:3], v[2:3], v[2:3]
	v_pk_mul_f32 v[4:5], v[4:5], v[4:5]
	v_add_f32_e32 v2, v2, v3
	v_add_f32_e32 v2, v4, v2
	v_add_f32_e32 v2, v5, v2
	v_mov_b32_e32 v3, 0
	global_store_dwordx2 v[10:11], v[6:7], off
	v_add_f32_dpp v2, v2, v2 quad_perm:[1,0,3,2] row_mask:0xf bank_mask:0xf bound_ctrl:1
	s_nop 1
	v_add_f32_dpp v2, v2, v2 quad_perm:[2,3,0,1] row_mask:0xf bank_mask:0xf bound_ctrl:1
	s_nop 1
	v_add_f32_dpp v2, v2, v2 row_half_mirror row_mask:0xf bank_mask:0xf bound_ctrl:1
	s_nop 1
	v_mov_b32_dpp v3, v2 row_mirror row_mask:0xf bank_mask:0xf
	s_and_saveexec_b64 s[2:3], s[10:11]
	s_cbranch_execz .LBB0_1610
	v_add_f32_e32 v2, v2, v3
	v_lshlrev_b32_e32 v1, 2, v1
	global_atomic_add_f32 v1, v2, s[18:19]
.LBB0_1610:
	s_or_b64 exec, exec, s[2:3]
	v_or3_b32 v1, v12, s26, 20
	v_lshl_add_u32 v10, v1, 10, v13
	v_ashrrev_i32_e32 v11, 31, v10
	v_lshl_add_u64 v[14:15], v[10:11], 2, s[12:13]
	ds_read_b128 v[6:9], v0 offset:5440
	v_lshl_add_u64 v[10:11], v[10:11], 1, s[16:17]
	s_waitcnt vmcnt(17) lgkmcnt(0)
	v_mov_b32_e32 v2, v164
	v_mov_b32_e32 v3, v165
	v_mov_b32_e32 v4, v166
	v_mov_b32_e32 v5, v167
	v_pk_fma_f32 v[2:3], v[6:7], 0.5, v[2:3] op_sel_hi:[1,0,1]
	v_pk_fma_f32 v[4:5], v[8:9], 0.5, v[4:5] op_sel_hi:[1,0,1]
	global_store_dwordx4 v[14:15], v[2:5], off
	v_cvt_pk_bf16_f32 v6, v2, v3
	v_cvt_pk_bf16_f32 v7, v4, v5
	v_pk_mul_f32 v[2:3], v[2:3], v[2:3]
	v_pk_mul_f32 v[4:5], v[4:5], v[4:5]
	v_add_f32_e32 v2, v2, v3
	v_add_f32_e32 v2, v4, v2
	v_add_f32_e32 v2, v5, v2
	v_mov_b32_e32 v3, 0
	global_store_dwordx2 v[10:11], v[6:7], off
	v_add_f32_dpp v2, v2, v2 quad_perm:[1,0,3,2] row_mask:0xf bank_mask:0xf bound_ctrl:1
	s_nop 1
	v_add_f32_dpp v2, v2, v2 quad_perm:[2,3,0,1] row_mask:0xf bank_mask:0xf bound_ctrl:1
	s_nop 1
	v_add_f32_dpp v2, v2, v2 row_half_mirror row_mask:0xf bank_mask:0xf bound_ctrl:1
	s_nop 1
	v_mov_b32_dpp v3, v2 row_mirror row_mask:0xf bank_mask:0xf
	s_and_saveexec_b64 s[2:3], s[10:11]
	s_cbranch_execz .LBB0_1612
	v_add_f32_e32 v2, v2, v3
	v_lshlrev_b32_e32 v1, 2, v1
	global_atomic_add_f32 v1, v2, s[18:19]
.LBB0_1612:
	s_or_b64 exec, exec, s[2:3]
	v_or3_b32 v1, v12, s26, 24
	v_lshl_add_u32 v10, v1, 10, v13
	v_ashrrev_i32_e32 v11, 31, v10
	v_lshl_add_u64 v[14:15], v[10:11], 2, s[12:13]
	ds_read_b128 v[6:9], v0 offset:6528
	v_lshl_add_u64 v[10:11], v[10:11], 1, s[16:17]
	s_waitcnt vmcnt(19) lgkmcnt(0)
	v_mov_b32_e32 v2, v168
	v_mov_b32_e32 v3, v169
	v_mov_b32_e32 v4, v170
	v_mov_b32_e32 v5, v171
	v_pk_fma_f32 v[2:3], v[6:7], 0.5, v[2:3] op_sel_hi:[1,0,1]
	v_pk_fma_f32 v[4:5], v[8:9], 0.5, v[4:5] op_sel_hi:[1,0,1]
	global_store_dwordx4 v[14:15], v[2:5], off
	v_cvt_pk_bf16_f32 v6, v2, v3
	v_cvt_pk_bf16_f32 v7, v4, v5
	v_pk_mul_f32 v[2:3], v[2:3], v[2:3]
	v_pk_mul_f32 v[4:5], v[4:5], v[4:5]
	v_add_f32_e32 v2, v2, v3
	v_add_f32_e32 v2, v4, v2
	v_add_f32_e32 v2, v5, v2
	v_mov_b32_e32 v3, 0
	global_store_dwordx2 v[10:11], v[6:7], off
	v_add_f32_dpp v2, v2, v2 quad_perm:[1,0,3,2] row_mask:0xf bank_mask:0xf bound_ctrl:1
	s_nop 1
	v_add_f32_dpp v2, v2, v2 quad_perm:[2,3,0,1] row_mask:0xf bank_mask:0xf bound_ctrl:1
	s_nop 1
	v_add_f32_dpp v2, v2, v2 row_half_mirror row_mask:0xf bank_mask:0xf bound_ctrl:1
	s_nop 1
	v_mov_b32_dpp v3, v2 row_mirror row_mask:0xf bank_mask:0xf
	s_and_saveexec_b64 s[2:3], s[10:11]
	s_cbranch_execz .LBB0_1614
	v_add_f32_e32 v2, v2, v3
	v_lshlrev_b32_e32 v1, 2, v1
	global_atomic_add_f32 v1, v2, s[18:19]
.LBB0_1614:
	s_or_b64 exec, exec, s[2:3]
	v_or3_b32 v1, v12, s26, 28
	v_lshl_add_u32 v10, v1, 10, v13
	v_ashrrev_i32_e32 v11, 31, v10
	v_lshl_add_u64 v[12:13], v[10:11], 2, s[12:13]
	ds_read_b128 v[6:9], v0 offset:7616
	v_lshl_add_u64 v[10:11], v[10:11], 1, s[16:17]
	s_waitcnt vmcnt(21) lgkmcnt(0)
	v_mov_b32_e32 v2, v172
	v_mov_b32_e32 v3, v173
	v_mov_b32_e32 v4, v174
	v_mov_b32_e32 v5, v175
	v_pk_fma_f32 v[2:3], v[6:7], 0.5, v[2:3] op_sel_hi:[1,0,1]
	v_pk_fma_f32 v[4:5], v[8:9], 0.5, v[4:5] op_sel_hi:[1,0,1]
	global_store_dwordx4 v[12:13], v[2:5], off
	v_cvt_pk_bf16_f32 v6, v2, v3
	v_cvt_pk_bf16_f32 v7, v4, v5
	v_pk_mul_f32 v[2:3], v[2:3], v[2:3]
	v_pk_mul_f32 v[4:5], v[4:5], v[4:5]
	v_add_f32_e32 v0, v2, v3
	v_add_f32_e32 v0, v4, v0
	v_add_f32_e32 v0, v5, v0
	v_mov_b32_e32 v2, 0
	global_store_dwordx2 v[10:11], v[6:7], off
	v_add_f32_dpp v0, v0, v0 quad_perm:[1,0,3,2] row_mask:0xf bank_mask:0xf bound_ctrl:1
	s_nop 1
	v_add_f32_dpp v0, v0, v0 quad_perm:[2,3,0,1] row_mask:0xf bank_mask:0xf bound_ctrl:1
	s_nop 1
	v_add_f32_dpp v0, v0, v0 row_half_mirror row_mask:0xf bank_mask:0xf bound_ctrl:1
	s_nop 1
	v_mov_b32_dpp v2, v0 row_mirror row_mask:0xf bank_mask:0xf
	s_and_b64 exec, exec, s[10:11]
	s_cbranch_execz .LBB0_1595
	v_add_f32_e32 v0, v0, v2
	v_lshlrev_b32_e32 v1, 2, v1
	global_atomic_add_f32 v1, v0, s[18:19]
	s_branch .LBB0_1595

; template <class Epi>
; __device__ __forceinline__ void small_gemm(const u16* __restrict__ A, const u16* __restrict__ Bt, int K, int N, const Epi& epi) {
;     ...
;   for (int piece = blockIdx.x; piece < npieces; piece += gridDim.x) {
;     int row0 = (piece & 3) * 32, col0 = (piece >> 2) * 64;
;     f32x4 acc[2][4] = {};
;     int kper = K >> 3, k0 = wid * kper;
;     for (int kk = k0; kk < k0 + kper; kk += 32) {
;       bf16x8 a[2], b[4];
; #pragma unroll
;       for (int m = 0; m < 2; ++m) a[m] = *(const bf16x8*)(A + (size_t)(row0 + m * 16 + fr) * K + kk + fq * 8);
; #pragma unroll
;       for (int n = 0; n < 4; ++n) b[n] = *(const bf16x8*)(Bt + (size_t)(col0 + n * 16 + fr) * K + kk + fq * 8);
; #pragma unroll
;       for (int m = 0; m < 2; ++m)
; #pragma unroll
;         for (int n = 0; n < 4; ++n) acc[m][n] = __builtin_amdgcn_mfma_f32_16x16x32_bf16(a[m], b[n], acc[m][n], 0, 0, 0);
;     }
;     __syncthreads();
; #pragma unroll
;     for (int m = 0; m < 2; ++m)
; #pragma unroll
;       for (int n = 0; n < 4; ++n) red[(wid * 8 + m * 4 + n) * 64 + lane] = acc[m][n];
;     __syncthreads();
;     if (wid == 0) {
; #pragma unroll
;       for (int m = 0; m < 2; ++m)
; #pragma unroll
;         for (int n = 0; n < 4; ++n) {
;           f32x4 s = red[(m * 4 + n) * 64 + lane];
; #pragma unroll
;           for (int w = 1; w < 8; ++w) s += red[(w * 8 + m * 4 + n) * 64 + lane];
;           acc[m][n] = s;
;         }
.LBB0_1828:
	v_lshl_add_u64 v[58:59], v[48:49], 0, v[32:33]
	v_add_co_u32_e64 v76, s[12:13], s23, v58
	v_lshl_add_u64 v[70:71], v[44:45], 0, v[32:33]
	s_nop 0
	v_addc_co_u32_e64 v77, s[12:13], 0, v59, s[12:13]
	v_add_co_u32_e64 v80, s[12:13], s24, v58
	v_lshl_add_u64 v[72:73], v[42:43], 0, v[32:33]
	v_lshl_add_u64 v[74:75], v[40:41], 0, v[32:33]
	v_lshl_add_u64 v[78:79], v[46:47], 0, v[32:33]
	v_addc_co_u32_e64 v81, s[12:13], 0, v59, s[12:13]
	global_load_dwordx4 v[58:61], v[70:71], off
	global_load_dwordx4 v[62:65], v[76:77], off
	global_load_dwordx4 v[66:69], v[80:81], off
	v_add_u32_e32 v34, 32, v34
	global_load_dwordx4 v[70:73], v[72:73], off
	v_cmp_ge_i32_e64 s[12:13], v34, v52
	global_load_dwordx4 v[74:77], v[74:75], off
	v_lshl_add_u64 v[46:47], v[46:47], 0, 64
	global_load_dwordx4 v[78:81], v[78:79], off
	v_lshl_add_u64 v[40:41], v[40:41], 0, 64
	v_lshl_add_u64 v[42:43], v[42:43], 0, 64
	v_lshl_add_u64 v[44:45], v[44:45], 0, 64
	s_or_b64 s[0:1], s[12:13], s[0:1]
	v_lshl_add_u64 v[48:49], v[48:49], 0, 64
	s_waitcnt vmcnt(4)
	v_mfma_f32_16x16x32_bf16 v[28:31], v[62:65], v[58:61], v[28:31]
	s_waitcnt vmcnt(2)
	v_mfma_f32_16x16x32_bf16 v[24:27], v[62:65], v[70:73], v[24:27]
	s_waitcnt vmcnt(1)
	v_mfma_f32_16x16x32_bf16 v[20:23], v[62:65], v[74:77], v[20:23]
	s_waitcnt vmcnt(0)
	v_mfma_f32_16x16x32_bf16 v[16:19], v[62:65], v[78:81], v[16:19]
	v_mfma_f32_16x16x32_bf16 v[12:15], v[66:69], v[58:61], v[12:15]
	v_mfma_f32_16x16x32_bf16 v[8:11], v[66:69], v[70:73], v[8:11]
	v_mfma_f32_16x16x32_bf16 v[4:7], v[66:69], v[74:77], v[4:7]
	v_mfma_f32_16x16x32_bf16 v[0:3], v[66:69], v[78:81], v[0:3]
	s_andn2_b64 exec, exec, s[0:1]
	s_cbranch_execnz .LBB0_1828
	s_or_b64 exec, exec, s[0:1]
	s_barrier
	ds_write_b128 v57, v[28:31]
	ds_write_b128 v57, v[24:27] offset:1024
	ds_write_b128 v57, v[20:23] offset:2048
	ds_write_b128 v57, v[16:19] offset:3072
	ds_write_b128 v57, v[12:15] offset:4096
	ds_write_b128 v57, v[8:11] offset:5120
	ds_write_b128 v57, v[4:7] offset:6144
	ds_write_b128 v57, v[0:3] offset:7168
	s_waitcnt lgkmcnt(0)
	s_barrier
	s_and_saveexec_b64 s[0:1], vcc
	s_cbranch_execz .LBB0_1826
	ds_read_b128 v[0:3], v51
	ds_read_b128 v[4:7], v51 offset:8192
	ds_read_b128 v[8:11], v51 offset:16384
	ds_read_b128 v[12:15], v51 offset:1024
	ds_read_b128 v[16:19], v51 offset:9216
	s_andn2_b32 s2, s2, 63
	s_waitcnt lgkmcnt(3)
	v_pk_add_f32 v[20:21], v[2:3], v[6:7]
	v_pk_add_f32 v[22:23], v[0:1], v[4:5]
	ds_read_b128 v[0:3], v51 offset:24576
	ds_read_b128 v[4:7], v51 offset:17408
	s_waitcnt lgkmcnt(4)
	v_pk_add_f32 v[24:25], v[20:21], v[10:11]
	v_pk_add_f32 v[26:27], v[22:23], v[8:9]
	ds_read_b128 v[8:11], v51 offset:32768
	ds_read_b128 v[20:23], v51 offset:25600
	s_waitcnt lgkmcnt(3)
	v_pk_add_f32 v[28:29], v[24:25], v[2:3]
	v_pk_add_f32 v[30:31], v[26:27], v[0:1]
	ds_read_b128 v[0:3], v51 offset:40960
	ds_read_b128 v[24:27], v51 offset:33792
	s_waitcnt lgkmcnt(3)
	v_pk_add_f32 v[40:41], v[28:29], v[10:11]
	v_pk_add_f32 v[42:43], v[30:31], v[8:9]
	ds_read_b128 v[8:11], v51 offset:49152
	ds_read_b128 v[28:31], v51 offset:41984
	s_waitcnt lgkmcnt(3)
	v_pk_add_f32 v[2:3], v[40:41], v[2:3]
	v_pk_add_f32 v[0:1], v[42:43], v[0:1]
	ds_read_b128 v[40:43], v51 offset:57344
	ds_read_b128 v[44:47], v51 offset:50176
	v_pk_add_f32 v[14:15], v[14:15], v[18:19]
	s_waitcnt lgkmcnt(3)
	v_pk_add_f32 v[2:3], v[2:3], v[10:11]
	v_pk_add_f32 v[48:49], v[0:1], v[8:9]
	ds_read_b128 v[8:11], v51 offset:58368
	v_pk_add_f32 v[12:13], v[12:13], v[16:17]
	v_pk_add_f32 v[6:7], v[14:15], v[6:7]
	v_pk_add_f32 v[4:5], v[12:13], v[4:5]
	v_pk_add_f32 v[6:7], v[6:7], v[22:23]
	v_pk_add_f32 v[4:5], v[4:5], v[20:21]
	v_pk_add_f32 v[6:7], v[6:7], v[26:27]
	v_pk_add_f32 v[4:5], v[4:5], v[24:25]
	s_waitcnt lgkmcnt(3)
	v_pk_add_f32 v[6:7], v[6:7], v[30:31]
	v_pk_add_f32 v[4:5], v[4:5], v[28:29]
	s_waitcnt lgkmcnt(1)
	v_pk_add_f32 v[6:7], v[6:7], v[46:47]
	v_pk_add_f32 v[18:19], v[4:5], v[44:45]
	s_waitcnt lgkmcnt(0)
	v_pk_add_f32 v[4:5], v[6:7], v[10:11]
	ds_read_b128 v[10:13], v51 offset:2048
	ds_read_b128 v[14:17], v51 offset:10240
	v_pk_add_f32 v[6:7], v[18:19], v[8:9]
	ds_read_b128 v[18:21], v51 offset:18432
	ds_read_b128 v[22:25], v51 offset:3072
	ds_read_b128 v[26:29], v51 offset:11264
	v_pk_add_f32 v[0:1], v[2:3], v[42:43]
	v_pk_add_f32 v[2:3], v[48:49], v[40:41]
	s_waitcnt lgkmcnt(3)
	v_pk_add_f32 v[16:17], v[12:13], v[16:17]
	v_pk_add_f32 v[30:31], v[10:11], v[14:15]
	ds_read_b128 v[8:11], v51 offset:26624
	ds_read_b128 v[12:15], v51 offset:19456
	s_waitcnt lgkmcnt(4)
	v_pk_add_f32 v[20:21], v[16:17], v[20:21]
	v_pk_add_f32 v[30:31], v[30:31], v[18:19]
	ds_read_b128 v[16:19], v51 offset:34816
	ds_read_b128 v[40:43], v51 offset:27648
	s_waitcnt lgkmcnt(3)
	v_pk_add_f32 v[20:21], v[20:21], v[10:11]
	v_pk_add_f32 v[30:31], v[30:31], v[8:9]
	ds_read_b128 v[8:11], v51 offset:43008
	ds_read_b128 v[44:47], v51 offset:35840
	s_waitcnt lgkmcnt(3)
	v_pk_add_f32 v[20:21], v[20:21], v[18:19]
	v_pk_add_f32 v[30:31], v[30:31], v[16:17]
	ds_read_b128 v[16:19], v51 offset:51200
	ds_read_b128 v[58:61], v51 offset:44032
	ds_read_b128 v[62:65], v51 offset:59392
	ds_read_b128 v[66:69], v51 offset:52224
	s_waitcnt lgkmcnt(5)
	v_pk_add_f32 v[10:11], v[20:21], v[10:11]
	v_pk_add_f32 v[8:9], v[30:31], v[8:9]
	s_waitcnt lgkmcnt(3)
	v_pk_add_f32 v[10:11], v[10:11], v[18:19]
	v_pk_add_f32 v[20:21], v[8:9], v[16:17]
	s_waitcnt lgkmcnt(1)
; template <class Epi>
; __device__ __forceinline__ void small_gemm(const u16* __restrict__ A, const u16* __restrict__ Bt, int K, int N, const Epi& epi) {
;     ...
;     if (wid == 0) {
; #pragma unroll
;       for (int m = 0; m < 2; ++m)
; #pragma unroll
;         for (int n = 0; n < 4; ++n) {
;           f32x4 s = red[(m * 4 + n) * 64 + lane];
; #pragma unroll
;           for (int w = 1; w < 8; ++w) s += red[(w * 8 + m * 4 + n) * 64 + lane];
;           acc[m][n] = s;
;         }
	v_pk_add_f32 v[8:9], v[10:11], v[64:65]
	v_pk_add_f32 v[10:11], v[20:21], v[62:63]
	v_pk_add_f32 v[20:21], v[24:25], v[28:29]
	ds_read_b128 v[16:19], v51 offset:60416
	v_pk_add_f32 v[22:23], v[22:23], v[26:27]
	v_pk_add_f32 v[14:15], v[20:21], v[14:15]
	v_pk_add_f32 v[12:13], v[22:23], v[12:13]
	v_pk_add_f32 v[14:15], v[14:15], v[42:43]
	v_pk_add_f32 v[12:13], v[12:13], v[40:41]
	v_pk_add_f32 v[14:15], v[14:15], v[46:47]
	v_pk_add_f32 v[12:13], v[12:13], v[44:45]
	v_pk_add_f32 v[14:15], v[14:15], v[60:61]
	v_pk_add_f32 v[12:13], v[12:13], v[58:59]
	s_waitcnt lgkmcnt(1)
	v_pk_add_f32 v[14:15], v[14:15], v[68:69]
	v_pk_add_f32 v[22:23], v[12:13], v[66:67]
	s_waitcnt lgkmcnt(0)
	v_pk_add_f32 v[48:49], v[14:15], v[18:19]
	ds_read_b128 v[12:15], v51 offset:4096
	ds_read_b128 v[18:21], v51 offset:12288
	v_pk_add_f32 v[70:71], v[22:23], v[16:17]
	ds_read_b128 v[22:25], v51 offset:20480
	ds_read_b128 v[26:29], v51 offset:5120
	ds_read_b128 v[40:43], v51 offset:13312
	s_waitcnt lgkmcnt(3)
	v_pk_add_f32 v[20:21], v[14:15], v[20:21]
	v_pk_add_f32 v[30:31], v[12:13], v[18:19]
	ds_read_b128 v[12:15], v51 offset:28672
	ds_read_b128 v[16:19], v51 offset:21504
	s_waitcnt lgkmcnt(4)
	v_pk_add_f32 v[24:25], v[20:21], v[24:25]
	v_pk_add_f32 v[30:31], v[30:31], v[22:23]
	ds_read_b128 v[20:23], v51 offset:36864
	ds_read_b128 v[44:47], v51 offset:29696
	s_waitcnt lgkmcnt(3)
	v_pk_add_f32 v[24:25], v[24:25], v[14:15]
	v_pk_add_f32 v[30:31], v[30:31], v[12:13]
	ds_read_b128 v[12:15], v51 offset:45056
	ds_read_b128 v[58:61], v51 offset:37888
	s_waitcnt lgkmcnt(3)
	v_pk_add_f32 v[24:25], v[24:25], v[22:23]
	v_pk_add_f32 v[30:31], v[30:31], v[20:21]
	ds_read_b128 v[20:23], v51 offset:53248
	ds_read_b128 v[62:65], v51 offset:46080
	s_waitcnt lgkmcnt(3)
	v_pk_add_f32 v[24:25], v[24:25], v[14:15]
	v_pk_add_f32 v[30:31], v[30:31], v[12:13]
	ds_read_b128 v[12:15], v51 offset:61440
	ds_read_b128 v[66:69], v51 offset:54272
	s_waitcnt lgkmcnt(3)
	v_pk_add_f32 v[30:31], v[30:31], v[20:21]
	v_pk_add_f32 v[24:25], v[24:25], v[22:23]
	ds_read_b128 v[20:23], v51 offset:62464
	s_waitcnt lgkmcnt(2)
	v_pk_add_f32 v[74:75], v[30:31], v[12:13]
	v_pk_add_f32 v[12:13], v[28:29], v[42:43]
	v_pk_add_f32 v[72:73], v[24:25], v[14:15]
	v_pk_add_f32 v[14:15], v[26:27], v[40:41]
	v_pk_add_f32 v[12:13], v[12:13], v[18:19]
	v_pk_add_f32 v[14:15], v[14:15], v[16:17]
	v_pk_add_f32 v[12:13], v[12:13], v[46:47]
	v_pk_add_f32 v[14:15], v[14:15], v[44:45]
	v_pk_add_f32 v[12:13], v[12:13], v[60:61]
	v_pk_add_f32 v[14:15], v[14:15], v[58:59]
	v_pk_add_f32 v[12:13], v[12:13], v[64:65]
	v_pk_add_f32 v[14:15], v[14:15], v[62:63]
	s_waitcnt lgkmcnt(1)
	v_pk_add_f32 v[12:13], v[12:13], v[68:69]
	v_pk_add_f32 v[24:25], v[14:15], v[66:67]
	s_waitcnt lgkmcnt(0)
	v_pk_add_f32 v[66:67], v[12:13], v[22:23]
	ds_read_b128 v[12:15], v51 offset:6144
	ds_read_b128 v[16:19], v51 offset:14336
	v_pk_add_f32 v[68:69], v[24:25], v[20:21]
	ds_read_b128 v[20:23], v51 offset:22528
	ds_read_b128 v[24:27], v51 offset:7168
	ds_read_b128 v[28:31], v51 offset:15360
	s_waitcnt lgkmcnt(3)
	v_pk_add_f32 v[40:41], v[14:15], v[18:19]
	v_pk_add_f32 v[42:43], v[12:13], v[16:17]
	ds_read_b128 v[12:15], v51 offset:30720
	ds_read_b128 v[16:19], v51 offset:23552
	s_waitcnt lgkmcnt(4)
	v_pk_add_f32 v[44:45], v[40:41], v[22:23]
	v_pk_add_f32 v[46:47], v[42:43], v[20:21]
	ds_read_b128 v[20:23], v51 offset:38912
	ds_read_b128 v[40:43], v51 offset:31744
	s_waitcnt lgkmcnt(3)
	v_pk_add_f32 v[58:59], v[44:45], v[14:15]
	v_pk_add_f32 v[60:61], v[46:47], v[12:13]
	ds_read_b128 v[12:15], v51 offset:47104
	ds_read_b128 v[44:47], v51 offset:39936
	s_waitcnt lgkmcnt(3)
	v_pk_add_f32 v[62:63], v[58:59], v[22:23]
	v_pk_add_f32 v[64:65], v[60:61], v[20:21]
	ds_read_b128 v[20:23], v51 offset:55296
	ds_read_b128 v[58:61], v51 offset:48128
	s_waitcnt lgkmcnt(3)
	v_pk_add_f32 v[76:77], v[62:63], v[14:15]
	v_pk_add_f32 v[78:79], v[64:65], v[12:13]
	ds_read_b128 v[12:15], v51 offset:63488
	ds_read_b128 v[62:65], v51 offset:56320
	s_waitcnt lgkmcnt(3)
	v_pk_add_f32 v[78:79], v[78:79], v[20:21]
	v_pk_add_f32 v[76:77], v[76:77], v[22:23]
	ds_read_b128 v[20:23], v51 offset:64512
	s_waitcnt lgkmcnt(2)
	v_pk_add_f32 v[78:79], v[78:79], v[12:13]
	v_pk_add_f32 v[12:13], v[26:27], v[30:31]
	v_pk_add_f32 v[76:77], v[76:77], v[14:15]
	v_pk_add_f32 v[12:13], v[12:13], v[18:19]
	v_pk_add_f32 v[14:15], v[24:25], v[28:29]
	v_pk_add_f32 v[12:13], v[12:13], v[42:43]
	v_pk_add_f32 v[14:15], v[14:15], v[16:17]
	v_pk_add_f32 v[12:13], v[12:13], v[46:47]
	v_pk_add_f32 v[14:15], v[14:15], v[40:41]
	v_pk_add_f32 v[12:13], v[12:13], v[60:61]
	v_pk_add_f32 v[14:15], v[14:15], v[44:45]
	s_waitcnt lgkmcnt(1)
	v_pk_add_f32 v[12:13], v[12:13], v[64:65]
	v_pk_add_f32 v[14:15], v[14:15], v[58:59]
	s_waitcnt lgkmcnt(0)
;   __device__ __forceinline__ void tile(const float* reg, int row0, int col0, int lane) const {
;     rows4(reg, lane, [&](int it, int rr, int c4, float4 v) {
;       int row = row0 + rr, idx = row * 1024 + col0 + c4;
;       float4 xo = *(const float4*)(xold + idx);
;       v.x = fmaf(coef, v.x, xo.x); v.y = fmaf(coef, v.y, xo.y); v.z = fmaf(coef, v.z, xo.z); v.w = fmaf(coef, v.w, xo.w);
;       *(float4*)(xnew + idx) = v;
;       *(bf16x4*)(xb + idx) = pack4(v.x, v.y, v.z, v.w);
;       float s = row16_sum(v.x * v.x + v.y * v.y + v.z * v.z + v.w * v.w);
;       if ((lane & 15) == 0) atomicAdd(ssqn + row, s);
;     });
; template <int MF, class Epi>
; __device__ __forceinline__ void staged_epilogue(f32x4 (&acc)[MF][4], int row0, int col0, const Epi& epi) {
;     ...
; #pragma unroll
;   for (int mp = 0; mp < MF / 2; ++mp) {
;     __builtin_amdgcn_sched_barrier(0);
; #pragma unroll
;     for (int mm = 0; mm < 2; ++mm)
; #pragma unroll
;       for (int n = 0; n < 4; ++n)
; #pragma unroll
;         for (int j = 0; j < 4; ++j) reg[(mm * 16 + fq * 4 + j) * 68 + n * 16 + fr] = acc[mp * 2 + mm][n][j];
;     __builtin_amdgcn_fence(__ATOMIC_ACQ_REL, "wavefront");
;     epi.tile(reg, row0 + mp * 32, col0, lane);
	v_pk_add_f32 v[16:17], v[12:13], v[22:23]
	v_mov_b32_e32 v13, v204
	v_mov_b32_e32 v12, v204
	v_pk_add_f32 v[14:15], v[14:15], v[62:63]
	v_lshrrev_b32_e32 v12, 6, v12
	v_mul_lo_u32 v12, v12, s25
	v_pk_add_f32 v[18:19], v[14:15], v[20:21]
	v_add_u32_e32 v14, 0x10000, v12
	v_lshrrev_b32_e32 v12, 2, v13
	v_and_b32_e32 v21, 15, v13
	v_and_b32_e32 v22, 12, v12
	v_bfe_u32 v12, v13, 4, 2
	v_lshlrev_b32_e32 v13, 2, v13
	v_and_b32_e32 v13, 60, v13
	v_lshl_or_b32 v23, v21, 2, v14
	v_lshl_or_b32 v14, v13, 2, v14
	v_or_b32_e32 v15, s28, v12
	v_or_b32_e32 v13, s2, v13
	v_cmp_eq_u32_e64 s[12:13], 0, v21
	v_mad_u32_u24 v24, v12, s26, v14
	v_lshl_add_u32 v20, v15, 10, v13
	v_mad_u32_u24 v21, v22, s26, v23
	ds_write2_b32 v21, v2, v6 offset1:16
	ds_write2_b32 v21, v3, v7 offset0:68 offset1:84
	ds_write2_b32 v21, v0, v4 offset0:136 offset1:152
	ds_write2_b32 v21, v1, v5 offset0:204 offset1:220
	ds_write2_b32 v21, v10, v70 offset0:32 offset1:48
	ds_write2_b32 v21, v11, v71 offset0:100 offset1:116
	ds_write2_b32 v21, v8, v48 offset0:168 offset1:184
	ds_write2_b32 v21, v9, v49 offset0:236 offset1:252
	v_add_u32_e32 v0, 0x1000, v21
	v_add_u32_e32 v1, 0x1400, v21
	ds_write2_b32 v0, v74, v68 offset0:64 offset1:80
	ds_write2_b32 v0, v75, v69 offset0:132 offset1:148
	ds_write2_b32 v0, v72, v66 offset0:200 offset1:216
	ds_write2_b32 v1, v73, v67 offset0:12 offset1:28
	ds_write2_b32 v0, v78, v18 offset0:96 offset1:112
	ds_write2_b32 v0, v79, v19 offset0:164 offset1:180
	ds_write2_b32 v0, v76, v16 offset0:232 offset1:248
	ds_write2_b32 v1, v77, v17 offset0:44 offset1:60
	v_mov_b32_e32 v178, v20
	v_ashrrev_i32_e32 v179, 31, v178
	v_lshl_add_u64 v[176:177], v[178:179], 2, s[16:17]
	global_load_dwordx4 v[144:147], v[176:177], off
	v_or3_b32 v184, v12, s28, 4
	v_lshl_add_u32 v176, v184, 10, v13
	v_ashrrev_i32_e32 v177, 31, v176
	v_lshl_add_u64 v[178:179], v[176:177], 2, s[16:17]
	global_load_dwordx4 v[148:151], v[178:179], off
	v_or3_b32 v184, v12, s28, 8
	v_lshl_add_u32 v176, v184, 10, v13
	v_ashrrev_i32_e32 v177, 31, v176
	v_lshl_add_u64 v[178:179], v[176:177], 2, s[16:17]
	global_load_dwordx4 v[152:155], v[178:179], off
	v_or3_b32 v184, v12, s28, 12
	v_lshl_add_u32 v176, v184, 10, v13
	v_ashrrev_i32_e32 v177, 31, v176
	v_lshl_add_u64 v[178:179], v[176:177], 2, s[16:17]
	global_load_dwordx4 v[156:159], v[178:179], off
	v_or3_b32 v184, v12, s28, 16
	v_lshl_add_u32 v176, v184, 10, v13
	v_ashrrev_i32_e32 v177, 31, v176
	v_lshl_add_u64 v[178:179], v[176:177], 2, s[16:17]
	global_load_dwordx4 v[160:163], v[178:179], off
	v_or3_b32 v184, v12, s28, 20
	v_lshl_add_u32 v176, v184, 10, v13
	v_ashrrev_i32_e32 v177, 31, v176
	v_lshl_add_u64 v[178:179], v[176:177], 2, s[16:17]
	global_load_dwordx4 v[164:167], v[178:179], off
	v_or3_b32 v184, v12, s28, 24
	v_lshl_add_u32 v176, v184, 10, v13
	v_ashrrev_i32_e32 v177, 31, v176
	v_lshl_add_u64 v[178:179], v[176:177], 2, s[16:17]
	global_load_dwordx4 v[168:171], v[178:179], off
	v_or3_b32 v184, v12, s28, 28
	v_lshl_add_u32 v176, v184, 10, v13
	v_ashrrev_i32_e32 v177, 31, v176
	v_lshl_add_u64 v[178:179], v[176:177], 2, s[16:17]
	global_load_dwordx4 v[172:175], v[178:179], off
	v_ashrrev_i32_e32 v21, 31, v20
	v_lshl_add_u64 v[8:9], v[20:21], 2, s[16:17]
	ds_read_b128 v[4:7], v24
	v_lshl_add_u64 v[10:11], v[20:21], 1, s[18:19]
	s_waitcnt vmcnt(7) lgkmcnt(0)
	v_mov_b32_e32 v0, v144
	v_mov_b32_e32 v1, v145
	v_mov_b32_e32 v2, v146
	v_mov_b32_e32 v3, v147
	v_pk_fma_f32 v[0:1], v[4:5], 0.5, v[0:1] op_sel_hi:[1,0,1]
	v_pk_fma_f32 v[2:3], v[6:7], 0.5, v[2:3] op_sel_hi:[1,0,1]
	global_store_dwordx4 v[8:9], v[0:3], off
	v_cvt_pk_bf16_f32 v4, v0, v1
	v_cvt_pk_bf16_f32 v5, v2, v3
	v_pk_mul_f32 v[0:1], v[0:1], v[0:1]
	v_pk_mul_f32 v[2:3], v[2:3], v[2:3]
	v_add_f32_e32 v0, v0, v1
	v_add_f32_e32 v0, v2, v0
	v_add_f32_e32 v0, v3, v0
	v_mov_b32_e32 v1, 0
	global_store_dwordx2 v[10:11], v[4:5], off
	v_add_f32_dpp v0, v0, v0 quad_perm:[1,0,3,2] row_mask:0xf bank_mask:0xf bound_ctrl:1
	s_nop 1
	v_add_f32_dpp v0, v0, v0 quad_perm:[2,3,0,1] row_mask:0xf bank_mask:0xf bound_ctrl:1
	s_nop 1
	v_add_f32_dpp v0, v0, v0 row_half_mirror row_mask:0xf bank_mask:0xf bound_ctrl:1
	s_nop 1
	v_mov_b32_dpp v1, v0 row_mirror row_mask:0xf bank_mask:0xf
	s_and_saveexec_b64 s[2:3], s[12:13]
	s_cbranch_execz .LBB0_1832
	v_add_f32_e32 v0, v0, v1
	v_lshlrev_b32_e32 v1, 2, v15
	global_atomic_add_f32 v1, v0, s[20:21]
.LBB0_1832:
	s_or_b64 exec, exec, s[2:3]
	v_or3_b32 v1, v12, s28, 4
	v_lshl_add_u32 v10, v1, 10, v13
	v_ashrrev_i32_e32 v11, 31, v10
	v_lshl_add_u64 v[16:17], v[10:11], 2, s[16:17]
	v_mul_u32_u24_e32 v0, 0x110, v12
	v_add_u32_e32 v0, v14, v0
	ds_read_b128 v[6:9], v0 offset:1088
	v_lshl_add_u64 v[10:11], v[10:11], 1, s[18:19]
	s_waitcnt vmcnt(9) lgkmcnt(0)
	v_mov_b32_e32 v2, v148
	v_mov_b32_e32 v3, v149
	v_mov_b32_e32 v4, v150
	v_mov_b32_e32 v5, v151
	v_pk_fma_f32 v[2:3], v[6:7], 0.5, v[2:3] op_sel_hi:[1,0,1]
	v_pk_fma_f32 v[4:5], v[8:9], 0.5, v[4:5] op_sel_hi:[1,0,1]
	global_store_dwordx4 v[16:17], v[2:5], off
	v_cvt_pk_bf16_f32 v6, v2, v3
	v_cvt_pk_bf16_f32 v7, v4, v5
	v_pk_mul_f32 v[2:3], v[2:3], v[2:3]
	v_pk_mul_f32 v[4:5], v[4:5], v[4:5]
	v_add_f32_e32 v2, v2, v3
	v_add_f32_e32 v2, v4, v2
	v_add_f32_e32 v2, v5, v2
	v_mov_b32_e32 v3, 0
	global_store_dwordx2 v[10:11], v[6:7], off
	v_add_f32_dpp v2, v2, v2 quad_perm:[1,0,3,2] row_mask:0xf bank_mask:0xf bound_ctrl:1
	s_nop 1
	v_add_f32_dpp v2, v2, v2 quad_perm:[2,3,0,1] row_mask:0xf bank_mask:0xf bound_ctrl:1
	s_nop 1
	v_add_f32_dpp v2, v2, v2 row_half_mirror row_mask:0xf bank_mask:0xf bound_ctrl:1
	s_nop 1
	v_mov_b32_dpp v3, v2 row_mirror row_mask:0xf bank_mask:0xf
	s_and_saveexec_b64 s[2:3], s[12:13]
	s_cbranch_execz .LBB0_1834
	v_add_f32_e32 v2, v2, v3
	v_lshlrev_b32_e32 v1, 2, v1
	global_atomic_add_f32 v1, v2, s[20:21]
;   __device__ __forceinline__ void tile(const float* reg, int row0, int col0, int lane) const {
;     rows4(reg, lane, [&](int it, int rr, int c4, float4 v) {
;       int row = row0 + rr, idx = row * 1024 + col0 + c4;
;       float4 xo = *(const float4*)(xold + idx);
;       v.x = fmaf(coef, v.x, xo.x); v.y = fmaf(coef, v.y, xo.y); v.z = fmaf(coef, v.z, xo.z); v.w = fmaf(coef, v.w, xo.w);
;       *(float4*)(xnew + idx) = v;
;       *(bf16x4*)(xb + idx) = pack4(v.x, v.y, v.z, v.w);
;       float s = row16_sum(v.x * v.x + v.y * v.y + v.z * v.z + v.w * v.w);
;       if ((lane & 15) == 0) atomicAdd(ssqn + row, s);
;     });
.LBB0_1834:
	s_or_b64 exec, exec, s[2:3]
	v_or3_b32 v1, v12, s28, 8
	v_lshl_add_u32 v10, v1, 10, v13
	v_ashrrev_i32_e32 v11, 31, v10
	v_lshl_add_u64 v[14:15], v[10:11], 2, s[16:17]
	ds_read_b128 v[6:9], v0 offset:2176
	v_lshl_add_u64 v[10:11], v[10:11], 1, s[18:19]
	s_waitcnt vmcnt(11) lgkmcnt(0)
	v_mov_b32_e32 v2, v152
	v_mov_b32_e32 v3, v153
	v_mov_b32_e32 v4, v154
	v_mov_b32_e32 v5, v155
	v_pk_fma_f32 v[2:3], v[6:7], 0.5, v[2:3] op_sel_hi:[1,0,1]
	v_pk_fma_f32 v[4:5], v[8:9], 0.5, v[4:5] op_sel_hi:[1,0,1]
	global_store_dwordx4 v[14:15], v[2:5], off
	v_cvt_pk_bf16_f32 v6, v2, v3
	v_cvt_pk_bf16_f32 v7, v4, v5
	v_pk_mul_f32 v[2:3], v[2:3], v[2:3]
	v_pk_mul_f32 v[4:5], v[4:5], v[4:5]
	v_add_f32_e32 v2, v2, v3
	v_add_f32_e32 v2, v4, v2
	v_add_f32_e32 v2, v5, v2
	v_mov_b32_e32 v3, 0
	global_store_dwordx2 v[10:11], v[6:7], off
	v_add_f32_dpp v2, v2, v2 quad_perm:[1,0,3,2] row_mask:0xf bank_mask:0xf bound_ctrl:1
	s_nop 1
	v_add_f32_dpp v2, v2, v2 quad_perm:[2,3,0,1] row_mask:0xf bank_mask:0xf bound_ctrl:1
	s_nop 1
	v_add_f32_dpp v2, v2, v2 row_half_mirror row_mask:0xf bank_mask:0xf bound_ctrl:1
	s_nop 1
	v_mov_b32_dpp v3, v2 row_mirror row_mask:0xf bank_mask:0xf
	s_and_saveexec_b64 s[2:3], s[12:13]
	s_cbranch_execz .LBB0_1836
	v_add_f32_e32 v2, v2, v3
	v_lshlrev_b32_e32 v1, 2, v1
	global_atomic_add_f32 v1, v2, s[20:21]
.LBB0_1836:
	s_or_b64 exec, exec, s[2:3]
	v_or3_b32 v1, v12, s28, 12
	v_lshl_add_u32 v10, v1, 10, v13
	v_ashrrev_i32_e32 v11, 31, v10
	v_lshl_add_u64 v[14:15], v[10:11], 2, s[16:17]
	ds_read_b128 v[6:9], v0 offset:3264
	v_lshl_add_u64 v[10:11], v[10:11], 1, s[18:19]
	s_waitcnt vmcnt(13) lgkmcnt(0)
	v_mov_b32_e32 v2, v156
	v_mov_b32_e32 v3, v157
	v_mov_b32_e32 v4, v158
	v_mov_b32_e32 v5, v159
	v_pk_fma_f32 v[2:3], v[6:7], 0.5, v[2:3] op_sel_hi:[1,0,1]
	v_pk_fma_f32 v[4:5], v[8:9], 0.5, v[4:5] op_sel_hi:[1,0,1]
	global_store_dwordx4 v[14:15], v[2:5], off
	v_cvt_pk_bf16_f32 v6, v2, v3
	v_cvt_pk_bf16_f32 v7, v4, v5
	v_pk_mul_f32 v[2:3], v[2:3], v[2:3]
	v_pk_mul_f32 v[4:5], v[4:5], v[4:5]
	v_add_f32_e32 v2, v2, v3
	v_add_f32_e32 v2, v4, v2
	v_add_f32_e32 v2, v5, v2
	v_mov_b32_e32 v3, 0
	global_store_dwordx2 v[10:11], v[6:7], off
	v_add_f32_dpp v2, v2, v2 quad_perm:[1,0,3,2] row_mask:0xf bank_mask:0xf bound_ctrl:1
	s_nop 1
	v_add_f32_dpp v2, v2, v2 quad_perm:[2,3,0,1] row_mask:0xf bank_mask:0xf bound_ctrl:1
	s_nop 1
	v_add_f32_dpp v2, v2, v2 row_half_mirror row_mask:0xf bank_mask:0xf bound_ctrl:1
	s_nop 1
	v_mov_b32_dpp v3, v2 row_mirror row_mask:0xf bank_mask:0xf
	s_and_saveexec_b64 s[2:3], s[12:13]
	s_cbranch_execz .LBB0_1838
	v_add_f32_e32 v2, v2, v3
	v_lshlrev_b32_e32 v1, 2, v1
	global_atomic_add_f32 v1, v2, s[20:21]
.LBB0_1838:
	s_or_b64 exec, exec, s[2:3]
	v_or3_b32 v1, v12, s28, 16
	v_lshl_add_u32 v10, v1, 10, v13
	v_ashrrev_i32_e32 v11, 31, v10
	v_lshl_add_u64 v[14:15], v[10:11], 2, s[16:17]
	ds_read_b128 v[6:9], v0 offset:4352
	v_lshl_add_u64 v[10:11], v[10:11], 1, s[18:19]
	s_waitcnt vmcnt(15) lgkmcnt(0)
	v_mov_b32_e32 v2, v160
	v_mov_b32_e32 v3, v161
	v_mov_b32_e32 v4, v162
	v_mov_b32_e32 v5, v163
	v_pk_fma_f32 v[2:3], v[6:7], 0.5, v[2:3] op_sel_hi:[1,0,1]
	v_pk_fma_f32 v[4:5], v[8:9], 0.5, v[4:5] op_sel_hi:[1,0,1]
	global_store_dwordx4 v[14:15], v[2:5], off
	v_cvt_pk_bf16_f32 v6, v2, v3
	v_cvt_pk_bf16_f32 v7, v4, v5
	v_pk_mul_f32 v[2:3], v[2:3], v[2:3]
	v_pk_mul_f32 v[4:5], v[4:5], v[4:5]
	v_add_f32_e32 v2, v2, v3
	v_add_f32_e32 v2, v4, v2
	v_add_f32_e32 v2, v5, v2
	v_mov_b32_e32 v3, 0
	global_store_dwordx2 v[10:11], v[6:7], off
	v_add_f32_dpp v2, v2, v2 quad_perm:[1,0,3,2] row_mask:0xf bank_mask:0xf bound_ctrl:1
	s_nop 1
	v_add_f32_dpp v2, v2, v2 quad_perm:[2,3,0,1] row_mask:0xf bank_mask:0xf bound_ctrl:1
	s_nop 1
	v_add_f32_dpp v2, v2, v2 row_half_mirror row_mask:0xf bank_mask:0xf bound_ctrl:1
	s_nop 1
	v_mov_b32_dpp v3, v2 row_mirror row_mask:0xf bank_mask:0xf
	s_and_saveexec_b64 s[2:3], s[12:13]
	s_cbranch_execz .LBB0_1840
	v_add_f32_e32 v2, v2, v3
	v_lshlrev_b32_e32 v1, 2, v1
	global_atomic_add_f32 v1, v2, s[20:21]
;   __device__ __forceinline__ void tile(const float* reg, int row0, int col0, int lane) const {
;     rows4(reg, lane, [&](int it, int rr, int c4, float4 v) {
;       int row = row0 + rr, idx = row * 1024 + col0 + c4;
;       float4 xo = *(const float4*)(xold + idx);
;       v.x = fmaf(coef, v.x, xo.x); v.y = fmaf(coef, v.y, xo.y); v.z = fmaf(coef, v.z, xo.z); v.w = fmaf(coef, v.w, xo.w);
;       *(float4*)(xnew + idx) = v;
;       *(bf16x4*)(xb + idx) = pack4(v.x, v.y, v.z, v.w);
;       float s = row16_sum(v.x * v.x + v.y * v.y + v.z * v.z + v.w * v.w);
;       if ((lane & 15) == 0) atomicAdd(ssqn + row, s);
;     });
.LBB0_1840:
	s_or_b64 exec, exec, s[2:3]
	v_or3_b32 v1, v12, s28, 20
	v_lshl_add_u32 v10, v1, 10, v13
	v_ashrrev_i32_e32 v11, 31, v10
	v_lshl_add_u64 v[14:15], v[10:11], 2, s[16:17]
	ds_read_b128 v[6:9], v0 offset:5440
	v_lshl_add_u64 v[10:11], v[10:11], 1, s[18:19]
	s_waitcnt vmcnt(17) lgkmcnt(0)
	v_mov_b32_e32 v2, v164
	v_mov_b32_e32 v3, v165
	v_mov_b32_e32 v4, v166
	v_mov_b32_e32 v5, v167
	v_pk_fma_f32 v[2:3], v[6:7], 0.5, v[2:3] op_sel_hi:[1,0,1]
	v_pk_fma_f32 v[4:5], v[8:9], 0.5, v[4:5] op_sel_hi:[1,0,1]
	global_store_dwordx4 v[14:15], v[2:5], off
	v_cvt_pk_bf16_f32 v6, v2, v3
	v_cvt_pk_bf16_f32 v7, v4, v5
	v_pk_mul_f32 v[2:3], v[2:3], v[2:3]
	v_pk_mul_f32 v[4:5], v[4:5], v[4:5]
	v_add_f32_e32 v2, v2, v3
	v_add_f32_e32 v2, v4, v2
	v_add_f32_e32 v2, v5, v2
	v_mov_b32_e32 v3, 0
	global_store_dwordx2 v[10:11], v[6:7], off
	v_add_f32_dpp v2, v2, v2 quad_perm:[1,0,3,2] row_mask:0xf bank_mask:0xf bound_ctrl:1
	s_nop 1
	v_add_f32_dpp v2, v2, v2 quad_perm:[2,3,0,1] row_mask:0xf bank_mask:0xf bound_ctrl:1
	s_nop 1
	v_add_f32_dpp v2, v2, v2 row_half_mirror row_mask:0xf bank_mask:0xf bound_ctrl:1
	s_nop 1
	v_mov_b32_dpp v3, v2 row_mirror row_mask:0xf bank_mask:0xf
	s_and_saveexec_b64 s[2:3], s[12:13]
	s_cbranch_execz .LBB0_1842
	v_add_f32_e32 v2, v2, v3
	v_lshlrev_b32_e32 v1, 2, v1
	global_atomic_add_f32 v1, v2, s[20:21]
.LBB0_1842:
	s_or_b64 exec, exec, s[2:3]
	v_or3_b32 v1, v12, s28, 24
	v_lshl_add_u32 v10, v1, 10, v13
	v_ashrrev_i32_e32 v11, 31, v10
	v_lshl_add_u64 v[14:15], v[10:11], 2, s[16:17]
	ds_read_b128 v[6:9], v0 offset:6528
	v_lshl_add_u64 v[10:11], v[10:11], 1, s[18:19]
	s_waitcnt vmcnt(19) lgkmcnt(0)
	v_mov_b32_e32 v2, v168
	v_mov_b32_e32 v3, v169
	v_mov_b32_e32 v4, v170
	v_mov_b32_e32 v5, v171
	v_pk_fma_f32 v[2:3], v[6:7], 0.5, v[2:3] op_sel_hi:[1,0,1]
	v_pk_fma_f32 v[4:5], v[8:9], 0.5, v[4:5] op_sel_hi:[1,0,1]
	global_store_dwordx4 v[14:15], v[2:5], off
	v_cvt_pk_bf16_f32 v6, v2, v3
	v_cvt_pk_bf16_f32 v7, v4, v5
	v_pk_mul_f32 v[2:3], v[2:3], v[2:3]
	v_pk_mul_f32 v[4:5], v[4:5], v[4:5]
	v_add_f32_e32 v2, v2, v3
	v_add_f32_e32 v2, v4, v2
	v_add_f32_e32 v2, v5, v2
	v_mov_b32_e32 v3, 0
	global_store_dwordx2 v[10:11], v[6:7], off
	v_add_f32_dpp v2, v2, v2 quad_perm:[1,0,3,2] row_mask:0xf bank_mask:0xf bound_ctrl:1
	s_nop 1
	v_add_f32_dpp v2, v2, v2 quad_perm:[2,3,0,1] row_mask:0xf bank_mask:0xf bound_ctrl:1
	s_nop 1
	v_add_f32_dpp v2, v2, v2 row_half_mirror row_mask:0xf bank_mask:0xf bound_ctrl:1
	s_nop 1
	v_mov_b32_dpp v3, v2 row_mirror row_mask:0xf bank_mask:0xf
	s_and_saveexec_b64 s[2:3], s[12:13]
	s_cbranch_execz .LBB0_1844
	v_add_f32_e32 v2, v2, v3
	v_lshlrev_b32_e32 v1, 2, v1
	global_atomic_add_f32 v1, v2, s[20:21]
.LBB0_1844:
	s_or_b64 exec, exec, s[2:3]
	v_or3_b32 v1, v12, s28, 28
	v_lshl_add_u32 v10, v1, 10, v13
	v_ashrrev_i32_e32 v11, 31, v10
	v_lshl_add_u64 v[12:13], v[10:11], 2, s[16:17]
	ds_read_b128 v[6:9], v0 offset:7616
	v_lshl_add_u64 v[10:11], v[10:11], 1, s[18:19]
	s_waitcnt vmcnt(21) lgkmcnt(0)
	v_mov_b32_e32 v2, v172
	v_mov_b32_e32 v3, v173
	v_mov_b32_e32 v4, v174
	v_mov_b32_e32 v5, v175
	v_pk_fma_f32 v[2:3], v[6:7], 0.5, v[2:3] op_sel_hi:[1,0,1]
	v_pk_fma_f32 v[4:5], v[8:9], 0.5, v[4:5] op_sel_hi:[1,0,1]
	global_store_dwordx4 v[12:13], v[2:5], off
	v_cvt_pk_bf16_f32 v6, v2, v3
	v_cvt_pk_bf16_f32 v7, v4, v5
	v_pk_mul_f32 v[2:3], v[2:3], v[2:3]
	v_pk_mul_f32 v[4:5], v[4:5], v[4:5]
	v_add_f32_e32 v0, v2, v3
	v_add_f32_e32 v0, v4, v0
	v_add_f32_e32 v0, v5, v0
	v_mov_b32_e32 v2, 0
	global_store_dwordx2 v[10:11], v[6:7], off
	v_add_f32_dpp v0, v0, v0 quad_perm:[1,0,3,2] row_mask:0xf bank_mask:0xf bound_ctrl:1
	s_nop 1
	v_add_f32_dpp v0, v0, v0 quad_perm:[2,3,0,1] row_mask:0xf bank_mask:0xf bound_ctrl:1
	s_nop 1
	v_add_f32_dpp v0, v0, v0 row_half_mirror row_mask:0xf bank_mask:0xf bound_ctrl:1
	s_nop 1
	v_mov_b32_dpp v2, v0 row_mirror row_mask:0xf bank_mask:0xf
	s_and_b64 exec, exec, s[12:13]
	s_cbranch_execz .LBB0_1825
	v_add_f32_e32 v0, v0, v2
	v_lshlrev_b32_e32 v1, 2, v1
	global_atomic_add_f32 v1, v0, s[20:21]
	s_branch .LBB0_1825

; template <class Epi>
; __device__ __forceinline__ void small_gemm(const u16* __restrict__ A, const u16* __restrict__ Bt, int K, int N, const Epi& epi) {
;     ...
;   for (int piece = blockIdx.x; piece < npieces; piece += gridDim.x) {
;     int row0 = (piece & 3) * 32, col0 = (piece >> 2) * 64;
;     f32x4 acc[2][4] = {};
;     int kper = K >> 3, k0 = wid * kper;
;     for (int kk = k0; kk < k0 + kper; kk += 32) {
;       bf16x8 a[2], b[4];
; #pragma unroll
;       for (int m = 0; m < 2; ++m) a[m] = *(const bf16x8*)(A + (size_t)(row0 + m * 16 + fr) * K + kk + fq * 8);
; #pragma unroll
;       for (int n = 0; n < 4; ++n) b[n] = *(const bf16x8*)(Bt + (size_t)(col0 + n * 16 + fr) * K + kk + fq * 8);
; #pragma unroll
;       for (int m = 0; m < 2; ++m)
; #pragma unroll
;         for (int n = 0; n < 4; ++n) acc[m][n] = __builtin_amdgcn_mfma_f32_16x16x32_bf16(a[m], b[n], acc[m][n], 0, 0, 0);
;     }
;     __syncthreads();
; #pragma unroll
;     for (int m = 0; m < 2; ++m)
; #pragma unroll
;       for (int n = 0; n < 4; ++n) red[(wid * 8 + m * 4 + n) * 64 + lane] = acc[m][n];
.LBB0_3116:
	s_and_b32 s25, s15, 0x60
	v_or_b32_e32 v0, s25, v18
	s_and_b32 s2, s14, 0xffffffc0
	v_or_b32_e32 v22, s2, v18
	v_lshlrev_b32_e32 v0, 11, v0
	v_lshl_add_u64 v[70:71], v[2:3], 0, v[0:1]
	v_ashrrev_i32_e32 v23, 31, v22
	global_load_dwordx4 v[6:9], v[70:71], off
	v_lshlrev_b64 v[10:11], 11, v[22:23]
	v_or_b32_e32 v14, 16, v22
	v_or_b32_e32 v22, 32, v22
	v_ashrrev_i32_e32 v15, 31, v14
	v_ashrrev_i32_e32 v23, 31, v22
	v_or_b32_e32 v26, s14, v20
	v_lshlrev_b64 v[14:15], 11, v[14:15]
	v_lshlrev_b64 v[22:23], 11, v[22:23]
	v_ashrrev_i32_e32 v27, 31, v26
	v_lshl_add_u64 v[72:73], v[4:5], 0, v[10:11]
	v_lshl_add_u64 v[74:75], v[4:5], 0, v[14:15]
	v_lshl_add_u64 v[78:79], v[4:5], 0, v[22:23]
	v_lshlrev_b64 v[26:27], 11, v[26:27]
	global_load_dwordx4 v[10:13], v[72:73], off
	global_load_dwordx4 v[14:17], v[74:75], off
	global_load_dwordx4 v[22:25], v[78:79], off
	v_lshl_add_u64 v[86:87], v[4:5], 0, v[26:27]
	global_load_dwordx4 v[26:29], v[70:71], off offset:64
	global_load_dwordx4 v[30:33], v[72:73], off offset:64
	global_load_dwordx4 v[38:41], v[86:87], off
	global_load_dwordx4 v[42:45], v[74:75], off offset:64
	v_add_co_u32_e64 v88, s[8:9], s21, v70
	global_load_dwordx4 v[50:53], v[78:79], off offset:64
	s_nop 0
	v_addc_co_u32_e64 v89, s[8:9], 0, v71, s[8:9]
	global_load_dwordx4 v[58:61], v[88:89], off
	global_load_dwordx4 v[62:65], v[86:87], off offset:64
	global_load_dwordx4 v[66:69], v[88:89], off offset:64
	s_waitcnt vmcnt(10)
	v_mfma_f32_16x16x32_bf16 v[34:37], v[6:9], v[10:13], 0
	s_waitcnt vmcnt(9)
	v_mfma_f32_16x16x32_bf16 v[46:49], v[6:9], v[14:17], 0
	s_waitcnt vmcnt(8)
	v_mfma_f32_16x16x32_bf16 v[54:57], v[6:9], v[22:25], 0
	s_waitcnt vmcnt(5)
	v_mfma_f32_16x16x32_bf16 v[6:9], v[6:9], v[38:41], 0
	s_waitcnt vmcnt(2)
	v_mfma_f32_16x16x32_bf16 v[10:13], v[58:61], v[10:13], 0
	v_mfma_f32_16x16x32_bf16 v[34:37], v[26:29], v[30:33], v[34:37]
	v_mfma_f32_16x16x32_bf16 v[46:49], v[26:29], v[42:45], v[46:49]
	v_mfma_f32_16x16x32_bf16 v[54:57], v[26:29], v[50:53], v[54:57]
	s_waitcnt vmcnt(1)
	v_mfma_f32_16x16x32_bf16 v[6:9], v[26:29], v[62:65], v[6:9]
	global_load_dwordx4 v[26:29], v[70:71], off offset:128
	v_mfma_f32_16x16x32_bf16 v[14:17], v[58:61], v[14:17], 0
	v_mfma_f32_16x16x32_bf16 v[22:25], v[58:61], v[22:25], 0
	v_mfma_f32_16x16x32_bf16 v[38:41], v[58:61], v[38:41], 0
	s_waitcnt vmcnt(1)
	v_mfma_f32_16x16x32_bf16 v[10:13], v[66:69], v[30:33], v[10:13]
	global_load_dwordx4 v[30:33], v[72:73], off offset:128
	v_mfma_f32_16x16x32_bf16 v[14:17], v[66:69], v[42:45], v[14:17]
	v_mfma_f32_16x16x32_bf16 v[22:25], v[66:69], v[50:53], v[22:25]
	global_load_dwordx4 v[42:45], v[74:75], off offset:128
	global_load_dwordx4 v[50:53], v[70:71], off offset:192
	global_load_dwordx4 v[58:61], v[72:73], off offset:192
	v_mfma_f32_16x16x32_bf16 v[38:41], v[66:69], v[62:65], v[38:41]
	global_load_dwordx4 v[62:65], v[78:79], off offset:128
	global_load_dwordx4 v[66:69], v[74:75], off offset:192
	global_load_dwordx4 v[70:73], v[86:87], off offset:128
	s_nop 0
	global_load_dwordx4 v[74:77], v[78:79], off offset:192
	s_nop 0
	global_load_dwordx4 v[78:81], v[88:89], off offset:128
	global_load_dwordx4 v[82:85], v[86:87], off offset:192
	s_waitcnt vmcnt(1)
	v_mfma_f32_16x16x32_bf16 v[14:17], v[78:81], v[42:45], v[14:17]
	v_mfma_f32_16x16x32_bf16 v[34:37], v[26:29], v[30:33], v[34:37]
	v_mfma_f32_16x16x32_bf16 v[46:49], v[26:29], v[42:45], v[46:49]
	v_mfma_f32_16x16x32_bf16 v[54:57], v[26:29], v[62:65], v[54:57]
	v_mfma_f32_16x16x32_bf16 v[6:9], v[26:29], v[70:73], v[6:9]
	global_load_dwordx4 v[26:29], v[88:89], off offset:192
	s_barrier
	v_mfma_f32_16x16x32_bf16 v[10:13], v[78:81], v[30:33], v[10:13]
	v_mfma_f32_16x16x32_bf16 v[22:25], v[78:81], v[62:65], v[22:25]
	v_mfma_f32_16x16x32_bf16 v[30:33], v[78:81], v[70:73], v[38:41]
	v_mfma_f32_16x16x32_bf16 v[34:37], v[50:53], v[58:61], v[34:37]
	v_mfma_f32_16x16x32_bf16 v[38:41], v[50:53], v[66:69], v[46:49]
	v_mfma_f32_16x16x32_bf16 v[42:45], v[50:53], v[74:77], v[54:57]
	s_nop 5
	ds_write_b128 v21, v[34:37]
	s_waitcnt vmcnt(1)
	v_mfma_f32_16x16x32_bf16 v[6:9], v[50:53], v[82:85], v[6:9]
	ds_write_b128 v21, v[38:41] offset:1024
	ds_write_b128 v21, v[42:45] offset:2048
	s_nop 5
	ds_write_b128 v21, v[6:9] offset:3072
	s_waitcnt vmcnt(0)
	v_mfma_f32_16x16x32_bf16 v[10:13], v[26:29], v[58:61], v[10:13]
	v_mfma_f32_16x16x32_bf16 v[14:17], v[26:29], v[66:69], v[14:17]
	v_mfma_f32_16x16x32_bf16 v[6:9], v[26:29], v[74:77], v[22:25]
	s_nop 5
	ds_write_b128 v21, v[10:13] offset:4096
	ds_write_b128 v21, v[14:17] offset:5120
	ds_write_b128 v21, v[6:9] offset:6144
	v_mfma_f32_16x16x32_bf16 v[6:9], v[26:29], v[82:85], v[30:33]
	s_nop 7
	ds_write_b128 v21, v[6:9] offset:7168
	s_waitcnt lgkmcnt(0)
	s_barrier
	s_and_saveexec_b64 s[0:1], vcc
	s_cbranch_execz .LBB0_3115
; template <class Epi>
; __device__ __forceinline__ void small_gemm(const u16* __restrict__ A, const u16* __restrict__ Bt, int K, int N, const Epi& epi) {
;     ...
;     if (wid == 0) {
; #pragma unroll
;       for (int m = 0; m < 2; ++m)
; #pragma unroll
;         for (int n = 0; n < 4; ++n) {
;           f32x4 s = red[(m * 4 + n) * 64 + lane];
; #pragma unroll
;           for (int w = 1; w < 8; ++w) s += red[(w * 8 + m * 4 + n) * 64 + lane];
;           acc[m][n] = s;
;         }
	ds_read_b128 v[6:9], v19
	ds_read_b128 v[10:13], v19 offset:8192
	ds_read_b128 v[14:17], v19 offset:16384
	ds_read_b128 v[22:25], v19 offset:1024
	ds_read_b128 v[26:29], v19 offset:9216
	v_mov_b32_e32 v0, v204
	s_waitcnt lgkmcnt(3)
	v_pk_add_f32 v[30:31], v[8:9], v[12:13]
	v_pk_add_f32 v[32:33], v[6:7], v[10:11]
	ds_read_b128 v[6:9], v19 offset:24576
	ds_read_b128 v[10:13], v19 offset:17408
	s_waitcnt lgkmcnt(4)
	v_pk_add_f32 v[34:35], v[30:31], v[16:17]
	v_pk_add_f32 v[36:37], v[32:33], v[14:15]
	ds_read_b128 v[14:17], v19 offset:32768
	ds_read_b128 v[30:33], v19 offset:25600
	s_waitcnt lgkmcnt(3)
	v_pk_add_f32 v[38:39], v[34:35], v[8:9]
	v_pk_add_f32 v[40:41], v[36:37], v[6:7]
	ds_read_b128 v[6:9], v19 offset:40960
	ds_read_b128 v[34:37], v19 offset:33792
	s_waitcnt lgkmcnt(3)
	v_pk_add_f32 v[42:43], v[38:39], v[16:17]
	v_pk_add_f32 v[44:45], v[40:41], v[14:15]
	ds_read_b128 v[14:17], v19 offset:49152
	ds_read_b128 v[38:41], v19 offset:41984
	s_waitcnt lgkmcnt(3)
	v_pk_add_f32 v[8:9], v[42:43], v[8:9]
	v_pk_add_f32 v[6:7], v[44:45], v[6:7]
	ds_read_b128 v[42:45], v19 offset:57344
	ds_read_b128 v[46:49], v19 offset:50176
	v_pk_add_f32 v[24:25], v[24:25], v[28:29]
	v_pk_add_f32 v[22:23], v[22:23], v[26:27]
	s_waitcnt lgkmcnt(3)
	v_pk_add_f32 v[8:9], v[8:9], v[16:17]
	v_pk_add_f32 v[50:51], v[6:7], v[14:15]
	ds_read_b128 v[14:17], v19 offset:58368
	v_pk_add_f32 v[12:13], v[24:25], v[12:13]
	v_pk_add_f32 v[10:11], v[22:23], v[10:11]
	ds_read_b128 v[22:25], v19 offset:2048
	ds_read_b128 v[26:29], v19 offset:10240
	v_pk_add_f32 v[12:13], v[12:13], v[32:33]
	v_pk_add_f32 v[10:11], v[10:11], v[30:31]
	v_pk_add_f32 v[12:13], v[12:13], v[36:37]
	v_pk_add_f32 v[10:11], v[10:11], v[34:35]
	s_waitcnt lgkmcnt(5)
	v_pk_add_f32 v[12:13], v[12:13], v[40:41]
	v_pk_add_f32 v[10:11], v[10:11], v[38:39]
	s_waitcnt lgkmcnt(3)
	v_pk_add_f32 v[12:13], v[12:13], v[48:49]
	v_pk_add_f32 v[30:31], v[10:11], v[46:47]
	s_waitcnt lgkmcnt(2)
	v_pk_add_f32 v[10:11], v[12:13], v[16:17]
	v_pk_add_f32 v[12:13], v[30:31], v[14:15]
	ds_read_b128 v[14:17], v19 offset:18432
	ds_read_b128 v[30:33], v19 offset:3072
	ds_read_b128 v[34:37], v19 offset:11264
	s_waitcnt lgkmcnt(3)
	v_pk_add_f32 v[38:39], v[24:25], v[28:29]
	v_pk_add_f32 v[40:41], v[22:23], v[26:27]
	ds_read_b128 v[22:25], v19 offset:26624
	ds_read_b128 v[26:29], v19 offset:19456
	v_pk_add_f32 v[6:7], v[8:9], v[44:45]
	v_pk_add_f32 v[8:9], v[50:51], v[42:43]
	s_waitcnt lgkmcnt(4)
	v_pk_add_f32 v[42:43], v[38:39], v[16:17]
	v_pk_add_f32 v[44:45], v[40:41], v[14:15]
	ds_read_b128 v[14:17], v19 offset:34816
	ds_read_b128 v[38:41], v19 offset:27648
	s_waitcnt lgkmcnt(3)
	v_pk_add_f32 v[46:47], v[42:43], v[24:25]
	v_pk_add_f32 v[48:49], v[44:45], v[22:23]
	ds_read_b128 v[22:25], v19 offset:43008
	ds_read_b128 v[42:45], v19 offset:35840
	s_waitcnt lgkmcnt(3)
	v_pk_add_f32 v[50:51], v[46:47], v[16:17]
	v_pk_add_f32 v[52:53], v[48:49], v[14:15]
	ds_read_b128 v[14:17], v19 offset:51200
	ds_read_b128 v[46:49], v19 offset:44032
	s_waitcnt lgkmcnt(3)
	v_pk_add_f32 v[54:55], v[50:51], v[24:25]
	v_pk_add_f32 v[56:57], v[52:53], v[22:23]
	ds_read_b128 v[22:25], v19 offset:59392
	ds_read_b128 v[50:53], v19 offset:52224
	s_waitcnt lgkmcnt(3)
	v_pk_add_f32 v[16:17], v[54:55], v[16:17]
	v_pk_add_f32 v[58:59], v[56:57], v[14:15]
	ds_read_b128 v[54:57], v19 offset:60416
	s_waitcnt lgkmcnt(2)
	v_pk_add_f32 v[14:15], v[16:17], v[24:25]
	v_pk_add_f32 v[16:17], v[58:59], v[22:23]
	v_pk_add_f32 v[22:23], v[32:33], v[36:37]
	v_pk_add_f32 v[24:25], v[30:31], v[34:35]
	v_pk_add_f32 v[22:23], v[22:23], v[28:29]
	v_pk_add_f32 v[24:25], v[24:25], v[26:27]
	v_pk_add_f32 v[22:23], v[22:23], v[40:41]
	v_pk_add_f32 v[24:25], v[24:25], v[38:39]
	v_pk_add_f32 v[22:23], v[22:23], v[44:45]
	v_pk_add_f32 v[24:25], v[24:25], v[42:43]
	v_pk_add_f32 v[22:23], v[22:23], v[48:49]
	v_pk_add_f32 v[24:25], v[24:25], v[46:47]
	s_waitcnt lgkmcnt(1)
	v_pk_add_f32 v[22:23], v[22:23], v[52:53]
	v_pk_add_f32 v[30:31], v[24:25], v[50:51]
	s_waitcnt lgkmcnt(0)
	v_pk_add_f32 v[58:59], v[22:23], v[56:57]
	ds_read_b128 v[22:25], v19 offset:4096
	ds_read_b128 v[26:29], v19 offset:12288
	v_pk_add_f32 v[60:61], v[30:31], v[54:55]
	ds_read_b128 v[30:33], v19 offset:20480
	ds_read_b128 v[34:37], v19 offset:5120
	ds_read_b128 v[38:41], v19 offset:13312
	s_waitcnt lgkmcnt(3)
	v_pk_add_f32 v[42:43], v[24:25], v[28:29]
	v_pk_add_f32 v[44:45], v[22:23], v[26:27]
	ds_read_b128 v[22:25], v19 offset:28672
	ds_read_b128 v[26:29], v19 offset:21504
	s_waitcnt lgkmcnt(4)
	v_pk_add_f32 v[46:47], v[42:43], v[32:33]
	v_pk_add_f32 v[48:49], v[44:45], v[30:31]
	ds_read_b128 v[30:33], v19 offset:36864
	ds_read_b128 v[42:45], v19 offset:29696
	s_waitcnt lgkmcnt(3)
	v_pk_add_f32 v[50:51], v[46:47], v[24:25]
	v_pk_add_f32 v[52:53], v[48:49], v[22:23]
	ds_read_b128 v[22:25], v19 offset:45056
	ds_read_b128 v[46:49], v19 offset:37888
	s_waitcnt lgkmcnt(3)
	v_pk_add_f32 v[54:55], v[50:51], v[32:33]
	v_pk_add_f32 v[56:57], v[52:53], v[30:31]
	ds_read_b128 v[30:33], v19 offset:53248
	ds_read_b128 v[50:53], v19 offset:46080
	s_waitcnt lgkmcnt(3)
	v_pk_add_f32 v[62:63], v[54:55], v[24:25]
	v_pk_add_f32 v[64:65], v[56:57], v[22:23]
	ds_read_b128 v[22:25], v19 offset:61440
	ds_read_b128 v[54:57], v19 offset:54272
	s_waitcnt lgkmcnt(3)
	v_pk_add_f32 v[64:65], v[64:65], v[30:31]
	v_pk_add_f32 v[62:63], v[62:63], v[32:33]
	ds_read_b128 v[30:33], v19 offset:62464
	s_waitcnt lgkmcnt(2)
;   __device__ __forceinline__ void tile(const float* reg, int row0, int col0, int lane) const {
;     rows4(reg, lane, [&](int it, int rr, int c4, float4 v) {
;       int row = row0 + rr, idx = row * 1024 + col0 + c4;
;       float4 xo = *(const float4*)(xold + idx);
;       v.x = fmaf(coef, v.x, xo.x); v.y = fmaf(coef, v.y, xo.y); v.z = fmaf(coef, v.z, xo.z); v.w = fmaf(coef, v.w, xo.w);
;       *(float4*)(xnew + idx) = v;
;       *(bf16x4*)(xb + idx) = pack4(v.x, v.y, v.z, v.w);
;       float s = row16_sum(v.x * v.x + v.y * v.y + v.z * v.z + v.w * v.w);
;       if ((lane & 15) == 0) atomicAdd(ssqn + row, s);
;     });
; template <int MF, class Epi>
; __device__ __forceinline__ void staged_epilogue(f32x4 (&acc)[MF][4], int row0, int col0, const Epi& epi) {
;     ...
; #pragma unroll
;   for (int mp = 0; mp < MF / 2; ++mp) {
;     __builtin_amdgcn_sched_barrier(0);
; #pragma unroll
;     for (int mm = 0; mm < 2; ++mm)
; #pragma unroll
;       for (int n = 0; n < 4; ++n)
; #pragma unroll
;         for (int j = 0; j < 4; ++j) reg[(mm * 16 + fq * 4 + j) * 68 + n * 16 + fr] = acc[mp * 2 + mm][n][j];
;     __builtin_amdgcn_fence(__ATOMIC_ACQ_REL, "wavefront");
;     epi.tile(reg, row0 + mp * 32, col0, lane);
	v_pk_add_f32 v[64:65], v[64:65], v[22:23]
	v_pk_add_f32 v[22:23], v[36:37], v[40:41]
	v_pk_add_f32 v[62:63], v[62:63], v[24:25]
	v_pk_add_f32 v[24:25], v[34:35], v[38:39]
	v_pk_add_f32 v[22:23], v[22:23], v[28:29]
	v_pk_add_f32 v[24:25], v[24:25], v[26:27]
	v_pk_add_f32 v[22:23], v[22:23], v[44:45]
	v_pk_add_f32 v[24:25], v[24:25], v[42:43]
	v_pk_add_f32 v[22:23], v[22:23], v[48:49]
	v_pk_add_f32 v[24:25], v[24:25], v[46:47]
	v_pk_add_f32 v[22:23], v[22:23], v[52:53]
	v_pk_add_f32 v[24:25], v[24:25], v[50:51]
	s_waitcnt lgkmcnt(1)
	v_pk_add_f32 v[22:23], v[22:23], v[56:57]
	v_pk_add_f32 v[34:35], v[24:25], v[54:55]
	s_waitcnt lgkmcnt(0)
	v_pk_add_f32 v[66:67], v[22:23], v[32:33]
	ds_read_b128 v[22:25], v19 offset:6144
	ds_read_b128 v[26:29], v19 offset:14336
	v_pk_add_f32 v[68:69], v[34:35], v[30:31]
	ds_read_b128 v[30:33], v19 offset:22528
	ds_read_b128 v[34:37], v19 offset:7168
	ds_read_b128 v[38:41], v19 offset:15360
	s_waitcnt lgkmcnt(3)
	v_pk_add_f32 v[42:43], v[24:25], v[28:29]
	v_pk_add_f32 v[44:45], v[22:23], v[26:27]
	ds_read_b128 v[22:25], v19 offset:30720
	ds_read_b128 v[26:29], v19 offset:23552
	s_waitcnt lgkmcnt(4)
	v_pk_add_f32 v[46:47], v[42:43], v[32:33]
	v_pk_add_f32 v[48:49], v[44:45], v[30:31]
	ds_read_b128 v[30:33], v19 offset:38912
	ds_read_b128 v[42:45], v19 offset:31744
	s_waitcnt lgkmcnt(3)
	v_pk_add_f32 v[50:51], v[46:47], v[24:25]
	v_pk_add_f32 v[52:53], v[48:49], v[22:23]
	ds_read_b128 v[22:25], v19 offset:47104
	ds_read_b128 v[46:49], v19 offset:39936
	s_waitcnt lgkmcnt(3)
	v_pk_add_f32 v[54:55], v[50:51], v[32:33]
	v_pk_add_f32 v[56:57], v[52:53], v[30:31]
	ds_read_b128 v[30:33], v19 offset:55296
	ds_read_b128 v[50:53], v19 offset:48128
	s_waitcnt lgkmcnt(3)
	v_pk_add_f32 v[70:71], v[54:55], v[24:25]
	v_pk_add_f32 v[72:73], v[56:57], v[22:23]
	ds_read_b128 v[22:25], v19 offset:63488
	ds_read_b128 v[54:57], v19 offset:56320
	s_waitcnt lgkmcnt(3)
	v_pk_add_f32 v[72:73], v[72:73], v[30:31]
	v_pk_add_f32 v[70:71], v[70:71], v[32:33]
	ds_read_b128 v[30:33], v19 offset:64512
	s_waitcnt lgkmcnt(2)
	v_pk_add_f32 v[72:73], v[72:73], v[22:23]
	v_pk_add_f32 v[22:23], v[36:37], v[40:41]
	v_pk_add_f32 v[70:71], v[70:71], v[24:25]
	v_pk_add_f32 v[22:23], v[22:23], v[28:29]
	v_pk_add_f32 v[24:25], v[34:35], v[38:39]
	v_pk_add_f32 v[22:23], v[22:23], v[44:45]
	v_pk_add_f32 v[24:25], v[24:25], v[26:27]
	v_pk_add_f32 v[22:23], v[22:23], v[48:49]
	v_pk_add_f32 v[24:25], v[24:25], v[42:43]
	v_pk_add_f32 v[22:23], v[22:23], v[52:53]
	v_pk_add_f32 v[24:25], v[24:25], v[46:47]
	s_waitcnt lgkmcnt(1)
	v_pk_add_f32 v[22:23], v[22:23], v[56:57]
	v_pk_add_f32 v[24:25], v[24:25], v[50:51]
	s_waitcnt lgkmcnt(0)
	v_pk_add_f32 v[26:27], v[22:23], v[32:33]
	v_mov_b32_e32 v22, v204
	v_pk_add_f32 v[24:25], v[24:25], v[54:55]
	v_lshrrev_b32_e32 v0, 6, v0
	v_mul_lo_u32 v0, v0, s22
	v_add_u32_e32 v23, 0x10000, v0
	v_lshrrev_b32_e32 v0, 2, v22
	v_pk_add_f32 v[28:29], v[24:25], v[30:31]
	v_and_b32_e32 v25, 15, v22
	v_and_b32_e32 v31, 12, v0
	v_bfe_u32 v0, v22, 4, 2
	v_lshlrev_b32_e32 v22, 2, v22
	v_and_b32_e32 v22, 60, v22
	v_lshl_or_b32 v32, v25, 2, v23
	v_lshl_or_b32 v23, v22, 2, v23
	v_or_b32_e32 v24, s25, v0
	v_or_b32_e32 v22, s2, v22
	v_cmp_eq_u32_e64 s[8:9], 0, v25
	v_mad_u32_u24 v33, v0, s23, v23
	v_lshl_add_u32 v30, v24, 10, v22
	v_mad_u32_u24 v25, v31, s23, v32
	ds_write2_b32 v25, v8, v12 offset1:16
	ds_write2_b32 v25, v9, v13 offset0:68 offset1:84
	ds_write2_b32 v25, v6, v10 offset0:136 offset1:152
	ds_write2_b32 v25, v7, v11 offset0:204 offset1:220
	ds_write2_b32 v25, v16, v60 offset0:32 offset1:48
	ds_write2_b32 v25, v17, v61 offset0:100 offset1:116
	ds_write2_b32 v25, v14, v58 offset0:168 offset1:184
	ds_write2_b32 v25, v15, v59 offset0:236 offset1:252
	v_add_u32_e32 v6, 0x1000, v25
	v_add_u32_e32 v7, 0x1400, v25
	ds_write2_b32 v6, v64, v68 offset0:64 offset1:80
	ds_write2_b32 v6, v65, v69 offset0:132 offset1:148
	ds_write2_b32 v6, v62, v66 offset0:200 offset1:216
	ds_write2_b32 v7, v63, v67 offset0:12 offset1:28
	ds_write2_b32 v6, v72, v28 offset0:96 offset1:112
	ds_write2_b32 v6, v73, v29 offset0:164 offset1:180
	ds_write2_b32 v6, v70, v26 offset0:232 offset1:248
	ds_write2_b32 v7, v71, v27 offset0:44 offset1:60
	v_mov_b32_e32 v178, v30
	v_ashrrev_i32_e32 v179, 31, v178
	v_lshl_add_u64 v[176:177], v[178:179], 2, s[12:13]
	global_load_dwordx4 v[144:147], v[176:177], off
	v_or3_b32 v184, v0, s25, 4
	v_lshl_add_u32 v176, v184, 10, v22
	v_ashrrev_i32_e32 v177, 31, v176
	v_lshl_add_u64 v[178:179], v[176:177], 2, s[12:13]
	global_load_dwordx4 v[148:151], v[178:179], off
	v_or3_b32 v184, v0, s25, 8
	v_lshl_add_u32 v176, v184, 10, v22
	v_ashrrev_i32_e32 v177, 31, v176
	v_lshl_add_u64 v[178:179], v[176:177], 2, s[12:13]
	global_load_dwordx4 v[152:155], v[178:179], off
	v_or3_b32 v184, v0, s25, 12
	v_lshl_add_u32 v176, v184, 10, v22
	v_ashrrev_i32_e32 v177, 31, v176
	v_lshl_add_u64 v[178:179], v[176:177], 2, s[12:13]
	global_load_dwordx4 v[156:159], v[178:179], off
	v_or3_b32 v184, v0, s25, 16
	v_lshl_add_u32 v176, v184, 10, v22
	v_ashrrev_i32_e32 v177, 31, v176
	v_lshl_add_u64 v[178:179], v[176:177], 2, s[12:13]
	global_load_dwordx4 v[160:163], v[178:179], off
	v_or3_b32 v184, v0, s25, 20
	v_lshl_add_u32 v176, v184, 10, v22
	v_ashrrev_i32_e32 v177, 31, v176
	v_lshl_add_u64 v[178:179], v[176:177], 2, s[12:13]
	global_load_dwordx4 v[164:167], v[178:179], off
	v_or3_b32 v184, v0, s25, 24
	v_lshl_add_u32 v176, v184, 10, v22
	v_ashrrev_i32_e32 v177, 31, v176
	v_lshl_add_u64 v[178:179], v[176:177], 2, s[12:13]
	global_load_dwordx4 v[168:171], v[178:179], off
	v_or3_b32 v184, v0, s25, 28
	v_lshl_add_u32 v176, v184, 10, v22
	v_ashrrev_i32_e32 v177, 31, v176
	v_lshl_add_u64 v[178:179], v[176:177], 2, s[12:13]
	global_load_dwordx4 v[172:175], v[178:179], off
	v_ashrrev_i32_e32 v31, 31, v30
	v_lshl_add_u64 v[14:15], v[30:31], 2, s[12:13]
	ds_read_b128 v[10:13], v33
	v_lshl_add_u64 v[16:17], v[30:31], 1, s[16:17]
	s_waitcnt vmcnt(7) lgkmcnt(0)
	v_mov_b32_e32 v6, v144
	v_mov_b32_e32 v7, v145
	v_mov_b32_e32 v8, v146
	v_mov_b32_e32 v9, v147
	v_pk_add_f32 v[6:7], v[10:11], v[6:7]
	v_pk_add_f32 v[8:9], v[12:13], v[8:9]
	global_store_dwordx4 v[14:15], v[6:9], off
	v_cvt_pk_bf16_f32 v10, v6, v7
	v_cvt_pk_bf16_f32 v11, v8, v9
	v_pk_mul_f32 v[6:7], v[6:7], v[6:7]
	v_pk_mul_f32 v[8:9], v[8:9], v[8:9]
	v_add_f32_e32 v6, v6, v7
	v_add_f32_e32 v6, v8, v6
	v_add_f32_e32 v6, v9, v6
	v_mov_b32_e32 v7, 0
	global_store_dwordx2 v[16:17], v[10:11], off
	v_add_f32_dpp v6, v6, v6 quad_perm:[1,0,3,2] row_mask:0xf bank_mask:0xf bound_ctrl:1
	s_nop 1
	v_add_f32_dpp v6, v6, v6 quad_perm:[2,3,0,1] row_mask:0xf bank_mask:0xf bound_ctrl:1
	s_nop 1
	v_add_f32_dpp v6, v6, v6 row_half_mirror row_mask:0xf bank_mask:0xf bound_ctrl:1
	s_nop 1
	v_mov_b32_dpp v7, v6 row_mirror row_mask:0xf bank_mask:0xf
	s_and_saveexec_b64 s[2:3], s[8:9]
	s_cbranch_execz .LBB0_3119
	v_add_f32_e32 v6, v6, v7
	v_lshlrev_b32_e32 v7, 2, v24
	global_atomic_add_f32 v7, v6, s[18:19]
;   __device__ __forceinline__ void tile(const float* reg, int row0, int col0, int lane) const {
;     rows4(reg, lane, [&](int it, int rr, int c4, float4 v) {
;       int row = row0 + rr, idx = row * 1024 + col0 + c4;
;       float4 xo = *(const float4*)(xold + idx);
;       v.x = fmaf(coef, v.x, xo.x); v.y = fmaf(coef, v.y, xo.y); v.z = fmaf(coef, v.z, xo.z); v.w = fmaf(coef, v.w, xo.w);
;       *(float4*)(xnew + idx) = v;
;       *(bf16x4*)(xb + idx) = pack4(v.x, v.y, v.z, v.w);
;       float s = row16_sum(v.x * v.x + v.y * v.y + v.z * v.z + v.w * v.w);
;       if ((lane & 15) == 0) atomicAdd(ssqn + row, s);
;     });
.LBB0_3119:
	s_or_b64 exec, exec, s[2:3]
	v_or3_b32 v7, v0, s25, 4
	v_lshl_add_u32 v16, v7, 10, v22
	v_ashrrev_i32_e32 v17, 31, v16
	v_lshl_add_u64 v[24:25], v[16:17], 2, s[12:13]
	v_mul_u32_u24_e32 v6, 0x110, v0
	v_add_u32_e32 v6, v23, v6
	ds_read_b128 v[12:15], v6 offset:1088
	v_lshl_add_u64 v[16:17], v[16:17], 1, s[16:17]
	s_waitcnt vmcnt(9) lgkmcnt(0)
	v_mov_b32_e32 v8, v148
	v_mov_b32_e32 v9, v149
	v_mov_b32_e32 v10, v150
	v_mov_b32_e32 v11, v151
	v_pk_add_f32 v[8:9], v[12:13], v[8:9]
	v_pk_add_f32 v[10:11], v[14:15], v[10:11]
	global_store_dwordx4 v[24:25], v[8:11], off
	v_cvt_pk_bf16_f32 v12, v8, v9
	v_cvt_pk_bf16_f32 v13, v10, v11
	v_pk_mul_f32 v[8:9], v[8:9], v[8:9]
	v_pk_mul_f32 v[10:11], v[10:11], v[10:11]
	v_add_f32_e32 v8, v8, v9
	v_add_f32_e32 v8, v10, v8
	v_add_f32_e32 v8, v11, v8
	v_mov_b32_e32 v9, 0
	global_store_dwordx2 v[16:17], v[12:13], off
	v_add_f32_dpp v8, v8, v8 quad_perm:[1,0,3,2] row_mask:0xf bank_mask:0xf bound_ctrl:1
	s_nop 1
	v_add_f32_dpp v8, v8, v8 quad_perm:[2,3,0,1] row_mask:0xf bank_mask:0xf bound_ctrl:1
	s_nop 1
	v_add_f32_dpp v8, v8, v8 row_half_mirror row_mask:0xf bank_mask:0xf bound_ctrl:1
	s_nop 1
	v_mov_b32_dpp v9, v8 row_mirror row_mask:0xf bank_mask:0xf
	s_and_saveexec_b64 s[2:3], s[8:9]
	s_cbranch_execz .LBB0_3121
	v_add_f32_e32 v8, v8, v9
	v_lshlrev_b32_e32 v7, 2, v7
	global_atomic_add_f32 v7, v8, s[18:19]
.LBB0_3121:
	s_or_b64 exec, exec, s[2:3]
	v_or3_b32 v7, v0, s25, 8
	v_lshl_add_u32 v16, v7, 10, v22
	v_ashrrev_i32_e32 v17, 31, v16
	v_lshl_add_u64 v[24:25], v[16:17], 2, s[12:13]
	ds_read_b128 v[12:15], v6 offset:2176
	v_lshl_add_u64 v[16:17], v[16:17], 1, s[16:17]
	s_waitcnt vmcnt(11) lgkmcnt(0)
	v_mov_b32_e32 v8, v152
	v_mov_b32_e32 v9, v153
	v_mov_b32_e32 v10, v154
	v_mov_b32_e32 v11, v155
	v_pk_add_f32 v[8:9], v[12:13], v[8:9]
	v_pk_add_f32 v[10:11], v[14:15], v[10:11]
	global_store_dwordx4 v[24:25], v[8:11], off
	v_cvt_pk_bf16_f32 v12, v8, v9
	v_cvt_pk_bf16_f32 v13, v10, v11
	v_pk_mul_f32 v[8:9], v[8:9], v[8:9]
	v_pk_mul_f32 v[10:11], v[10:11], v[10:11]
	v_add_f32_e32 v8, v8, v9
	v_add_f32_e32 v8, v10, v8
	v_add_f32_e32 v8, v11, v8
	v_mov_b32_e32 v9, 0
	global_store_dwordx2 v[16:17], v[12:13], off
	v_add_f32_dpp v8, v8, v8 quad_perm:[1,0,3,2] row_mask:0xf bank_mask:0xf bound_ctrl:1
	s_nop 1
	v_add_f32_dpp v8, v8, v8 quad_perm:[2,3,0,1] row_mask:0xf bank_mask:0xf bound_ctrl:1
	s_nop 1
	v_add_f32_dpp v8, v8, v8 row_half_mirror row_mask:0xf bank_mask:0xf bound_ctrl:1
	s_nop 1
	v_mov_b32_dpp v9, v8 row_mirror row_mask:0xf bank_mask:0xf
	s_and_saveexec_b64 s[2:3], s[8:9]
	s_cbranch_execz .LBB0_3123
	v_add_f32_e32 v8, v8, v9
	v_lshlrev_b32_e32 v7, 2, v7
	global_atomic_add_f32 v7, v8, s[18:19]
.LBB0_3123:
	s_or_b64 exec, exec, s[2:3]
	v_or3_b32 v7, v0, s25, 12
	v_lshl_add_u32 v16, v7, 10, v22
	v_ashrrev_i32_e32 v17, 31, v16
	v_lshl_add_u64 v[24:25], v[16:17], 2, s[12:13]
	ds_read_b128 v[12:15], v6 offset:3264
	v_lshl_add_u64 v[16:17], v[16:17], 1, s[16:17]
	s_waitcnt vmcnt(13) lgkmcnt(0)
	v_mov_b32_e32 v8, v156
	v_mov_b32_e32 v9, v157
	v_mov_b32_e32 v10, v158
	v_mov_b32_e32 v11, v159
	v_pk_add_f32 v[8:9], v[12:13], v[8:9]
	v_pk_add_f32 v[10:11], v[14:15], v[10:11]
	global_store_dwordx4 v[24:25], v[8:11], off
	v_cvt_pk_bf16_f32 v12, v8, v9
	v_cvt_pk_bf16_f32 v13, v10, v11
	v_pk_mul_f32 v[8:9], v[8:9], v[8:9]
	v_pk_mul_f32 v[10:11], v[10:11], v[10:11]
	v_add_f32_e32 v8, v8, v9
	v_add_f32_e32 v8, v10, v8
	v_add_f32_e32 v8, v11, v8
	v_mov_b32_e32 v9, 0
	global_store_dwordx2 v[16:17], v[12:13], off
	v_add_f32_dpp v8, v8, v8 quad_perm:[1,0,3,2] row_mask:0xf bank_mask:0xf bound_ctrl:1
	s_nop 1
	v_add_f32_dpp v8, v8, v8 quad_perm:[2,3,0,1] row_mask:0xf bank_mask:0xf bound_ctrl:1
	s_nop 1
	v_add_f32_dpp v8, v8, v8 row_half_mirror row_mask:0xf bank_mask:0xf bound_ctrl:1
	s_nop 1
	v_mov_b32_dpp v9, v8 row_mirror row_mask:0xf bank_mask:0xf
	s_and_saveexec_b64 s[2:3], s[8:9]
	s_cbranch_execz .LBB0_3125
	v_add_f32_e32 v8, v8, v9
	v_lshlrev_b32_e32 v7, 2, v7
	global_atomic_add_f32 v7, v8, s[18:19]
;   __device__ __forceinline__ void tile(const float* reg, int row0, int col0, int lane) const {
;     rows4(reg, lane, [&](int it, int rr, int c4, float4 v) {
;       int row = row0 + rr, idx = row * 1024 + col0 + c4;
;       float4 xo = *(const float4*)(xold + idx);
;       v.x = fmaf(coef, v.x, xo.x); v.y = fmaf(coef, v.y, xo.y); v.z = fmaf(coef, v.z, xo.z); v.w = fmaf(coef, v.w, xo.w);
;       *(float4*)(xnew + idx) = v;
;       *(bf16x4*)(xb + idx) = pack4(v.x, v.y, v.z, v.w);
;       float s = row16_sum(v.x * v.x + v.y * v.y + v.z * v.z + v.w * v.w);
;       if ((lane & 15) == 0) atomicAdd(ssqn + row, s);
;     });
.LBB0_3125:
	s_or_b64 exec, exec, s[2:3]
	v_or3_b32 v7, v0, s25, 16
	v_lshl_add_u32 v16, v7, 10, v22
	v_ashrrev_i32_e32 v17, 31, v16
	v_lshl_add_u64 v[24:25], v[16:17], 2, s[12:13]
	ds_read_b128 v[12:15], v6 offset:4352
	v_lshl_add_u64 v[16:17], v[16:17], 1, s[16:17]
	s_waitcnt vmcnt(15) lgkmcnt(0)
	v_mov_b32_e32 v8, v160
	v_mov_b32_e32 v9, v161
	v_mov_b32_e32 v10, v162
	v_mov_b32_e32 v11, v163
	v_pk_add_f32 v[8:9], v[12:13], v[8:9]
	v_pk_add_f32 v[10:11], v[14:15], v[10:11]
	global_store_dwordx4 v[24:25], v[8:11], off
	v_cvt_pk_bf16_f32 v12, v8, v9
	v_cvt_pk_bf16_f32 v13, v10, v11
	v_pk_mul_f32 v[8:9], v[8:9], v[8:9]
	v_pk_mul_f32 v[10:11], v[10:11], v[10:11]
	v_add_f32_e32 v8, v8, v9
	v_add_f32_e32 v8, v10, v8
	v_add_f32_e32 v8, v11, v8
	v_mov_b32_e32 v9, 0
	global_store_dwordx2 v[16:17], v[12:13], off
	v_add_f32_dpp v8, v8, v8 quad_perm:[1,0,3,2] row_mask:0xf bank_mask:0xf bound_ctrl:1
	s_nop 1
	v_add_f32_dpp v8, v8, v8 quad_perm:[2,3,0,1] row_mask:0xf bank_mask:0xf bound_ctrl:1
	s_nop 1
	v_add_f32_dpp v8, v8, v8 row_half_mirror row_mask:0xf bank_mask:0xf bound_ctrl:1
	s_nop 1
	v_mov_b32_dpp v9, v8 row_mirror row_mask:0xf bank_mask:0xf
	s_and_saveexec_b64 s[2:3], s[8:9]
	s_cbranch_execz .LBB0_3127
	v_add_f32_e32 v8, v8, v9
	v_lshlrev_b32_e32 v7, 2, v7
	global_atomic_add_f32 v7, v8, s[18:19]
.LBB0_3127:
	s_or_b64 exec, exec, s[2:3]
	v_or3_b32 v7, v0, s25, 20
	v_lshl_add_u32 v16, v7, 10, v22
	v_ashrrev_i32_e32 v17, 31, v16
	v_lshl_add_u64 v[24:25], v[16:17], 2, s[12:13]
	ds_read_b128 v[12:15], v6 offset:5440
	v_lshl_add_u64 v[16:17], v[16:17], 1, s[16:17]
	s_waitcnt vmcnt(17) lgkmcnt(0)
	v_mov_b32_e32 v8, v164
	v_mov_b32_e32 v9, v165
	v_mov_b32_e32 v10, v166
	v_mov_b32_e32 v11, v167
	v_pk_add_f32 v[8:9], v[12:13], v[8:9]
	v_pk_add_f32 v[10:11], v[14:15], v[10:11]
	global_store_dwordx4 v[24:25], v[8:11], off
	v_cvt_pk_bf16_f32 v12, v8, v9
	v_cvt_pk_bf16_f32 v13, v10, v11
	v_pk_mul_f32 v[8:9], v[8:9], v[8:9]
	v_pk_mul_f32 v[10:11], v[10:11], v[10:11]
	v_add_f32_e32 v8, v8, v9
	v_add_f32_e32 v8, v10, v8
	v_add_f32_e32 v8, v11, v8
	v_mov_b32_e32 v9, 0
	global_store_dwordx2 v[16:17], v[12:13], off
	v_add_f32_dpp v8, v8, v8 quad_perm:[1,0,3,2] row_mask:0xf bank_mask:0xf bound_ctrl:1
	s_nop 1
	v_add_f32_dpp v8, v8, v8 quad_perm:[2,3,0,1] row_mask:0xf bank_mask:0xf bound_ctrl:1
	s_nop 1
	v_add_f32_dpp v8, v8, v8 row_half_mirror row_mask:0xf bank_mask:0xf bound_ctrl:1
	s_nop 1
	v_mov_b32_dpp v9, v8 row_mirror row_mask:0xf bank_mask:0xf
	s_and_saveexec_b64 s[2:3], s[8:9]
	s_cbranch_execz .LBB0_3129
	v_add_f32_e32 v8, v8, v9
	v_lshlrev_b32_e32 v7, 2, v7
	global_atomic_add_f32 v7, v8, s[18:19]
.LBB0_3129:
	s_or_b64 exec, exec, s[2:3]
	v_or3_b32 v7, v0, s25, 24
	v_lshl_add_u32 v16, v7, 10, v22
	v_ashrrev_i32_e32 v17, 31, v16
	v_lshl_add_u64 v[24:25], v[16:17], 2, s[12:13]
	ds_read_b128 v[12:15], v6 offset:6528
	v_lshl_add_u64 v[16:17], v[16:17], 1, s[16:17]
	s_waitcnt vmcnt(19) lgkmcnt(0)
	v_mov_b32_e32 v8, v168
	v_mov_b32_e32 v9, v169
	v_mov_b32_e32 v10, v170
	v_mov_b32_e32 v11, v171
	v_pk_add_f32 v[8:9], v[12:13], v[8:9]
	v_pk_add_f32 v[10:11], v[14:15], v[10:11]
	global_store_dwordx4 v[24:25], v[8:11], off
	v_cvt_pk_bf16_f32 v12, v8, v9
	v_cvt_pk_bf16_f32 v13, v10, v11
	v_pk_mul_f32 v[8:9], v[8:9], v[8:9]
	v_pk_mul_f32 v[10:11], v[10:11], v[10:11]
	v_add_f32_e32 v8, v8, v9
	v_add_f32_e32 v8, v10, v8
	v_add_f32_e32 v8, v11, v8
	v_mov_b32_e32 v9, 0
	global_store_dwordx2 v[16:17], v[12:13], off
	v_add_f32_dpp v8, v8, v8 quad_perm:[1,0,3,2] row_mask:0xf bank_mask:0xf bound_ctrl:1
	s_nop 1
	v_add_f32_dpp v8, v8, v8 quad_perm:[2,3,0,1] row_mask:0xf bank_mask:0xf bound_ctrl:1
	s_nop 1
	v_add_f32_dpp v8, v8, v8 row_half_mirror row_mask:0xf bank_mask:0xf bound_ctrl:1
	s_nop 1
	v_mov_b32_dpp v9, v8 row_mirror row_mask:0xf bank_mask:0xf
	s_and_saveexec_b64 s[2:3], s[8:9]
	s_cbranch_execz .LBB0_3131
	v_add_f32_e32 v8, v8, v9
	v_lshlrev_b32_e32 v7, 2, v7
	global_atomic_add_f32 v7, v8, s[18:19]
.LBB0_3131:
	s_or_b64 exec, exec, s[2:3]
	v_or3_b32 v0, v0, s25, 28
	v_lshl_add_u32 v16, v0, 10, v22
	v_ashrrev_i32_e32 v17, 31, v16
	v_lshl_add_u64 v[22:23], v[16:17], 2, s[12:13]
	ds_read_b128 v[12:15], v6 offset:7616
	v_lshl_add_u64 v[16:17], v[16:17], 1, s[16:17]
	s_waitcnt vmcnt(21) lgkmcnt(0)
	v_mov_b32_e32 v8, v172
	v_mov_b32_e32 v9, v173
	v_mov_b32_e32 v10, v174
	v_mov_b32_e32 v11, v175
	v_pk_add_f32 v[6:7], v[12:13], v[8:9]
	v_pk_add_f32 v[8:9], v[14:15], v[10:11]
	global_store_dwordx4 v[22:23], v[6:9], off
	v_cvt_pk_bf16_f32 v10, v6, v7
	v_cvt_pk_bf16_f32 v11, v8, v9
	v_pk_mul_f32 v[6:7], v[6:7], v[6:7]
	v_pk_mul_f32 v[8:9], v[8:9], v[8:9]
	v_add_f32_e32 v6, v6, v7
	v_add_f32_e32 v6, v8, v6
	v_add_f32_e32 v6, v9, v6
	v_mov_b32_e32 v7, 0
	global_store_dwordx2 v[16:17], v[10:11], off
	v_add_f32_dpp v6, v6, v6 quad_perm:[1,0,3,2] row_mask:0xf bank_mask:0xf bound_ctrl:1
	s_nop 1
	v_add_f32_dpp v6, v6, v6 quad_perm:[2,3,0,1] row_mask:0xf bank_mask:0xf bound_ctrl:1
	s_nop 1
	v_add_f32_dpp v6, v6, v6 row_half_mirror row_mask:0xf bank_mask:0xf bound_ctrl:1
	s_nop 1
	v_mov_b32_dpp v7, v6 row_mirror row_mask:0xf bank_mask:0xf
	s_and_b64 exec, exec, s[8:9]
	s_cbranch_execz .LBB0_3114
	v_add_f32_e32 v6, v6, v7
	v_lshlrev_b32_e32 v0, 2, v0
	global_atomic_add_f32 v0, v6, s[18:19]
	s_branch .LBB0_3114

; template <class Epi>
; __device__ __forceinline__ void small_gemm(const u16* __restrict__ A, const u16* __restrict__ Bt, int K, int N, const Epi& epi) {
;     ...
;     for (int kk = k0; kk < k0 + kper; kk += 32) {
;       bf16x8 a[2], b[4];
; #pragma unroll
;       for (int m = 0; m < 2; ++m) a[m] = *(const bf16x8*)(A + (size_t)(row0 + m * 16 + fr) * K + kk + fq * 8);
; #pragma unroll
;       for (int n = 0; n < 4; ++n) b[n] = *(const bf16x8*)(Bt + (size_t)(col0 + n * 16 + fr) * K + kk + fq * 8);
; #pragma unroll
;       for (int m = 0; m < 2; ++m)
; #pragma unroll
;         for (int n = 0; n < 4; ++n) acc[m][n] = __builtin_amdgcn_mfma_f32_16x16x32_bf16(a[m], b[n], acc[m][n], 0, 0, 0);
;     }
;     __syncthreads();
; #pragma unroll
;     for (int m = 0; m < 2; ++m)
; #pragma unroll
;       for (int n = 0; n < 4; ++n) red[(wid * 8 + m * 4 + n) * 64 + lane] = acc[m][n];
;     __syncthreads();
;     if (wid == 0) {
; #pragma unroll
;       for (int m = 0; m < 2; ++m)
; #pragma unroll
;         for (int n = 0; n < 4; ++n) {
;           f32x4 s = red[(m * 4 + n) * 64 + lane];
; #pragma unroll
;           for (int w = 1; w < 8; ++w) s += red[(w * 8 + m * 4 + n) * 64 + lane];
;           acc[m][n] = s;
;         }
.LBB0_3235:
	v_lshl_add_u64 v[58:59], v[46:47], 0, v[36:37]
	v_add_co_u32_e64 v82, s[6:7], s16, v58
	v_lshl_add_u64 v[74:75], v[46:47], 0, v[38:39]
	s_nop 0
	v_addc_co_u32_e64 v83, s[6:7], 0, v59, s[6:7]
	v_lshl_add_u64 v[76:77], v[46:47], 0, v[40:41]
	v_lshl_add_u64 v[78:79], v[46:47], 0, v[42:43]
	v_lshl_add_u64 v[80:81], v[46:47], 0, v[44:45]
	v_add_co_u32_e64 v84, s[6:7], s17, v58
	v_add_u32_e32 v56, 32, v56
	s_nop 0
	v_addc_co_u32_e64 v85, s[6:7], 0, v59, s[6:7]
	global_load_dwordx4 v[58:61], v[74:75], off
	global_load_dwordx4 v[62:65], v[76:77], off
	global_load_dwordx4 v[66:69], v[82:83], off
	global_load_dwordx4 v[70:73], v[84:85], off
	v_cmp_ge_i32_e64 s[6:7], v56, v50
	global_load_dwordx4 v[74:77], v[78:79], off
	s_or_b64 s[0:1], s[6:7], s[0:1]
	global_load_dwordx4 v[78:81], v[80:81], off
	v_lshl_add_u64 v[46:47], v[46:47], 0, 64
	s_waitcnt vmcnt(3)
	v_mfma_f32_16x16x32_bf16 v[28:31], v[66:69], v[58:61], v[28:31]
	v_mfma_f32_16x16x32_bf16 v[24:27], v[66:69], v[62:65], v[24:27]
	s_waitcnt vmcnt(1)
	v_mfma_f32_16x16x32_bf16 v[20:23], v[66:69], v[74:77], v[20:23]
	s_waitcnt vmcnt(0)
	v_mfma_f32_16x16x32_bf16 v[16:19], v[66:69], v[78:81], v[16:19]
	v_mfma_f32_16x16x32_bf16 v[12:15], v[70:73], v[58:61], v[12:15]
	v_mfma_f32_16x16x32_bf16 v[8:11], v[70:73], v[62:65], v[8:11]
	v_mfma_f32_16x16x32_bf16 v[4:7], v[70:73], v[74:77], v[4:7]
	v_mfma_f32_16x16x32_bf16 v[0:3], v[70:73], v[78:81], v[0:3]
	s_andn2_b64 exec, exec, s[0:1]
	s_cbranch_execnz .LBB0_3235
	s_or_b64 exec, exec, s[0:1]
	s_barrier
	ds_write_b128 v55, v[28:31]
	ds_write_b128 v55, v[24:27] offset:1024
	ds_write_b128 v55, v[20:23] offset:2048
	ds_write_b128 v55, v[16:19] offset:3072
	ds_write_b128 v55, v[12:15] offset:4096
	ds_write_b128 v55, v[8:11] offset:5120
	ds_write_b128 v55, v[4:7] offset:6144
	ds_write_b128 v55, v[0:3] offset:7168
	s_waitcnt lgkmcnt(0)
	s_barrier
	s_and_saveexec_b64 s[0:1], vcc
	s_cbranch_execz .LBB0_3233
	ds_read_b128 v[0:3], v49
	ds_read_b128 v[4:7], v49 offset:8192
	ds_read_b128 v[8:11], v49 offset:16384
	ds_read_b128 v[12:15], v49 offset:1024
	ds_read_b128 v[16:19], v49 offset:9216
	s_andn2_b32 s2, s2, 63
	s_waitcnt lgkmcnt(3)
	v_pk_add_f32 v[20:21], v[2:3], v[6:7]
	v_pk_add_f32 v[22:23], v[0:1], v[4:5]
	ds_read_b128 v[0:3], v49 offset:24576
	ds_read_b128 v[4:7], v49 offset:17408
	s_waitcnt lgkmcnt(4)
	v_pk_add_f32 v[24:25], v[20:21], v[10:11]
	v_pk_add_f32 v[26:27], v[22:23], v[8:9]
	ds_read_b128 v[8:11], v49 offset:32768
	ds_read_b128 v[20:23], v49 offset:25600
	s_waitcnt lgkmcnt(3)
	v_pk_add_f32 v[28:29], v[24:25], v[2:3]
	v_pk_add_f32 v[30:31], v[26:27], v[0:1]
	ds_read_b128 v[0:3], v49 offset:40960
	ds_read_b128 v[24:27], v49 offset:33792
	s_waitcnt lgkmcnt(3)
	v_pk_add_f32 v[38:39], v[28:29], v[10:11]
	v_pk_add_f32 v[40:41], v[30:31], v[8:9]
	ds_read_b128 v[8:11], v49 offset:49152
	ds_read_b128 v[28:31], v49 offset:41984
	s_waitcnt lgkmcnt(3)
	v_pk_add_f32 v[2:3], v[38:39], v[2:3]
	v_pk_add_f32 v[0:1], v[40:41], v[0:1]
	ds_read_b128 v[38:41], v49 offset:57344
	ds_read_b128 v[42:45], v49 offset:50176
	v_pk_add_f32 v[14:15], v[14:15], v[18:19]
	s_waitcnt lgkmcnt(3)
	v_pk_add_f32 v[2:3], v[2:3], v[10:11]
	v_pk_add_f32 v[46:47], v[0:1], v[8:9]
	ds_read_b128 v[8:11], v49 offset:58368
	v_pk_add_f32 v[12:13], v[12:13], v[16:17]
	v_pk_add_f32 v[6:7], v[14:15], v[6:7]
	v_pk_add_f32 v[4:5], v[12:13], v[4:5]
	v_pk_add_f32 v[6:7], v[6:7], v[22:23]
	v_pk_add_f32 v[4:5], v[4:5], v[20:21]
	v_pk_add_f32 v[6:7], v[6:7], v[26:27]
	v_pk_add_f32 v[4:5], v[4:5], v[24:25]
	s_waitcnt lgkmcnt(3)
	v_pk_add_f32 v[6:7], v[6:7], v[30:31]
	v_pk_add_f32 v[4:5], v[4:5], v[28:29]
	s_waitcnt lgkmcnt(1)
	v_pk_add_f32 v[6:7], v[6:7], v[44:45]
	v_pk_add_f32 v[18:19], v[4:5], v[42:43]
	s_waitcnt lgkmcnt(0)
	v_pk_add_f32 v[4:5], v[6:7], v[10:11]
	ds_read_b128 v[10:13], v49 offset:2048
	ds_read_b128 v[14:17], v49 offset:10240
	v_pk_add_f32 v[6:7], v[18:19], v[8:9]
	ds_read_b128 v[18:21], v49 offset:18432
	ds_read_b128 v[22:25], v49 offset:3072
	ds_read_b128 v[26:29], v49 offset:11264
	v_pk_add_f32 v[0:1], v[2:3], v[40:41]
	v_pk_add_f32 v[2:3], v[46:47], v[38:39]
	s_waitcnt lgkmcnt(3)
	v_pk_add_f32 v[16:17], v[12:13], v[16:17]
	v_pk_add_f32 v[30:31], v[10:11], v[14:15]
	ds_read_b128 v[8:11], v49 offset:26624
	ds_read_b128 v[12:15], v49 offset:19456
	s_waitcnt lgkmcnt(4)
	v_pk_add_f32 v[20:21], v[16:17], v[20:21]
	v_pk_add_f32 v[30:31], v[30:31], v[18:19]
	ds_read_b128 v[16:19], v49 offset:34816
	ds_read_b128 v[38:41], v49 offset:27648
	s_waitcnt lgkmcnt(3)
	v_pk_add_f32 v[20:21], v[20:21], v[10:11]
	v_pk_add_f32 v[30:31], v[30:31], v[8:9]
	ds_read_b128 v[8:11], v49 offset:43008
	ds_read_b128 v[42:45], v49 offset:35840
	s_waitcnt lgkmcnt(3)
	v_pk_add_f32 v[20:21], v[20:21], v[18:19]
	v_pk_add_f32 v[30:31], v[30:31], v[16:17]
	ds_read_b128 v[16:19], v49 offset:51200
	ds_read_b128 v[56:59], v49 offset:44032
	ds_read_b128 v[60:63], v49 offset:59392
	ds_read_b128 v[64:67], v49 offset:52224
	s_waitcnt lgkmcnt(5)
	v_pk_add_f32 v[10:11], v[20:21], v[10:11]
	v_pk_add_f32 v[8:9], v[30:31], v[8:9]
	s_waitcnt lgkmcnt(3)
	v_pk_add_f32 v[10:11], v[10:11], v[18:19]
	v_pk_add_f32 v[20:21], v[8:9], v[16:17]
	s_waitcnt lgkmcnt(1)
	v_pk_add_f32 v[8:9], v[10:11], v[62:63]
	v_pk_add_f32 v[10:11], v[20:21], v[60:61]
	v_pk_add_f32 v[20:21], v[24:25], v[28:29]
	ds_read_b128 v[16:19], v49 offset:60416
	v_pk_add_f32 v[22:23], v[22:23], v[26:27]
	v_pk_add_f32 v[14:15], v[20:21], v[14:15]
	v_pk_add_f32 v[12:13], v[22:23], v[12:13]
	v_pk_add_f32 v[14:15], v[14:15], v[40:41]
	v_pk_add_f32 v[12:13], v[12:13], v[38:39]
	v_pk_add_f32 v[14:15], v[14:15], v[44:45]
	v_pk_add_f32 v[12:13], v[12:13], v[42:43]
	v_pk_add_f32 v[14:15], v[14:15], v[58:59]
	v_pk_add_f32 v[12:13], v[12:13], v[56:57]
	s_waitcnt lgkmcnt(1)
; template <int MF, class Epi>
; __device__ __forceinline__ void staged_epilogue(f32x4 (&acc)[MF][4], int row0, int col0, const Epi& epi) {
;     ...
;         for (int j = 0; j < 4; ++j) reg[(mm * 16 + fq * 4 + j) * 68 + n * 16 + fr] = acc[mp * 2 + mm][n][j];
; template <class Epi>
; __device__ __forceinline__ void small_gemm(const u16* __restrict__ A, const u16* __restrict__ Bt, int K, int N, const Epi& epi) {
;     ...
;         for (int n = 0; n < 4; ++n) {
;           f32x4 s = red[(m * 4 + n) * 64 + lane];
; #pragma unroll
;           for (int w = 1; w < 8; ++w) s += red[(w * 8 + m * 4 + n) * 64 + lane];
;           acc[m][n] = s;
;         }
	v_pk_add_f32 v[14:15], v[14:15], v[66:67]
	v_pk_add_f32 v[22:23], v[12:13], v[64:65]
	s_waitcnt lgkmcnt(0)
	v_pk_add_f32 v[46:47], v[14:15], v[18:19]
	ds_read_b128 v[12:15], v49 offset:4096
	ds_read_b128 v[18:21], v49 offset:12288
	v_pk_add_f32 v[68:69], v[22:23], v[16:17]
	ds_read_b128 v[22:25], v49 offset:20480
	ds_read_b128 v[26:29], v49 offset:5120
	ds_read_b128 v[38:41], v49 offset:13312
	s_waitcnt lgkmcnt(3)
	v_pk_add_f32 v[20:21], v[14:15], v[20:21]
	v_pk_add_f32 v[30:31], v[12:13], v[18:19]
	ds_read_b128 v[12:15], v49 offset:28672
	ds_read_b128 v[16:19], v49 offset:21504
	s_waitcnt lgkmcnt(4)
	v_pk_add_f32 v[24:25], v[20:21], v[24:25]
	v_pk_add_f32 v[30:31], v[30:31], v[22:23]
	ds_read_b128 v[20:23], v49 offset:36864
	ds_read_b128 v[42:45], v49 offset:29696
	s_waitcnt lgkmcnt(3)
	v_pk_add_f32 v[24:25], v[24:25], v[14:15]
	v_pk_add_f32 v[30:31], v[30:31], v[12:13]
	ds_read_b128 v[12:15], v49 offset:45056
	ds_read_b128 v[56:59], v49 offset:37888
	s_waitcnt lgkmcnt(3)
	v_pk_add_f32 v[24:25], v[24:25], v[22:23]
	v_pk_add_f32 v[30:31], v[30:31], v[20:21]
	ds_read_b128 v[20:23], v49 offset:53248
	ds_read_b128 v[60:63], v49 offset:46080
	s_waitcnt lgkmcnt(3)
	v_pk_add_f32 v[24:25], v[24:25], v[14:15]
	v_pk_add_f32 v[30:31], v[30:31], v[12:13]
	ds_read_b128 v[12:15], v49 offset:61440
	ds_read_b128 v[64:67], v49 offset:54272
	s_waitcnt lgkmcnt(3)
	v_pk_add_f32 v[30:31], v[30:31], v[20:21]
	v_pk_add_f32 v[24:25], v[24:25], v[22:23]
	ds_read_b128 v[20:23], v49 offset:62464
	s_waitcnt lgkmcnt(2)
	v_pk_add_f32 v[72:73], v[30:31], v[12:13]
	v_pk_add_f32 v[12:13], v[28:29], v[40:41]
	v_pk_add_f32 v[70:71], v[24:25], v[14:15]
	v_pk_add_f32 v[14:15], v[26:27], v[38:39]
	v_pk_add_f32 v[12:13], v[12:13], v[18:19]
	v_pk_add_f32 v[14:15], v[14:15], v[16:17]
	v_pk_add_f32 v[12:13], v[12:13], v[44:45]
	v_pk_add_f32 v[14:15], v[14:15], v[42:43]
	v_pk_add_f32 v[12:13], v[12:13], v[58:59]
	v_pk_add_f32 v[14:15], v[14:15], v[56:57]
	v_pk_add_f32 v[12:13], v[12:13], v[62:63]
	v_pk_add_f32 v[14:15], v[14:15], v[60:61]
	s_waitcnt lgkmcnt(1)
	v_pk_add_f32 v[12:13], v[12:13], v[66:67]
	v_pk_add_f32 v[24:25], v[14:15], v[64:65]
	s_waitcnt lgkmcnt(0)
	v_pk_add_f32 v[64:65], v[12:13], v[22:23]
	ds_read_b128 v[12:15], v49 offset:6144
	ds_read_b128 v[16:19], v49 offset:14336
	v_pk_add_f32 v[66:67], v[24:25], v[20:21]
	ds_read_b128 v[20:23], v49 offset:22528
	ds_read_b128 v[24:27], v49 offset:7168
	ds_read_b128 v[28:31], v49 offset:15360
	s_waitcnt lgkmcnt(3)
	v_pk_add_f32 v[38:39], v[14:15], v[18:19]
	v_pk_add_f32 v[40:41], v[12:13], v[16:17]
	ds_read_b128 v[12:15], v49 offset:30720
	ds_read_b128 v[16:19], v49 offset:23552
	s_waitcnt lgkmcnt(4)
	v_pk_add_f32 v[42:43], v[38:39], v[22:23]
	v_pk_add_f32 v[44:45], v[40:41], v[20:21]
	ds_read_b128 v[20:23], v49 offset:38912
	ds_read_b128 v[38:41], v49 offset:31744
	s_waitcnt lgkmcnt(3)
	v_pk_add_f32 v[56:57], v[42:43], v[14:15]
	v_pk_add_f32 v[58:59], v[44:45], v[12:13]
	ds_read_b128 v[12:15], v49 offset:47104
	ds_read_b128 v[42:45], v49 offset:39936
	s_waitcnt lgkmcnt(3)
	v_pk_add_f32 v[60:61], v[56:57], v[22:23]
	v_pk_add_f32 v[62:63], v[58:59], v[20:21]
	ds_read_b128 v[20:23], v49 offset:55296
	ds_read_b128 v[56:59], v49 offset:48128
	s_waitcnt lgkmcnt(3)
	v_pk_add_f32 v[74:75], v[60:61], v[14:15]
	v_pk_add_f32 v[76:77], v[62:63], v[12:13]
	ds_read_b128 v[12:15], v49 offset:63488
	ds_read_b128 v[60:63], v49 offset:56320
	s_waitcnt lgkmcnt(3)
	v_pk_add_f32 v[76:77], v[76:77], v[20:21]
	v_pk_add_f32 v[74:75], v[74:75], v[22:23]
	ds_read_b128 v[20:23], v49 offset:64512
	s_waitcnt lgkmcnt(2)
	v_pk_add_f32 v[76:77], v[76:77], v[12:13]
	v_pk_add_f32 v[12:13], v[26:27], v[30:31]
	v_pk_add_f32 v[74:75], v[74:75], v[14:15]
	v_pk_add_f32 v[12:13], v[12:13], v[18:19]
	v_pk_add_f32 v[14:15], v[24:25], v[28:29]
	v_pk_add_f32 v[12:13], v[12:13], v[40:41]
	v_pk_add_f32 v[14:15], v[14:15], v[16:17]
	v_pk_add_f32 v[12:13], v[12:13], v[44:45]
	v_pk_add_f32 v[14:15], v[14:15], v[38:39]
	v_pk_add_f32 v[12:13], v[12:13], v[58:59]
	v_pk_add_f32 v[14:15], v[14:15], v[42:43]
	s_waitcnt lgkmcnt(1)
	v_pk_add_f32 v[12:13], v[12:13], v[62:63]
	v_pk_add_f32 v[14:15], v[14:15], v[56:57]
	s_waitcnt lgkmcnt(0)
	v_pk_add_f32 v[16:17], v[12:13], v[22:23]
	v_mov_b32_e32 v13, v204
	v_mov_b32_e32 v12, v204
	v_pk_add_f32 v[14:15], v[14:15], v[60:61]
	v_lshrrev_b32_e32 v12, 6, v12
	v_mul_lo_u32 v12, v12, s18
	v_pk_add_f32 v[18:19], v[14:15], v[20:21]
	v_add_u32_e32 v14, 0x10000, v12
	v_lshrrev_b32_e32 v12, 2, v13
	v_and_b32_e32 v21, 15, v13
	v_and_b32_e32 v22, 12, v12
	v_bfe_u32 v12, v13, 4, 2
	v_lshlrev_b32_e32 v13, 2, v13
	v_and_b32_e32 v13, 60, v13
	v_lshl_or_b32 v23, v21, 2, v14
	v_lshl_or_b32 v14, v13, 2, v14
	v_or_b32_e32 v15, s21, v12
	v_or_b32_e32 v13, s2, v13
	v_cmp_eq_u32_e64 s[6:7], 0, v21
	v_mad_u32_u24 v24, v12, s19, v14
	v_lshl_add_u32 v20, v15, 10, v13
	v_mad_u32_u24 v21, v22, s19, v23
	ds_write2_b32 v21, v2, v6 offset1:16
	ds_write2_b32 v21, v3, v7 offset0:68 offset1:84
	ds_write2_b32 v21, v0, v4 offset0:136 offset1:152
	ds_write2_b32 v21, v1, v5 offset0:204 offset1:220
	ds_write2_b32 v21, v10, v68 offset0:32 offset1:48
	ds_write2_b32 v21, v11, v69 offset0:100 offset1:116
	ds_write2_b32 v21, v8, v46 offset0:168 offset1:184
	ds_write2_b32 v21, v9, v47 offset0:236 offset1:252
	v_add_u32_e32 v0, 0x1000, v21
	v_add_u32_e32 v1, 0x1400, v21
	ds_write2_b32 v0, v72, v66 offset0:64 offset1:80
	ds_write2_b32 v0, v73, v67 offset0:132 offset1:148
	ds_write2_b32 v0, v70, v64 offset0:200 offset1:216
	ds_write2_b32 v1, v71, v65 offset0:12 offset1:28
	ds_write2_b32 v0, v76, v18 offset0:96 offset1:112
	ds_write2_b32 v0, v77, v19 offset0:164 offset1:180
;   __device__ __forceinline__ void tile(const float* reg, int row0, int col0, int lane) const {
;     rows4(reg, lane, [&](int it, int rr, int c4, float4 v) {
;       int row = row0 + rr, idx = row * 1024 + col0 + c4;
;       float4 xo = *(const float4*)(xold + idx);
;       v.x = fmaf(coef, v.x, xo.x); v.y = fmaf(coef, v.y, xo.y); v.z = fmaf(coef, v.z, xo.z); v.w = fmaf(coef, v.w, xo.w);
;       *(float4*)(xnew + idx) = v;
;       *(bf16x4*)(xb + idx) = pack4(v.x, v.y, v.z, v.w);
;       float s = row16_sum(v.x * v.x + v.y * v.y + v.z * v.z + v.w * v.w);
;       if ((lane & 15) == 0) atomicAdd(ssqn + row, s);
;     });
	ds_write2_b32 v0, v74, v16 offset0:232 offset1:248
	ds_write2_b32 v1, v75, v17 offset0:44 offset1:60
	v_mov_b32_e32 v178, v20
	v_ashrrev_i32_e32 v179, 31, v178
	v_lshl_add_u64 v[176:177], v[178:179], 2, s[8:9]
	global_load_dwordx4 v[144:147], v[176:177], off
	v_or3_b32 v184, v12, s21, 4
	v_lshl_add_u32 v176, v184, 10, v13
	v_ashrrev_i32_e32 v177, 31, v176
	v_lshl_add_u64 v[178:179], v[176:177], 2, s[8:9]
	global_load_dwordx4 v[148:151], v[178:179], off
	v_or3_b32 v184, v12, s21, 8
	v_lshl_add_u32 v176, v184, 10, v13
	v_ashrrev_i32_e32 v177, 31, v176
	v_lshl_add_u64 v[178:179], v[176:177], 2, s[8:9]
	global_load_dwordx4 v[152:155], v[178:179], off
	v_or3_b32 v184, v12, s21, 12
	v_lshl_add_u32 v176, v184, 10, v13
	v_ashrrev_i32_e32 v177, 31, v176
	v_lshl_add_u64 v[178:179], v[176:177], 2, s[8:9]
	global_load_dwordx4 v[156:159], v[178:179], off
	v_or3_b32 v184, v12, s21, 16
	v_lshl_add_u32 v176, v184, 10, v13
	v_ashrrev_i32_e32 v177, 31, v176
	v_lshl_add_u64 v[178:179], v[176:177], 2, s[8:9]
	global_load_dwordx4 v[160:163], v[178:179], off
	v_or3_b32 v184, v12, s21, 20
	v_lshl_add_u32 v176, v184, 10, v13
	v_ashrrev_i32_e32 v177, 31, v176
	v_lshl_add_u64 v[178:179], v[176:177], 2, s[8:9]
	global_load_dwordx4 v[164:167], v[178:179], off
	v_or3_b32 v184, v12, s21, 24
	v_lshl_add_u32 v176, v184, 10, v13
	v_ashrrev_i32_e32 v177, 31, v176
	v_lshl_add_u64 v[178:179], v[176:177], 2, s[8:9]
	global_load_dwordx4 v[168:171], v[178:179], off
	v_or3_b32 v184, v12, s21, 28
	v_lshl_add_u32 v176, v184, 10, v13
	v_ashrrev_i32_e32 v177, 31, v176
	v_lshl_add_u64 v[178:179], v[176:177], 2, s[8:9]
	global_load_dwordx4 v[172:175], v[178:179], off
	v_ashrrev_i32_e32 v21, 31, v20
	v_lshl_add_u64 v[8:9], v[20:21], 2, s[8:9]
	ds_read_b128 v[4:7], v24
	v_lshl_add_u64 v[10:11], v[20:21], 1, s[12:13]
	s_waitcnt vmcnt(7) lgkmcnt(0)
	v_mov_b32_e32 v0, v144
	v_mov_b32_e32 v1, v145
	v_mov_b32_e32 v2, v146
	v_mov_b32_e32 v3, v147
	v_pk_fma_f32 v[0:1], v[4:5], 0.5, v[0:1] op_sel_hi:[1,0,1]
	v_pk_fma_f32 v[2:3], v[6:7], 0.5, v[2:3] op_sel_hi:[1,0,1]
	global_store_dwordx4 v[8:9], v[0:3], off
	v_cvt_pk_bf16_f32 v4, v0, v1
	v_cvt_pk_bf16_f32 v5, v2, v3
	v_pk_mul_f32 v[0:1], v[0:1], v[0:1]
	v_pk_mul_f32 v[2:3], v[2:3], v[2:3]
	v_add_f32_e32 v0, v0, v1
	v_add_f32_e32 v0, v2, v0
	v_add_f32_e32 v0, v3, v0
	v_mov_b32_e32 v1, v37
	global_store_dwordx2 v[10:11], v[4:5], off
	v_add_f32_dpp v0, v0, v0 quad_perm:[1,0,3,2] row_mask:0xf bank_mask:0xf bound_ctrl:1
	s_nop 1
	v_add_f32_dpp v0, v0, v0 quad_perm:[2,3,0,1] row_mask:0xf bank_mask:0xf bound_ctrl:1
	s_nop 1
	v_add_f32_dpp v0, v0, v0 row_half_mirror row_mask:0xf bank_mask:0xf bound_ctrl:1
	s_nop 1
	v_mov_b32_dpp v1, v0 row_mirror row_mask:0xf bank_mask:0xf
	s_and_saveexec_b64 s[2:3], s[6:7]
	s_cbranch_execz .LBB0_3239
	v_add_f32_e32 v0, v0, v1
	v_lshlrev_b32_e32 v1, 2, v15
	global_atomic_add_f32 v1, v0, s[14:15]
.LBB0_3239:
	s_or_b64 exec, exec, s[2:3]
	v_or3_b32 v1, v12, s21, 4
	v_lshl_add_u32 v10, v1, 10, v13
	v_ashrrev_i32_e32 v11, 31, v10
	v_lshl_add_u64 v[16:17], v[10:11], 2, s[8:9]
	v_mul_u32_u24_e32 v0, 0x110, v12
	v_add_u32_e32 v0, v14, v0
	ds_read_b128 v[6:9], v0 offset:1088
	v_lshl_add_u64 v[10:11], v[10:11], 1, s[12:13]
	s_waitcnt vmcnt(9) lgkmcnt(0)
	v_mov_b32_e32 v2, v148
	v_mov_b32_e32 v3, v149
	v_mov_b32_e32 v4, v150
	v_mov_b32_e32 v5, v151
	v_pk_fma_f32 v[2:3], v[6:7], 0.5, v[2:3] op_sel_hi:[1,0,1]
	v_pk_fma_f32 v[4:5], v[8:9], 0.5, v[4:5] op_sel_hi:[1,0,1]
	global_store_dwordx4 v[16:17], v[2:5], off
	v_cvt_pk_bf16_f32 v6, v2, v3
	v_cvt_pk_bf16_f32 v7, v4, v5
	v_pk_mul_f32 v[2:3], v[2:3], v[2:3]
	v_pk_mul_f32 v[4:5], v[4:5], v[4:5]
	v_add_f32_e32 v2, v2, v3
	v_add_f32_e32 v2, v4, v2
	v_add_f32_e32 v2, v5, v2
	v_mov_b32_e32 v3, 0
	global_store_dwordx2 v[10:11], v[6:7], off
	v_add_f32_dpp v2, v2, v2 quad_perm:[1,0,3,2] row_mask:0xf bank_mask:0xf bound_ctrl:1
	s_nop 1
	v_add_f32_dpp v2, v2, v2 quad_perm:[2,3,0,1] row_mask:0xf bank_mask:0xf bound_ctrl:1
	s_nop 1
	v_add_f32_dpp v2, v2, v2 row_half_mirror row_mask:0xf bank_mask:0xf bound_ctrl:1
	s_nop 1
	v_mov_b32_dpp v3, v2 row_mirror row_mask:0xf bank_mask:0xf
	s_and_saveexec_b64 s[2:3], s[6:7]
	s_cbranch_execz .LBB0_3241
	v_add_f32_e32 v2, v2, v3
	v_lshlrev_b32_e32 v1, 2, v1
	global_atomic_add_f32 v1, v2, s[14:15]
.LBB0_3241:
	s_or_b64 exec, exec, s[2:3]
	v_or3_b32 v1, v12, s21, 8
	v_lshl_add_u32 v10, v1, 10, v13
	v_ashrrev_i32_e32 v11, 31, v10
	v_lshl_add_u64 v[14:15], v[10:11], 2, s[8:9]
	ds_read_b128 v[6:9], v0 offset:2176
	v_lshl_add_u64 v[10:11], v[10:11], 1, s[12:13]
	s_waitcnt vmcnt(11) lgkmcnt(0)
	v_mov_b32_e32 v2, v152
	v_mov_b32_e32 v3, v153
	v_mov_b32_e32 v4, v154
	v_mov_b32_e32 v5, v155
	v_pk_fma_f32 v[2:3], v[6:7], 0.5, v[2:3] op_sel_hi:[1,0,1]
	v_pk_fma_f32 v[4:5], v[8:9], 0.5, v[4:5] op_sel_hi:[1,0,1]
	global_store_dwordx4 v[14:15], v[2:5], off
	v_cvt_pk_bf16_f32 v6, v2, v3
	v_cvt_pk_bf16_f32 v7, v4, v5
	v_pk_mul_f32 v[2:3], v[2:3], v[2:3]
	v_pk_mul_f32 v[4:5], v[4:5], v[4:5]
	v_add_f32_e32 v2, v2, v3
	v_add_f32_e32 v2, v4, v2
	v_add_f32_e32 v2, v5, v2
	v_mov_b32_e32 v3, 0
	global_store_dwordx2 v[10:11], v[6:7], off
	v_add_f32_dpp v2, v2, v2 quad_perm:[1,0,3,2] row_mask:0xf bank_mask:0xf bound_ctrl:1
	s_nop 1
	v_add_f32_dpp v2, v2, v2 quad_perm:[2,3,0,1] row_mask:0xf bank_mask:0xf bound_ctrl:1
	s_nop 1
	v_add_f32_dpp v2, v2, v2 row_half_mirror row_mask:0xf bank_mask:0xf bound_ctrl:1
	s_nop 1
	v_mov_b32_dpp v3, v2 row_mirror row_mask:0xf bank_mask:0xf
	s_and_saveexec_b64 s[2:3], s[6:7]
	s_cbranch_execz .LBB0_3243
	v_add_f32_e32 v2, v2, v3
	v_lshlrev_b32_e32 v1, 2, v1
	global_atomic_add_f32 v1, v2, s[14:15]
;   __device__ __forceinline__ void tile(const float* reg, int row0, int col0, int lane) const {
;     rows4(reg, lane, [&](int it, int rr, int c4, float4 v) {
;       int row = row0 + rr, idx = row * 1024 + col0 + c4;
;       float4 xo = *(const float4*)(xold + idx);
;       v.x = fmaf(coef, v.x, xo.x); v.y = fmaf(coef, v.y, xo.y); v.z = fmaf(coef, v.z, xo.z); v.w = fmaf(coef, v.w, xo.w);
;       *(float4*)(xnew + idx) = v;
;       *(bf16x4*)(xb + idx) = pack4(v.x, v.y, v.z, v.w);
;       float s = row16_sum(v.x * v.x + v.y * v.y + v.z * v.z + v.w * v.w);
;       if ((lane & 15) == 0) atomicAdd(ssqn + row, s);
;     });
.LBB0_3243:
	s_or_b64 exec, exec, s[2:3]
	v_or3_b32 v1, v12, s21, 12
	v_lshl_add_u32 v10, v1, 10, v13
	v_ashrrev_i32_e32 v11, 31, v10
	v_lshl_add_u64 v[14:15], v[10:11], 2, s[8:9]
	ds_read_b128 v[6:9], v0 offset:3264
	v_lshl_add_u64 v[10:11], v[10:11], 1, s[12:13]
	s_waitcnt vmcnt(13) lgkmcnt(0)
	v_mov_b32_e32 v2, v156
	v_mov_b32_e32 v3, v157
	v_mov_b32_e32 v4, v158
	v_mov_b32_e32 v5, v159
	v_pk_fma_f32 v[2:3], v[6:7], 0.5, v[2:3] op_sel_hi:[1,0,1]
	v_pk_fma_f32 v[4:5], v[8:9], 0.5, v[4:5] op_sel_hi:[1,0,1]
	global_store_dwordx4 v[14:15], v[2:5], off
	v_cvt_pk_bf16_f32 v6, v2, v3
	v_cvt_pk_bf16_f32 v7, v4, v5
	v_pk_mul_f32 v[2:3], v[2:3], v[2:3]
	v_pk_mul_f32 v[4:5], v[4:5], v[4:5]
	v_add_f32_e32 v2, v2, v3
	v_add_f32_e32 v2, v4, v2
	v_add_f32_e32 v2, v5, v2
	v_mov_b32_e32 v3, 0
	global_store_dwordx2 v[10:11], v[6:7], off
	v_add_f32_dpp v2, v2, v2 quad_perm:[1,0,3,2] row_mask:0xf bank_mask:0xf bound_ctrl:1
	s_nop 1
	v_add_f32_dpp v2, v2, v2 quad_perm:[2,3,0,1] row_mask:0xf bank_mask:0xf bound_ctrl:1
	s_nop 1
	v_add_f32_dpp v2, v2, v2 row_half_mirror row_mask:0xf bank_mask:0xf bound_ctrl:1
	s_nop 1
	v_mov_b32_dpp v3, v2 row_mirror row_mask:0xf bank_mask:0xf
	s_and_saveexec_b64 s[2:3], s[6:7]
	s_cbranch_execz .LBB0_3245
	v_add_f32_e32 v2, v2, v3
	v_lshlrev_b32_e32 v1, 2, v1
	global_atomic_add_f32 v1, v2, s[14:15]
.LBB0_3245:
	s_or_b64 exec, exec, s[2:3]
	v_or3_b32 v1, v12, s21, 16
	v_lshl_add_u32 v10, v1, 10, v13
	v_ashrrev_i32_e32 v11, 31, v10
	v_lshl_add_u64 v[14:15], v[10:11], 2, s[8:9]
	ds_read_b128 v[6:9], v0 offset:4352
	v_lshl_add_u64 v[10:11], v[10:11], 1, s[12:13]
	s_waitcnt vmcnt(15) lgkmcnt(0)
	v_mov_b32_e32 v2, v160
	v_mov_b32_e32 v3, v161
	v_mov_b32_e32 v4, v162
	v_mov_b32_e32 v5, v163
	v_pk_fma_f32 v[2:3], v[6:7], 0.5, v[2:3] op_sel_hi:[1,0,1]
	v_pk_fma_f32 v[4:5], v[8:9], 0.5, v[4:5] op_sel_hi:[1,0,1]
	global_store_dwordx4 v[14:15], v[2:5], off
	v_cvt_pk_bf16_f32 v6, v2, v3
	v_cvt_pk_bf16_f32 v7, v4, v5
	v_pk_mul_f32 v[2:3], v[2:3], v[2:3]
	v_pk_mul_f32 v[4:5], v[4:5], v[4:5]
	v_add_f32_e32 v2, v2, v3
	v_add_f32_e32 v2, v4, v2
	v_add_f32_e32 v2, v5, v2
	v_mov_b32_e32 v3, 0
	global_store_dwordx2 v[10:11], v[6:7], off
	v_add_f32_dpp v2, v2, v2 quad_perm:[1,0,3,2] row_mask:0xf bank_mask:0xf bound_ctrl:1
	s_nop 1
	v_add_f32_dpp v2, v2, v2 quad_perm:[2,3,0,1] row_mask:0xf bank_mask:0xf bound_ctrl:1
	s_nop 1
	v_add_f32_dpp v2, v2, v2 row_half_mirror row_mask:0xf bank_mask:0xf bound_ctrl:1
	s_nop 1
	v_mov_b32_dpp v3, v2 row_mirror row_mask:0xf bank_mask:0xf
	s_and_saveexec_b64 s[2:3], s[6:7]
	s_cbranch_execz .LBB0_3247
	v_add_f32_e32 v2, v2, v3
	v_lshlrev_b32_e32 v1, 2, v1
	global_atomic_add_f32 v1, v2, s[14:15]
.LBB0_3247:
	s_or_b64 exec, exec, s[2:3]
	v_or3_b32 v1, v12, s21, 20
	v_lshl_add_u32 v10, v1, 10, v13
	v_ashrrev_i32_e32 v11, 31, v10
	v_lshl_add_u64 v[14:15], v[10:11], 2, s[8:9]
	ds_read_b128 v[6:9], v0 offset:5440
	v_lshl_add_u64 v[10:11], v[10:11], 1, s[12:13]
	s_waitcnt vmcnt(17) lgkmcnt(0)
	v_mov_b32_e32 v2, v164
	v_mov_b32_e32 v3, v165
	v_mov_b32_e32 v4, v166
	v_mov_b32_e32 v5, v167
	v_pk_fma_f32 v[2:3], v[6:7], 0.5, v[2:3] op_sel_hi:[1,0,1]
	v_pk_fma_f32 v[4:5], v[8:9], 0.5, v[4:5] op_sel_hi:[1,0,1]
	global_store_dwordx4 v[14:15], v[2:5], off
	v_cvt_pk_bf16_f32 v6, v2, v3
	v_cvt_pk_bf16_f32 v7, v4, v5
	v_pk_mul_f32 v[2:3], v[2:3], v[2:3]
	v_pk_mul_f32 v[4:5], v[4:5], v[4:5]
	v_add_f32_e32 v2, v2, v3
	v_add_f32_e32 v2, v4, v2
	v_add_f32_e32 v2, v5, v2
	v_mov_b32_e32 v3, 0
	global_store_dwordx2 v[10:11], v[6:7], off
	v_add_f32_dpp v2, v2, v2 quad_perm:[1,0,3,2] row_mask:0xf bank_mask:0xf bound_ctrl:1
	s_nop 1
	v_add_f32_dpp v2, v2, v2 quad_perm:[2,3,0,1] row_mask:0xf bank_mask:0xf bound_ctrl:1
	s_nop 1
	v_add_f32_dpp v2, v2, v2 row_half_mirror row_mask:0xf bank_mask:0xf bound_ctrl:1
	s_nop 1
	v_mov_b32_dpp v3, v2 row_mirror row_mask:0xf bank_mask:0xf
	s_and_saveexec_b64 s[2:3], s[6:7]
	s_cbranch_execz .LBB0_3249
	v_add_f32_e32 v2, v2, v3
	v_lshlrev_b32_e32 v1, 2, v1
	global_atomic_add_f32 v1, v2, s[14:15]
.LBB0_3249:
	s_or_b64 exec, exec, s[2:3]
	v_or3_b32 v1, v12, s21, 24
	v_lshl_add_u32 v10, v1, 10, v13
	v_ashrrev_i32_e32 v11, 31, v10
	v_lshl_add_u64 v[14:15], v[10:11], 2, s[8:9]
	ds_read_b128 v[6:9], v0 offset:6528
	v_lshl_add_u64 v[10:11], v[10:11], 1, s[12:13]
	s_waitcnt vmcnt(19) lgkmcnt(0)
	v_mov_b32_e32 v2, v168
	v_mov_b32_e32 v3, v169
	v_mov_b32_e32 v4, v170
	v_mov_b32_e32 v5, v171
	v_pk_fma_f32 v[2:3], v[6:7], 0.5, v[2:3] op_sel_hi:[1,0,1]
	v_pk_fma_f32 v[4:5], v[8:9], 0.5, v[4:5] op_sel_hi:[1,0,1]
	global_store_dwordx4 v[14:15], v[2:5], off
	v_cvt_pk_bf16_f32 v6, v2, v3
	v_cvt_pk_bf16_f32 v7, v4, v5
	v_pk_mul_f32 v[2:3], v[2:3], v[2:3]
	v_pk_mul_f32 v[4:5], v[4:5], v[4:5]
	v_add_f32_e32 v2, v2, v3
	v_add_f32_e32 v2, v4, v2
	v_add_f32_e32 v2, v5, v2
	v_mov_b32_e32 v3, 0
	global_store_dwordx2 v[10:11], v[6:7], off
	v_add_f32_dpp v2, v2, v2 quad_perm:[1,0,3,2] row_mask:0xf bank_mask:0xf bound_ctrl:1
	s_nop 1
	v_add_f32_dpp v2, v2, v2 quad_perm:[2,3,0,1] row_mask:0xf bank_mask:0xf bound_ctrl:1
	s_nop 1
	v_add_f32_dpp v2, v2, v2 row_half_mirror row_mask:0xf bank_mask:0xf bound_ctrl:1
	s_nop 1
	v_mov_b32_dpp v3, v2 row_mirror row_mask:0xf bank_mask:0xf
	s_and_saveexec_b64 s[2:3], s[6:7]
	s_cbranch_execz .LBB0_3251
	v_add_f32_e32 v2, v2, v3
	v_lshlrev_b32_e32 v1, 2, v1
	global_atomic_add_f32 v1, v2, s[14:15]
.LBB0_3251:
	s_or_b64 exec, exec, s[2:3]
	v_or3_b32 v1, v12, s21, 28
	v_lshl_add_u32 v10, v1, 10, v13
	v_ashrrev_i32_e32 v11, 31, v10
	v_lshl_add_u64 v[12:13], v[10:11], 2, s[8:9]
	ds_read_b128 v[6:9], v0 offset:7616
	v_lshl_add_u64 v[10:11], v[10:11], 1, s[12:13]
	s_waitcnt vmcnt(21) lgkmcnt(0)
	v_mov_b32_e32 v2, v172
	v_mov_b32_e32 v3, v173
	v_mov_b32_e32 v4, v174
	v_mov_b32_e32 v5, v175
	v_pk_fma_f32 v[2:3], v[6:7], 0.5, v[2:3] op_sel_hi:[1,0,1]
	v_pk_fma_f32 v[4:5], v[8:9], 0.5, v[4:5] op_sel_hi:[1,0,1]
	global_store_dwordx4 v[12:13], v[2:5], off
	v_cvt_pk_bf16_f32 v6, v2, v3
	v_cvt_pk_bf16_f32 v7, v4, v5
	v_pk_mul_f32 v[2:3], v[2:3], v[2:3]
	v_pk_mul_f32 v[4:5], v[4:5], v[4:5]
	v_add_f32_e32 v0, v2, v3
	v_add_f32_e32 v0, v4, v0
	v_add_f32_e32 v0, v5, v0
	v_mov_b32_e32 v2, 0
	global_store_dwordx2 v[10:11], v[6:7], off
	v_add_f32_dpp v0, v0, v0 quad_perm:[1,0,3,2] row_mask:0xf bank_mask:0xf bound_ctrl:1
	s_nop 1
	v_add_f32_dpp v0, v0, v0 quad_perm:[2,3,0,1] row_mask:0xf bank_mask:0xf bound_ctrl:1
	s_nop 1
	v_add_f32_dpp v0, v0, v0 row_half_mirror row_mask:0xf bank_mask:0xf bound_ctrl:1
	s_nop 1
	v_mov_b32_dpp v2, v0 row_mirror row_mask:0xf bank_mask:0xf
	s_and_b64 exec, exec, s[6:7]
	s_cbranch_execz .LBB0_3232
	v_add_f32_e32 v0, v0, v2
	v_lshlrev_b32_e32 v1, 2, v1
	global_atomic_add_f32 v1, v0, s[14:15]
	s_branch .LBB0_3232
